# GEMM K-loops: redundant s_waitcnt lgkmcnt(0) after the opening barrier of each MFMA block removed (one issue slot less before the first MFMA)
# speedup vs baseline: 1.0067x; 1.0067x over previous
; #define PG8_STAGE(bufoff, gbase, voff) do { if constexpr (!pg8_noload<Epi>::value) { _Pragma("unroll") for (int _i = 0; _i < 2; ++_i) \
;         __builtin_amdgcn_global_load_lds((const unsigned*)((const char*)(gbase) + (size_t)_i * pstep + (voff)[0]), (PG8_LAS unsigned*)(lds + (bufoff) + ldsw + _i * 8192), 16, 0, 0); } } while (0)
; #define PG8_LDA(dst, b, h) do { _Pragma("unroll") for (int m = 0; m < 4; ++m) _Pragma("unroll") for (int k = 0; k < 2; ++k) dst[m][k] = *(const PG8_LAS bf16x8*)(lds + PG8_SA(b, h) + aoff + m * 2048 + k * 1024); } while (0)
; #define PG8_LDB(dst, b, h) do { _Pragma("unroll") for (int n = 0; n < 2; ++n) _Pragma("unroll") for (int k = 0; k < 2; ++k) dst[n][k] = *(const PG8_LAS bf16x8*)(lds + PG8_SB(b, h) + boff + n * 2048 + k * 1024); } while (0)
; #define PG8_MMA(ai, bj, At, Bt) do { __builtin_amdgcn_s_setprio(1); _Pragma("unroll") for (int m = 0; m < 4; ++m) _Pragma("unroll") for (int n = 0; n < 2; ++n) _Pragma("unroll") for (int k = 0; k < 2; ++k) \
;         acc[ai][bj][m][n] = __builtin_amdgcn_mfma_f32_16x16x32_bf16(Bt[n][k], At[m][k], acc[ai][bj][m][n], 0, 0, 0); __builtin_amdgcn_s_setprio(0); } while (0)
; #define PG8_BAR __builtin_amdgcn_s_barrier()
; template <class Epi, class Sched, bool ALIGN_EPI = false, bool SP2 = false, bool ABLK = false>
; __device__ __forceinline__ void gemm_phase(PG8_LAS unsigned char* lds, const Gemm g, const Sched& S, const Epi& E) {
;     ...
;         for (int t = 0; t < nt; t += 2) {
;             const bool last = (t == nt - 2);
;             const char* a1 = cA + (size_t)(t + 1) * kstep;
;             const char* a2 = last ? nA : cA + (size_t)(t + 2) * kstep; const char* b2 = last ? nB : cB + (size_t)(t + 2) * kstepB;
;             const char* a3 = a2 + kstep; const char* b3 = b2 + kstepB;
;             if (last && has_next) S.a_ready(nxt);
;             if constexpr (SP2) {
;             PG8_LDB(B0, 0, 0); PG8_LDB(B1, 0, 1); PG8_SCHED; PG8_LDA(At, 0, 0); PG8_STAGE(PG8_SA(1, 1), a1 + hstep, voffA);
;             PG8_WAIT_V(8); PG8_WAIT_L(0); PG8_BAR; PG8_MMA(0, 0, At, B0); PG8_MMA(0, 1, At, B1); PG8_BAR; PG8_SCHED;
;             PG8_LDA(At, 0, 1); PG8_STAGE(PG8_SB(0, 0), b2, voffB); PG8_STAGE(PG8_SB(0, 1), b2 + hstep, voffB); PG8_STAGE(PG8_SA(0, 0), a2, voffA);
;             PG8_WAIT_V(8); PG8_WAIT_L(0); PG8_BAR; PG8_MMA(1, 0, At, B0); PG8_MMA(1, 1, At, B1); PG8_BAR; PG8_SCHED;
.LBB0_114:
	ds_read_b128 v[144:147], v168
	ds_read_b128 v[184:187], v168 offset:1024
	ds_read_b128 v[188:191], v168 offset:2048
	ds_read_b128 v[192:195], v168 offset:3072
	ds_read_b128 v[196:199], v169
	ds_read_b128 v[200:203], v169 offset:1024
	ds_read_b128 v[204:207], v169 offset:2048
	ds_read_b128 v[208:211], v169 offset:3072
	s_add_u32 s71, vcc_lo, 0xfff80800
	s_addc_u32 s73, vcc_hi, -1
	s_cmp_eq_u32 s70, 28
	s_cselect_b32 s75, s3, s73
	s_cselect_b32 s74, s7, s71
	s_cselect_b32 s77, s21, s17
	s_cselect_b32 s76, s72, s16
	v_lshl_add_u64 v[244:245], vcc, 0, v[136:137]
	s_add_i32 m0, s53, 0xc000
	ds_read_b128 v[212:215], v170
	ds_read_b128 v[216:219], v170 offset:1024
	ds_read_b128 v[220:223], v170 offset:2048
	ds_read_b128 v[224:227], v170 offset:3072
	ds_read_b128 v[228:231], v170 offset:4096
	ds_read_b128 v[232:235], v170 offset:5120
	ds_read_b128 v[236:239], v170 offset:6144
	ds_read_b128 v[240:243], v170 offset:7168
	global_load_lds_dwordx4 v[244:245], off
	v_lshl_add_u64 v[244:245], v[244:245], 0, s[0:1]
	s_add_i32 m0, s53, 0xe000
	s_nop 0
	global_load_lds_dwordx4 v[244:245], off
	s_waitcnt vmcnt(8)
	s_waitcnt lgkmcnt(0)
	s_barrier
	s_setprio 1
	v_mfma_f32_16x16x32_bf16 v[126:129], v[144:147], v[212:215], v[126:129]
	v_mfma_f32_16x16x32_bf16 v[126:129], v[184:187], v[216:219], v[126:129]
	v_mfma_f32_16x16x32_bf16 v[110:113], v[184:187], v[224:227], v[110:113]
	v_mfma_f32_16x16x32_bf16 v[110:113], v[144:147], v[220:223], v[110:113]
	v_mfma_f32_16x16x32_bf16 v[94:97], v[144:147], v[228:231], v[94:97]
	v_mfma_f32_16x16x32_bf16 v[94:97], v[184:187], v[232:235], v[94:97]
	v_mfma_f32_16x16x32_bf16 v[78:81], v[184:187], v[240:243], v[78:81]
	v_mfma_f32_16x16x32_bf16 v[78:81], v[144:147], v[236:239], v[78:81]
	v_mfma_f32_16x16x32_bf16 v[74:77], v[188:191], v[236:239], v[74:77]
	v_mfma_f32_16x16x32_bf16 v[74:77], v[192:195], v[240:243], v[74:77]
	v_mfma_f32_16x16x32_bf16 v[90:93], v[192:195], v[232:235], v[90:93]
	v_mfma_f32_16x16x32_bf16 v[90:93], v[188:191], v[228:231], v[90:93]
	v_mfma_f32_16x16x32_bf16 v[106:109], v[188:191], v[220:223], v[106:109]
	v_mfma_f32_16x16x32_bf16 v[106:109], v[192:195], v[224:227], v[106:109]
	v_mfma_f32_16x16x32_bf16 v[122:125], v[192:195], v[216:219], v[122:125]
	v_mfma_f32_16x16x32_bf16 v[122:125], v[188:191], v[212:215], v[122:125]
	v_mfma_f32_16x16x32_bf16 v[118:121], v[196:199], v[212:215], v[118:121]
	v_mfma_f32_16x16x32_bf16 v[118:121], v[200:203], v[216:219], v[118:121]
	v_mfma_f32_16x16x32_bf16 v[102:105], v[200:203], v[224:227], v[102:105]
	v_mfma_f32_16x16x32_bf16 v[102:105], v[196:199], v[220:223], v[102:105]
	v_mfma_f32_16x16x32_bf16 v[86:89], v[196:199], v[228:231], v[86:89]
	v_mfma_f32_16x16x32_bf16 v[86:89], v[200:203], v[232:235], v[86:89]
	v_mfma_f32_16x16x32_bf16 v[70:73], v[200:203], v[240:243], v[70:73]
	v_mfma_f32_16x16x32_bf16 v[70:73], v[196:199], v[236:239], v[70:73]
	v_mfma_f32_16x16x32_bf16 v[66:69], v[204:207], v[236:239], v[66:69]
	v_mfma_f32_16x16x32_bf16 v[66:69], v[208:211], v[240:243], v[66:69]
	v_mfma_f32_16x16x32_bf16 v[82:85], v[208:211], v[232:235], v[82:85]
	v_mfma_f32_16x16x32_bf16 v[82:85], v[204:207], v[228:231], v[82:85]
	s_barrier
	s_setprio 2
	v_mfma_f32_16x16x32_bf16 v[98:101], v[204:207], v[220:223], v[98:101]
	v_mfma_f32_16x16x32_bf16 v[98:101], v[208:211], v[224:227], v[98:101]
	v_mfma_f32_16x16x32_bf16 v[114:117], v[208:211], v[216:219], v[114:117]
	v_mfma_f32_16x16x32_bf16 v[114:117], v[204:207], v[212:215], v[114:117]
	s_setprio 0
	s_add_i32 s71, s64, s52
	v_lshl_add_u64 v[244:245], s[76:77], 0, v[130:131]
	s_mov_b32 m0, s71
	ds_read_b128 v[212:215], v170 offset:16384
	ds_read_b128 v[216:219], v170 offset:17408
	ds_read_b128 v[220:223], v170 offset:18432
	ds_read_b128 v[224:227], v170 offset:19456
	ds_read_b128 v[228:231], v170 offset:20480
	ds_read_b128 v[232:235], v170 offset:21504
	ds_read_b128 v[236:239], v170 offset:22528
	ds_read_b128 v[240:243], v170 offset:23552
	global_load_lds_dwordx4 v[244:245], off
	v_lshl_add_u64 v[246:247], v[244:245], 0, s[0:1]
	s_add_i32 m0, s71, 0x2000
	s_add_i32 s71, s65, s52
	global_load_lds_dwordx4 v[246:247], off
	v_lshl_add_u64 v[246:247], v[244:245], 0, s[14:15]
	s_mov_b32 m0, s71
	s_nop 0
	global_load_lds_dwordx4 v[246:247], off
	v_lshl_add_u64 v[246:247], v[244:245], 0, s[18:19]
	s_add_i32 m0, s71, 0x2000
	s_nop 0
	global_load_lds_dwordx4 v[246:247], off
	v_lshl_add_u64 v[246:247], s[74:75], 0, v[130:131]
	s_mov_b32 m0, s53
	v_lshl_add_u64 v[248:249], v[246:247], 0, s[0:1]
	global_load_lds_dwordx4 v[246:247], off
	s_mov_b32 m0, s54
	s_nop 0
	global_load_lds_dwordx4 v[248:249], off
	s_waitcnt vmcnt(8)
	s_waitcnt lgkmcnt(0)
	s_barrier
	s_setprio 1
	v_mfma_f32_16x16x32_bf16 v[62:65], v[144:147], v[212:215], v[62:65]
	v_mfma_f32_16x16x32_bf16 v[62:65], v[184:187], v[216:219], v[62:65]
	v_mfma_f32_16x16x32_bf16 v[46:49], v[184:187], v[224:227], v[46:49]
	v_mfma_f32_16x16x32_bf16 v[46:49], v[144:147], v[220:223], v[46:49]
	v_mfma_f32_16x16x32_bf16 v[30:33], v[144:147], v[228:231], v[30:33]
	v_mfma_f32_16x16x32_bf16 v[30:33], v[184:187], v[232:235], v[30:33]
	v_mfma_f32_16x16x32_bf16 v[14:17], v[184:187], v[240:243], v[14:17]
	v_mfma_f32_16x16x32_bf16 v[14:17], v[144:147], v[236:239], v[14:17]
	v_mfma_f32_16x16x32_bf16 v[10:13], v[188:191], v[236:239], v[10:13]
	v_mfma_f32_16x16x32_bf16 v[10:13], v[192:195], v[240:243], v[10:13]
	v_mfma_f32_16x16x32_bf16 v[26:29], v[192:195], v[232:235], v[26:29]
	v_mfma_f32_16x16x32_bf16 v[26:29], v[188:191], v[228:231], v[26:29]
	v_mfma_f32_16x16x32_bf16 v[42:45], v[188:191], v[220:223], v[42:45]
	v_mfma_f32_16x16x32_bf16 v[42:45], v[192:195], v[224:227], v[42:45]
	v_mfma_f32_16x16x32_bf16 v[58:61], v[192:195], v[216:219], v[58:61]
	v_mfma_f32_16x16x32_bf16 v[58:61], v[188:191], v[212:215], v[58:61]
	v_mfma_f32_16x16x32_bf16 v[54:57], v[196:199], v[212:215], v[54:57]
	v_mfma_f32_16x16x32_bf16 v[54:57], v[200:203], v[216:219], v[54:57]
	v_mfma_f32_16x16x32_bf16 v[38:41], v[200:203], v[224:227], v[38:41]
	v_mfma_f32_16x16x32_bf16 v[38:41], v[196:199], v[220:223], v[38:41]
	v_mfma_f32_16x16x32_bf16 v[22:25], v[196:199], v[228:231], v[22:25]
	v_mfma_f32_16x16x32_bf16 v[22:25], v[200:203], v[232:235], v[22:25]
	v_mfma_f32_16x16x32_bf16 v[6:9], v[200:203], v[240:243], v[6:9]
	v_mfma_f32_16x16x32_bf16 v[6:9], v[196:199], v[236:239], v[6:9]
	v_mfma_f32_16x16x32_bf16 v[2:5], v[204:207], v[236:239], v[2:5]
	v_mfma_f32_16x16x32_bf16 v[2:5], v[208:211], v[240:243], v[2:5]
	v_mfma_f32_16x16x32_bf16 v[18:21], v[208:211], v[232:235], v[18:21]
	v_mfma_f32_16x16x32_bf16 v[18:21], v[204:207], v[228:231], v[18:21]
	s_barrier
; #define PG8_STAGE(bufoff, gbase, voff) do { if constexpr (!pg8_noload<Epi>::value) { _Pragma("unroll") for (int _i = 0; _i < 2; ++_i) \
;         __builtin_amdgcn_global_load_lds((const unsigned*)((const char*)(gbase) + (size_t)_i * pstep + (voff)[0]), (PG8_LAS unsigned*)(lds + (bufoff) + ldsw + _i * 8192), 16, 0, 0); } } while (0)
; #define PG8_LDA(dst, b, h) do { _Pragma("unroll") for (int m = 0; m < 4; ++m) _Pragma("unroll") for (int k = 0; k < 2; ++k) dst[m][k] = *(const PG8_LAS bf16x8*)(lds + PG8_SA(b, h) + aoff + m * 2048 + k * 1024); } while (0)
; #define PG8_LDB(dst, b, h) do { _Pragma("unroll") for (int n = 0; n < 2; ++n) _Pragma("unroll") for (int k = 0; k < 2; ++k) dst[n][k] = *(const PG8_LAS bf16x8*)(lds + PG8_SB(b, h) + boff + n * 2048 + k * 1024); } while (0)
; #define PG8_MMA(ai, bj, At, Bt) do { __builtin_amdgcn_s_setprio(1); _Pragma("unroll") for (int m = 0; m < 4; ++m) _Pragma("unroll") for (int n = 0; n < 2; ++n) _Pragma("unroll") for (int k = 0; k < 2; ++k) \
;         acc[ai][bj][m][n] = __builtin_amdgcn_mfma_f32_16x16x32_bf16(Bt[n][k], At[m][k], acc[ai][bj][m][n], 0, 0, 0); __builtin_amdgcn_s_setprio(0); } while (0)
; #define PG8_WAIT_V(n) asm volatile("s_waitcnt vmcnt(" #n ")" ::: "memory")
; #define PG8_WAIT_L(n) asm volatile("s_waitcnt lgkmcnt(" #n ")" ::: "memory")
; #define PG8_BAR __builtin_amdgcn_s_barrier()
; #define PG8_SCHED __builtin_amdgcn_sched_barrier(0)
; template <class Epi, class Sched, bool ALIGN_EPI = false, bool SP2 = false, bool ABLK = false>
; __device__ __forceinline__ void gemm_phase(PG8_LAS unsigned char* lds, const Gemm g, const Sched& S, const Epi& E) {
;     ...
;             PG8_WAIT_V(8); PG8_WAIT_L(0); PG8_BAR; PG8_MMA(1, 0, At, B0); PG8_MMA(1, 1, At, B1); PG8_BAR; PG8_SCHED;
;             PG8_LDB(B0, 1, 0); PG8_LDB(B1, 1, 1); PG8_SCHED; PG8_LDA(At, 1, 0); PG8_STAGE(PG8_SA(0, 1), a2 + hstep, voffA);
;             PG8_WAIT_V(8); PG8_WAIT_L(0); PG8_BAR; PG8_MMA(0, 0, At, B0); PG8_MMA(0, 1, At, B1); PG8_BAR; PG8_SCHED;
	s_setprio 2
	v_mfma_f32_16x16x32_bf16 v[34:37], v[204:207], v[220:223], v[34:37]
	v_mfma_f32_16x16x32_bf16 v[34:37], v[208:211], v[224:227], v[34:37]
	v_mfma_f32_16x16x32_bf16 v[50:53], v[208:211], v[216:219], v[50:53]
	v_mfma_f32_16x16x32_bf16 v[50:53], v[204:207], v[212:215], v[50:53]
	s_setprio 0
	s_add_i32 s71, 0, 0x18000
	v_add_u32_e32 v133, s71, v149
	s_add_i32 s73, 0, 0x1c000
	ds_read_b128 v[144:147], v133
	ds_read_b128 v[184:187], v133 offset:1024
	ds_read_b128 v[188:191], v133 offset:2048
	ds_read_b128 v[192:195], v133 offset:3072
	v_add_u32_e32 v133, s73, v149
	ds_read_b128 v[196:199], v133
	ds_read_b128 v[200:203], v133 offset:1024
	ds_read_b128 v[204:207], v133 offset:2048
	ds_read_b128 v[208:211], v133 offset:3072
	s_mov_b32 m0, s55
	v_lshl_add_u64 v[248:249], v[246:247], 0, s[14:15]
	ds_read_b128 v[212:215], v170 offset:32768
	ds_read_b128 v[216:219], v170 offset:33792
	ds_read_b128 v[220:223], v170 offset:34816
	ds_read_b128 v[224:227], v170 offset:35840
	ds_read_b128 v[228:231], v170 offset:36864
	ds_read_b128 v[232:235], v170 offset:37888
	ds_read_b128 v[236:239], v170 offset:38912
	ds_read_b128 v[240:243], v170 offset:39936
	global_load_lds_dwordx4 v[248:249], off
	v_lshl_add_u64 v[248:249], v[246:247], 0, s[18:19]
	s_mov_b32 m0, s56
	s_nop 0
	global_load_lds_dwordx4 v[248:249], off
	s_waitcnt vmcnt(8)
	s_waitcnt lgkmcnt(0)
	s_barrier
	s_setprio 1
	v_mfma_f32_16x16x32_bf16 v[126:129], v[144:147], v[212:215], v[126:129]
	v_mfma_f32_16x16x32_bf16 v[126:129], v[184:187], v[216:219], v[126:129]
	v_mfma_f32_16x16x32_bf16 v[110:113], v[184:187], v[224:227], v[110:113]
	v_mfma_f32_16x16x32_bf16 v[110:113], v[144:147], v[220:223], v[110:113]
	v_mfma_f32_16x16x32_bf16 v[94:97], v[144:147], v[228:231], v[94:97]
	v_mfma_f32_16x16x32_bf16 v[94:97], v[184:187], v[232:235], v[94:97]
	v_mfma_f32_16x16x32_bf16 v[78:81], v[184:187], v[240:243], v[78:81]
	v_mfma_f32_16x16x32_bf16 v[78:81], v[144:147], v[236:239], v[78:81]
	v_mfma_f32_16x16x32_bf16 v[74:77], v[188:191], v[236:239], v[74:77]
	v_mfma_f32_16x16x32_bf16 v[74:77], v[192:195], v[240:243], v[74:77]
	v_mfma_f32_16x16x32_bf16 v[90:93], v[192:195], v[232:235], v[90:93]
	v_mfma_f32_16x16x32_bf16 v[90:93], v[188:191], v[228:231], v[90:93]
	v_mfma_f32_16x16x32_bf16 v[106:109], v[188:191], v[220:223], v[106:109]
	v_mfma_f32_16x16x32_bf16 v[106:109], v[192:195], v[224:227], v[106:109]
	v_mfma_f32_16x16x32_bf16 v[122:125], v[192:195], v[216:219], v[122:125]
	v_mfma_f32_16x16x32_bf16 v[122:125], v[188:191], v[212:215], v[122:125]
	v_mfma_f32_16x16x32_bf16 v[118:121], v[196:199], v[212:215], v[118:121]
	v_mfma_f32_16x16x32_bf16 v[118:121], v[200:203], v[216:219], v[118:121]
	v_mfma_f32_16x16x32_bf16 v[102:105], v[200:203], v[224:227], v[102:105]
	v_mfma_f32_16x16x32_bf16 v[102:105], v[196:199], v[220:223], v[102:105]
	v_mfma_f32_16x16x32_bf16 v[86:89], v[196:199], v[228:231], v[86:89]
	v_mfma_f32_16x16x32_bf16 v[86:89], v[200:203], v[232:235], v[86:89]
	v_mfma_f32_16x16x32_bf16 v[70:73], v[200:203], v[240:243], v[70:73]
	v_mfma_f32_16x16x32_bf16 v[70:73], v[196:199], v[236:239], v[70:73]
	v_mfma_f32_16x16x32_bf16 v[66:69], v[204:207], v[236:239], v[66:69]
	v_mfma_f32_16x16x32_bf16 v[66:69], v[208:211], v[240:243], v[66:69]
	v_mfma_f32_16x16x32_bf16 v[82:85], v[208:211], v[232:235], v[82:85]
	v_mfma_f32_16x16x32_bf16 v[82:85], v[204:207], v[228:231], v[82:85]
	s_barrier
;     __host__ __device__ bool next(int i, Unit& u) const { const bool ok = so.next(i, u); u.pm = 0; u.pn = 0; return ok; }
; #define PG8_STAGE(bufoff, gbase, voff) do { if constexpr (!pg8_noload<Epi>::value) { _Pragma("unroll") for (int _i = 0; _i < 2; ++_i) \
;         __builtin_amdgcn_global_load_lds((const unsigned*)((const char*)(gbase) + (size_t)_i * pstep + (voff)[0]), (PG8_LAS unsigned*)(lds + (bufoff) + ldsw + _i * 8192), 16, 0, 0); } } while (0)
; #define PG8_LDA(dst, b, h) do { _Pragma("unroll") for (int m = 0; m < 4; ++m) _Pragma("unroll") for (int k = 0; k < 2; ++k) dst[m][k] = *(const PG8_LAS bf16x8*)(lds + PG8_SA(b, h) + aoff + m * 2048 + k * 1024); } while (0)
; #define PG8_MMA(ai, bj, At, Bt) do { __builtin_amdgcn_s_setprio(1); _Pragma("unroll") for (int m = 0; m < 4; ++m) _Pragma("unroll") for (int n = 0; n < 2; ++n) _Pragma("unroll") for (int k = 0; k < 2; ++k) \
;         acc[ai][bj][m][n] = __builtin_amdgcn_mfma_f32_16x16x32_bf16(Bt[n][k], At[m][k], acc[ai][bj][m][n], 0, 0, 0); __builtin_amdgcn_s_setprio(0); } while (0)
; #define PG8_BAR __builtin_amdgcn_s_barrier()
; template <class Epi, class Sched, bool ALIGN_EPI = false, bool SP2 = false, bool ABLK = false>
; __device__ __forceinline__ void gemm_phase(PG8_LAS unsigned char* lds, const Gemm g, const Sched& S, const Epi& E) {
;     ...
;     for (;;) {
;         const bool has_next = S.next(ui + 1, nxt);
;         const char* nA = has_next ? (const char*)g.A + (size_t)nxt.pm * tstep + (size_t)nxt.ko * KOA : cA; const char* nB = has_next ? (const char*)g.Bt + (size_t)nxt.pn * tstep + (size_t)nxt.ko * 32 : cB;
;         for (int t = 0; t < nt; t += 2) {
;             const bool last = (t == nt - 2);
;             const char* a1 = cA + (size_t)(t + 1) * kstep;
;             const char* a2 = last ? nA : cA + (size_t)(t + 2) * kstep; const char* b2 = last ? nB : cB + (size_t)(t + 2) * kstepB;
;             const char* a3 = a2 + kstep; const char* b3 = b2 + kstepB;
;             if (last && has_next) S.a_ready(nxt);
;     ...
;             PG8_WAIT_V(8); PG8_WAIT_L(0); PG8_BAR; PG8_MMA(0, 0, At, B0); PG8_MMA(0, 1, At, B1); PG8_BAR; PG8_SCHED;
;             PG8_LDA(At, 1, 1); PG8_STAGE(PG8_SB(1, 0), b3, voffB); PG8_STAGE(PG8_SB(1, 1), b3 + hstep, voffB); PG8_STAGE(PG8_SA(1, 0), a3, voffA);
;             PG8_WAIT_V(8); PG8_WAIT_L(0); PG8_BAR; PG8_MMA(1, 0, At, B0); PG8_MMA(1, 1, At, B1); PG8_BAR; PG8_SCHED;
	s_setprio 2
	v_mfma_f32_16x16x32_bf16 v[98:101], v[204:207], v[220:223], v[98:101]
	v_mfma_f32_16x16x32_bf16 v[98:101], v[208:211], v[224:227], v[98:101]
	v_mfma_f32_16x16x32_bf16 v[114:117], v[208:211], v[216:219], v[114:117]
	v_mfma_f32_16x16x32_bf16 v[114:117], v[204:207], v[212:215], v[114:117]
	s_setprio 0
	s_add_i32 s71, s71, s52
	v_lshl_add_u64 v[248:249], v[244:245], 0, s[28:29]
	s_mov_b32 m0, s71
	ds_read_b128 v[212:215], v170 offset:49152
	ds_read_b128 v[216:219], v170 offset:50176
	ds_read_b128 v[220:223], v170 offset:51200
	ds_read_b128 v[224:227], v170 offset:52224
	ds_read_b128 v[228:231], v170 offset:53248
	ds_read_b128 v[232:235], v170 offset:54272
	ds_read_b128 v[236:239], v170 offset:55296
	ds_read_b128 v[240:243], v170 offset:56320
	global_load_lds_dwordx4 v[248:249], off
	v_lshl_add_u64 v[248:249], v[244:245], 0, s[30:31]
	s_add_i32 m0, s71, 0x2000
	s_add_i32 s71, s73, s52
	global_load_lds_dwordx4 v[248:249], off
	v_lshl_add_u64 v[248:249], v[244:245], 0, s[34:35]
	s_mov_b32 m0, s71
	v_lshl_add_u64 v[244:245], v[244:245], 0, s[36:37]
	global_load_lds_dwordx4 v[248:249], off
	s_add_i32 m0, s71, 0x2000
	s_nop 0
	global_load_lds_dwordx4 v[244:245], off
	v_lshl_add_u64 v[244:245], v[246:247], 0, s[28:29]
	s_mov_b32 m0, s59
	s_nop 0
	global_load_lds_dwordx4 v[244:245], off
	v_lshl_add_u64 v[244:245], v[246:247], 0, s[30:31]
	s_mov_b32 m0, s60
	s_nop 0
	global_load_lds_dwordx4 v[244:245], off
	s_waitcnt vmcnt(8)
	s_waitcnt lgkmcnt(0)
	s_barrier
	s_setprio 1
	v_mfma_f32_16x16x32_bf16 v[62:65], v[144:147], v[212:215], v[62:65]
	v_mfma_f32_16x16x32_bf16 v[62:65], v[184:187], v[216:219], v[62:65]
	v_mfma_f32_16x16x32_bf16 v[46:49], v[184:187], v[224:227], v[46:49]
	v_mfma_f32_16x16x32_bf16 v[46:49], v[144:147], v[220:223], v[46:49]
	v_mfma_f32_16x16x32_bf16 v[30:33], v[144:147], v[228:231], v[30:33]
	v_mfma_f32_16x16x32_bf16 v[30:33], v[184:187], v[232:235], v[30:33]
	v_mfma_f32_16x16x32_bf16 v[14:17], v[184:187], v[240:243], v[14:17]
	v_mfma_f32_16x16x32_bf16 v[14:17], v[144:147], v[236:239], v[14:17]
	v_mfma_f32_16x16x32_bf16 v[10:13], v[188:191], v[236:239], v[10:13]
	v_mfma_f32_16x16x32_bf16 v[10:13], v[192:195], v[240:243], v[10:13]
	v_mfma_f32_16x16x32_bf16 v[26:29], v[192:195], v[232:235], v[26:29]
	v_mfma_f32_16x16x32_bf16 v[26:29], v[188:191], v[228:231], v[26:29]
	v_mfma_f32_16x16x32_bf16 v[42:45], v[188:191], v[220:223], v[42:45]
	v_mfma_f32_16x16x32_bf16 v[42:45], v[192:195], v[224:227], v[42:45]
	v_mfma_f32_16x16x32_bf16 v[58:61], v[192:195], v[216:219], v[58:61]
	v_mfma_f32_16x16x32_bf16 v[58:61], v[188:191], v[212:215], v[58:61]
	v_mfma_f32_16x16x32_bf16 v[54:57], v[196:199], v[212:215], v[54:57]
	v_mfma_f32_16x16x32_bf16 v[54:57], v[200:203], v[216:219], v[54:57]
	v_mfma_f32_16x16x32_bf16 v[38:41], v[200:203], v[224:227], v[38:41]
	v_mfma_f32_16x16x32_bf16 v[38:41], v[196:199], v[220:223], v[38:41]
	v_mfma_f32_16x16x32_bf16 v[22:25], v[196:199], v[228:231], v[22:25]
	v_mfma_f32_16x16x32_bf16 v[22:25], v[200:203], v[232:235], v[22:25]
	v_mfma_f32_16x16x32_bf16 v[6:9], v[200:203], v[240:243], v[6:9]
	v_mfma_f32_16x16x32_bf16 v[6:9], v[196:199], v[236:239], v[6:9]
	v_mfma_f32_16x16x32_bf16 v[2:5], v[204:207], v[236:239], v[2:5]
	v_mfma_f32_16x16x32_bf16 v[2:5], v[208:211], v[240:243], v[2:5]
	v_mfma_f32_16x16x32_bf16 v[18:21], v[208:211], v[232:235], v[18:21]
	v_mfma_f32_16x16x32_bf16 v[18:21], v[204:207], v[228:231], v[18:21]
	s_barrier
	s_setprio 2
	v_mfma_f32_16x16x32_bf16 v[34:37], v[204:207], v[220:223], v[34:37]
	v_mfma_f32_16x16x32_bf16 v[34:37], v[208:211], v[224:227], v[34:37]
	v_mfma_f32_16x16x32_bf16 v[50:53], v[208:211], v[216:219], v[50:53]
	v_mfma_f32_16x16x32_bf16 v[50:53], v[204:207], v[212:215], v[50:53]
	s_setprio 0
	s_add_i32 s70, s70, 2
	s_add_u32 vcc_lo, vcc_lo, 0x1000
	s_addc_u32 vcc_hi, vcc_hi, 0
	s_add_u32 s16, s16, 0x1000
	s_addc_u32 s17, s17, 0
	s_cmp_gt_u32 s70, 29
	s_cbranch_scc0 .LBB0_114
	s_and_b64 vcc, exec, s[38:39]
	s_cbranch_vccz .LBB0_117
	s_barrier

; #define PG8_STAGE(bufoff, gbase, voff) do { if constexpr (!pg8_noload<Epi>::value) { _Pragma("unroll") for (int _i = 0; _i < 2; ++_i) \
;         __builtin_amdgcn_global_load_lds((const unsigned*)((const char*)(gbase) + (size_t)_i * pstep + (voff)[0]), (PG8_LAS unsigned*)(lds + (bufoff) + ldsw + _i * 8192), 16, 0, 0); } } while (0)
; #define PG8_LDA(dst, b, h) do { _Pragma("unroll") for (int m = 0; m < 4; ++m) _Pragma("unroll") for (int k = 0; k < 2; ++k) dst[m][k] = *(const PG8_LAS bf16x8*)(lds + PG8_SA(b, h) + aoff + m * 2048 + k * 1024); } while (0)
; #define PG8_LDB(dst, b, h) do { _Pragma("unroll") for (int n = 0; n < 2; ++n) _Pragma("unroll") for (int k = 0; k < 2; ++k) dst[n][k] = *(const PG8_LAS bf16x8*)(lds + PG8_SB(b, h) + boff + n * 2048 + k * 1024); } while (0)
; #define PG8_MMA(ai, bj, At, Bt) do { __builtin_amdgcn_s_setprio(1); _Pragma("unroll") for (int m = 0; m < 4; ++m) _Pragma("unroll") for (int n = 0; n < 2; ++n) _Pragma("unroll") for (int k = 0; k < 2; ++k) \
;         acc[ai][bj][m][n] = __builtin_amdgcn_mfma_f32_16x16x32_bf16(Bt[n][k], At[m][k], acc[ai][bj][m][n], 0, 0, 0); __builtin_amdgcn_s_setprio(0); } while (0)
; #define PG8_BAR __builtin_amdgcn_s_barrier()
; template <class Epi, class Sched, bool ALIGN_EPI = false, bool SP2 = false, bool ABLK = false>
; __device__ __forceinline__ void gemm_phase(PG8_LAS unsigned char* lds, const Gemm g, const Sched& S, const Epi& E) {
;     ...
;         for (int t = 0; t < nt; t += 2) {
;             const bool last = (t == nt - 2);
;             const char* a1 = cA + (size_t)(t + 1) * kstep;
;             const char* a2 = last ? nA : cA + (size_t)(t + 2) * kstep; const char* b2 = last ? nB : cB + (size_t)(t + 2) * kstepB;
;             const char* a3 = a2 + kstep; const char* b3 = b2 + kstepB;
;             if (last && has_next) S.a_ready(nxt);
;             if constexpr (SP2) {
;             PG8_LDB(B0, 0, 0); PG8_LDB(B1, 0, 1); PG8_SCHED; PG8_LDA(At, 0, 0); PG8_STAGE(PG8_SA(1, 1), a1 + hstep, voffA);
;             PG8_WAIT_V(8); PG8_WAIT_L(0); PG8_BAR; PG8_MMA(0, 0, At, B0); PG8_MMA(0, 1, At, B1); PG8_BAR; PG8_SCHED;
;             PG8_LDA(At, 0, 1); PG8_STAGE(PG8_SB(0, 0), b2, voffB); PG8_STAGE(PG8_SB(0, 1), b2 + hstep, voffB); PG8_STAGE(PG8_SA(0, 0), a2, voffA);
;             PG8_WAIT_V(8); PG8_WAIT_L(0); PG8_BAR; PG8_MMA(1, 0, At, B0); PG8_MMA(1, 1, At, B1); PG8_BAR; PG8_SCHED;
.LBB0_487:
	ds_read_b128 v[114:117], v167
	ds_read_b128 v[126:129], v167 offset:1024
	ds_read_b128 v[130:133], v167 offset:2048
	ds_read_b128 v[142:145], v167 offset:3072
	ds_read_b128 v[146:149], v168
	ds_read_b128 v[150:153], v168 offset:1024
	ds_read_b128 v[174:177], v168 offset:2048
	ds_read_b128 v[178:181], v168 offset:3072
	s_add_i32 s65, s39, 2
	s_add_u32 s68, s92, 0xfff00800
	s_addc_u32 s69, s93, -1
	s_cmp_eq_u32 s3, s39
	s_cselect_b32 s69, s79, s69
	s_cselect_b32 s68, s78, s68
	s_cselect_b32 s71, s89, s37
	s_cselect_b32 s70, s88, s11
	v_lshl_add_u64 v[162:163], s[92:93], 0, v[158:159]
	s_add_i32 m0, s56, 0xc000
	ds_read_b128 v[184:187], v169
	ds_read_b128 v[188:191], v169 offset:1024
	ds_read_b128 v[192:195], v169 offset:2048
	ds_read_b128 v[196:199], v169 offset:3072
	ds_read_b128 v[200:203], v169 offset:4096
	ds_read_b128 v[204:207], v169 offset:5120
	ds_read_b128 v[208:211], v169 offset:6144
	ds_read_b128 v[212:215], v169 offset:7168
	global_load_lds_dwordx4 v[162:163], off
	v_lshl_add_u64 v[162:163], v[162:163], 0, s[12:13]
	s_add_i32 m0, s56, 0xe000
	s_nop 0
	global_load_lds_dwordx4 v[162:163], off
	s_waitcnt vmcnt(8)
	s_waitcnt lgkmcnt(0)
	s_barrier
	s_setprio 1
	v_mfma_f32_16x16x32_bf16 v[138:141], v[114:117], v[184:187], v[138:141]
	v_mfma_f32_16x16x32_bf16 v[138:141], v[126:129], v[188:191], v[138:141]
	v_mfma_f32_16x16x32_bf16 v[110:113], v[126:129], v[196:199], v[110:113]
	v_mfma_f32_16x16x32_bf16 v[110:113], v[114:117], v[192:195], v[110:113]
	v_mfma_f32_16x16x32_bf16 v[94:97], v[114:117], v[200:203], v[94:97]
	v_mfma_f32_16x16x32_bf16 v[94:97], v[126:129], v[204:207], v[94:97]
	v_mfma_f32_16x16x32_bf16 v[78:81], v[126:129], v[212:215], v[78:81]
	v_mfma_f32_16x16x32_bf16 v[78:81], v[114:117], v[208:211], v[78:81]
	v_mfma_f32_16x16x32_bf16 v[74:77], v[130:133], v[208:211], v[74:77]
	v_mfma_f32_16x16x32_bf16 v[74:77], v[142:145], v[212:215], v[74:77]
	v_mfma_f32_16x16x32_bf16 v[90:93], v[142:145], v[204:207], v[90:93]
	v_mfma_f32_16x16x32_bf16 v[90:93], v[130:133], v[200:203], v[90:93]
	v_mfma_f32_16x16x32_bf16 v[106:109], v[130:133], v[192:195], v[106:109]
	v_mfma_f32_16x16x32_bf16 v[106:109], v[142:145], v[196:199], v[106:109]
	v_mfma_f32_16x16x32_bf16 v[134:137], v[142:145], v[188:191], v[134:137]
	v_mfma_f32_16x16x32_bf16 v[134:137], v[130:133], v[184:187], v[134:137]
	v_mfma_f32_16x16x32_bf16 v[122:125], v[146:149], v[184:187], v[122:125]
	v_mfma_f32_16x16x32_bf16 v[122:125], v[150:153], v[188:191], v[122:125]
	v_mfma_f32_16x16x32_bf16 v[102:105], v[150:153], v[196:199], v[102:105]
	v_mfma_f32_16x16x32_bf16 v[102:105], v[146:149], v[192:195], v[102:105]
	v_mfma_f32_16x16x32_bf16 v[86:89], v[146:149], v[200:203], v[86:89]
	v_mfma_f32_16x16x32_bf16 v[86:89], v[150:153], v[204:207], v[86:89]
	v_mfma_f32_16x16x32_bf16 v[70:73], v[150:153], v[212:215], v[70:73]
	v_mfma_f32_16x16x32_bf16 v[70:73], v[146:149], v[208:211], v[70:73]
	v_mfma_f32_16x16x32_bf16 v[66:69], v[174:177], v[208:211], v[66:69]
	v_mfma_f32_16x16x32_bf16 v[66:69], v[178:181], v[212:215], v[66:69]
	v_mfma_f32_16x16x32_bf16 v[82:85], v[178:181], v[204:207], v[82:85]
	v_mfma_f32_16x16x32_bf16 v[82:85], v[174:177], v[200:203], v[82:85]
	s_barrier
	s_setprio 2
	v_mfma_f32_16x16x32_bf16 v[98:101], v[174:177], v[192:195], v[98:101]
	v_mfma_f32_16x16x32_bf16 v[98:101], v[178:181], v[196:199], v[98:101]
	v_mfma_f32_16x16x32_bf16 v[118:121], v[178:181], v[188:191], v[118:121]
	v_mfma_f32_16x16x32_bf16 v[118:121], v[174:177], v[184:187], v[118:121]
	s_setprio 0
	s_add_i32 s39, s73, s55
	v_lshl_add_u64 v[162:163], s[70:71], 0, v[154:155]
	s_mov_b32 m0, s39
	ds_read_b128 v[184:187], v169 offset:16384
	ds_read_b128 v[188:191], v169 offset:17408
	ds_read_b128 v[192:195], v169 offset:18432
	ds_read_b128 v[196:199], v169 offset:19456
	ds_read_b128 v[200:203], v169 offset:20480
	ds_read_b128 v[204:207], v169 offset:21504
	ds_read_b128 v[208:211], v169 offset:22528
	ds_read_b128 v[212:215], v169 offset:23552
	global_load_lds_dwordx4 v[162:163], off
	v_lshl_add_u64 v[216:217], v[162:163], 0, s[12:13]
	s_add_i32 m0, s39, 0x2000
	s_add_i32 s39, s74, s55
	global_load_lds_dwordx4 v[216:217], off
	v_lshl_add_u64 v[216:217], v[162:163], 0, s[14:15]
	s_mov_b32 m0, s39
	s_nop 0
	global_load_lds_dwordx4 v[216:217], off
	v_lshl_add_u64 v[216:217], v[162:163], 0, s[16:17]
	s_add_i32 m0, s39, 0x2000
	s_nop 0
	global_load_lds_dwordx4 v[216:217], off
	v_lshl_add_u64 v[216:217], s[68:69], 0, v[154:155]
	s_mov_b32 m0, s56
	v_lshl_add_u64 v[218:219], v[216:217], 0, s[12:13]
	global_load_lds_dwordx4 v[216:217], off
	s_mov_b32 m0, s57
	s_nop 0
	global_load_lds_dwordx4 v[218:219], off
	s_waitcnt vmcnt(8)
	s_waitcnt lgkmcnt(0)
	s_barrier
; #define PG8_STAGE(bufoff, gbase, voff) do { if constexpr (!pg8_noload<Epi>::value) { _Pragma("unroll") for (int _i = 0; _i < 2; ++_i) \
;         __builtin_amdgcn_global_load_lds((const unsigned*)((const char*)(gbase) + (size_t)_i * pstep + (voff)[0]), (PG8_LAS unsigned*)(lds + (bufoff) + ldsw + _i * 8192), 16, 0, 0); } } while (0)
; #define PG8_LDA(dst, b, h) do { _Pragma("unroll") for (int m = 0; m < 4; ++m) _Pragma("unroll") for (int k = 0; k < 2; ++k) dst[m][k] = *(const PG8_LAS bf16x8*)(lds + PG8_SA(b, h) + aoff + m * 2048 + k * 1024); } while (0)
; #define PG8_LDB(dst, b, h) do { _Pragma("unroll") for (int n = 0; n < 2; ++n) _Pragma("unroll") for (int k = 0; k < 2; ++k) dst[n][k] = *(const PG8_LAS bf16x8*)(lds + PG8_SB(b, h) + boff + n * 2048 + k * 1024); } while (0)
; #define PG8_MMA(ai, bj, At, Bt) do { __builtin_amdgcn_s_setprio(1); _Pragma("unroll") for (int m = 0; m < 4; ++m) _Pragma("unroll") for (int n = 0; n < 2; ++n) _Pragma("unroll") for (int k = 0; k < 2; ++k) \
;         acc[ai][bj][m][n] = __builtin_amdgcn_mfma_f32_16x16x32_bf16(Bt[n][k], At[m][k], acc[ai][bj][m][n], 0, 0, 0); __builtin_amdgcn_s_setprio(0); } while (0)
; #define PG8_WAIT_V(n) asm volatile("s_waitcnt vmcnt(" #n ")" ::: "memory")
; #define PG8_WAIT_L(n) asm volatile("s_waitcnt lgkmcnt(" #n ")" ::: "memory")
; #define PG8_BAR __builtin_amdgcn_s_barrier()
; #define PG8_SCHED __builtin_amdgcn_sched_barrier(0)
; template <class Epi, class Sched, bool ALIGN_EPI = false, bool SP2 = false, bool ABLK = false>
; __device__ __forceinline__ void gemm_phase(PG8_LAS unsigned char* lds, const Gemm g, const Sched& S, const Epi& E) {
;     ...
;             PG8_WAIT_V(8); PG8_WAIT_L(0); PG8_BAR; PG8_MMA(1, 0, At, B0); PG8_MMA(1, 1, At, B1); PG8_BAR; PG8_SCHED;
;             PG8_LDB(B0, 1, 0); PG8_LDB(B1, 1, 1); PG8_SCHED; PG8_LDA(At, 1, 0); PG8_STAGE(PG8_SA(0, 1), a2 + hstep, voffA);
;             PG8_WAIT_V(8); PG8_WAIT_L(0); PG8_BAR; PG8_MMA(0, 0, At, B0); PG8_MMA(0, 1, At, B1); PG8_BAR; PG8_SCHED;
	s_setprio 1
	v_mfma_f32_16x16x32_bf16 v[62:65], v[114:117], v[184:187], v[62:65]
	v_mfma_f32_16x16x32_bf16 v[62:65], v[126:129], v[188:191], v[62:65]
	v_mfma_f32_16x16x32_bf16 v[46:49], v[126:129], v[196:199], v[46:49]
	v_mfma_f32_16x16x32_bf16 v[46:49], v[114:117], v[192:195], v[46:49]
	v_mfma_f32_16x16x32_bf16 v[30:33], v[114:117], v[200:203], v[30:33]
	v_mfma_f32_16x16x32_bf16 v[30:33], v[126:129], v[204:207], v[30:33]
	v_mfma_f32_16x16x32_bf16 v[14:17], v[126:129], v[212:215], v[14:17]
	v_mfma_f32_16x16x32_bf16 v[14:17], v[114:117], v[208:211], v[14:17]
	v_mfma_f32_16x16x32_bf16 v[10:13], v[130:133], v[208:211], v[10:13]
	v_mfma_f32_16x16x32_bf16 v[10:13], v[142:145], v[212:215], v[10:13]
	v_mfma_f32_16x16x32_bf16 v[26:29], v[142:145], v[204:207], v[26:29]
	v_mfma_f32_16x16x32_bf16 v[26:29], v[130:133], v[200:203], v[26:29]
	v_mfma_f32_16x16x32_bf16 v[42:45], v[130:133], v[192:195], v[42:45]
	v_mfma_f32_16x16x32_bf16 v[42:45], v[142:145], v[196:199], v[42:45]
	v_mfma_f32_16x16x32_bf16 v[58:61], v[142:145], v[188:191], v[58:61]
	v_mfma_f32_16x16x32_bf16 v[58:61], v[130:133], v[184:187], v[58:61]
	v_mfma_f32_16x16x32_bf16 v[54:57], v[146:149], v[184:187], v[54:57]
	v_mfma_f32_16x16x32_bf16 v[54:57], v[150:153], v[188:191], v[54:57]
	v_mfma_f32_16x16x32_bf16 v[38:41], v[150:153], v[196:199], v[38:41]
	v_mfma_f32_16x16x32_bf16 v[38:41], v[146:149], v[192:195], v[38:41]
	v_mfma_f32_16x16x32_bf16 v[22:25], v[146:149], v[200:203], v[22:25]
	v_mfma_f32_16x16x32_bf16 v[22:25], v[150:153], v[204:207], v[22:25]
	v_mfma_f32_16x16x32_bf16 v[6:9], v[150:153], v[212:215], v[6:9]
	v_mfma_f32_16x16x32_bf16 v[6:9], v[146:149], v[208:211], v[6:9]
	v_mfma_f32_16x16x32_bf16 v[2:5], v[174:177], v[208:211], v[2:5]
	v_mfma_f32_16x16x32_bf16 v[2:5], v[178:181], v[212:215], v[2:5]
	v_mfma_f32_16x16x32_bf16 v[18:21], v[178:181], v[204:207], v[18:21]
	v_mfma_f32_16x16x32_bf16 v[18:21], v[174:177], v[200:203], v[18:21]
	s_barrier
	s_setprio 2
	v_mfma_f32_16x16x32_bf16 v[34:37], v[174:177], v[192:195], v[34:37]
	v_mfma_f32_16x16x32_bf16 v[34:37], v[178:181], v[196:199], v[34:37]
	v_mfma_f32_16x16x32_bf16 v[50:53], v[178:181], v[188:191], v[50:53]
	v_mfma_f32_16x16x32_bf16 v[50:53], v[174:177], v[184:187], v[50:53]
	s_setprio 0
	s_add_i32 s39, 0, 0x18000
	s_add_i32 s68, 0, 0x1c000
	v_add_u32_e32 v142, s39, v1
	v_add_u32_e32 v173, s68, v1
	ds_read_b128 v[114:117], v142
	ds_read_b128 v[126:129], v142 offset:1024
	ds_read_b128 v[130:133], v142 offset:2048
	ds_read_b128 v[142:145], v142 offset:3072
	ds_read_b128 v[146:149], v173
	ds_read_b128 v[150:153], v173 offset:1024
	ds_read_b128 v[174:177], v173 offset:2048
	ds_read_b128 v[178:181], v173 offset:3072
	s_mov_b32 m0, s58
	v_lshl_add_u64 v[218:219], v[216:217], 0, s[14:15]
	ds_read_b128 v[184:187], v169 offset:32768
	ds_read_b128 v[188:191], v169 offset:33792
	ds_read_b128 v[192:195], v169 offset:34816
	ds_read_b128 v[196:199], v169 offset:35840
	ds_read_b128 v[200:203], v169 offset:36864
	ds_read_b128 v[204:207], v169 offset:37888
	ds_read_b128 v[208:211], v169 offset:38912
	ds_read_b128 v[212:215], v169 offset:39936
	global_load_lds_dwordx4 v[218:219], off
	v_lshl_add_u64 v[218:219], v[216:217], 0, s[16:17]
	s_mov_b32 m0, s59
	s_nop 0
	global_load_lds_dwordx4 v[218:219], off
	s_waitcnt vmcnt(8)
	s_waitcnt lgkmcnt(0)
	s_barrier
	s_setprio 1
	v_mfma_f32_16x16x32_bf16 v[138:141], v[114:117], v[184:187], v[138:141]
	v_mfma_f32_16x16x32_bf16 v[138:141], v[126:129], v[188:191], v[138:141]
	v_mfma_f32_16x16x32_bf16 v[110:113], v[126:129], v[196:199], v[110:113]
	v_mfma_f32_16x16x32_bf16 v[110:113], v[114:117], v[192:195], v[110:113]
	v_mfma_f32_16x16x32_bf16 v[94:97], v[114:117], v[200:203], v[94:97]
	v_mfma_f32_16x16x32_bf16 v[94:97], v[126:129], v[204:207], v[94:97]
	v_mfma_f32_16x16x32_bf16 v[78:81], v[126:129], v[212:215], v[78:81]
	v_mfma_f32_16x16x32_bf16 v[78:81], v[114:117], v[208:211], v[78:81]
	v_mfma_f32_16x16x32_bf16 v[74:77], v[130:133], v[208:211], v[74:77]
	v_mfma_f32_16x16x32_bf16 v[74:77], v[142:145], v[212:215], v[74:77]
	v_mfma_f32_16x16x32_bf16 v[90:93], v[142:145], v[204:207], v[90:93]
	v_mfma_f32_16x16x32_bf16 v[90:93], v[130:133], v[200:203], v[90:93]
	v_mfma_f32_16x16x32_bf16 v[106:109], v[130:133], v[192:195], v[106:109]
	v_mfma_f32_16x16x32_bf16 v[106:109], v[142:145], v[196:199], v[106:109]
	v_mfma_f32_16x16x32_bf16 v[134:137], v[142:145], v[188:191], v[134:137]
	v_mfma_f32_16x16x32_bf16 v[134:137], v[130:133], v[184:187], v[134:137]
	v_mfma_f32_16x16x32_bf16 v[122:125], v[146:149], v[184:187], v[122:125]
	v_mfma_f32_16x16x32_bf16 v[122:125], v[150:153], v[188:191], v[122:125]
	v_mfma_f32_16x16x32_bf16 v[102:105], v[150:153], v[196:199], v[102:105]
	v_mfma_f32_16x16x32_bf16 v[102:105], v[146:149], v[192:195], v[102:105]
	v_mfma_f32_16x16x32_bf16 v[86:89], v[146:149], v[200:203], v[86:89]
	v_mfma_f32_16x16x32_bf16 v[86:89], v[150:153], v[204:207], v[86:89]
	v_mfma_f32_16x16x32_bf16 v[70:73], v[150:153], v[212:215], v[70:73]
	v_mfma_f32_16x16x32_bf16 v[70:73], v[146:149], v[208:211], v[70:73]
	v_mfma_f32_16x16x32_bf16 v[66:69], v[174:177], v[208:211], v[66:69]
	v_mfma_f32_16x16x32_bf16 v[66:69], v[178:181], v[212:215], v[66:69]
	v_mfma_f32_16x16x32_bf16 v[82:85], v[178:181], v[204:207], v[82:85]
	v_mfma_f32_16x16x32_bf16 v[82:85], v[174:177], v[200:203], v[82:85]
	s_barrier
; #define PG8_LDA(dst, b, h) do { _Pragma("unroll") for (int m = 0; m < 4; ++m) _Pragma("unroll") for (int k = 0; k < 2; ++k) dst[m][k] = *(const PG8_LAS bf16x8*)(lds + PG8_SA(b, h) + aoff + m * 2048 + k * 1024); } while (0)
; #define PG8_WAIT_V(n) asm volatile("s_waitcnt vmcnt(" #n ")" ::: "memory")
; template <class Epi, class Sched, bool ALIGN_EPI = false, bool SP2 = false, bool ABLK = false>
; __device__ __forceinline__ void gemm_phase(PG8_LAS unsigned char* lds, const Gemm g, const Sched& S, const Epi& E) {
;     ...
;             PG8_WAIT_V(8); PG8_WAIT_L(0); PG8_BAR; PG8_MMA(0, 0, At, B0); PG8_MMA(0, 1, At, B1); PG8_BAR; PG8_SCHED;
;             PG8_LDA(At, 1, 1); PG8_STAGE(PG8_SB(1, 0), b3, voffB); PG8_STAGE(PG8_SB(1, 1), b3 + hstep, voffB); PG8_STAGE(PG8_SA(1, 0), a3, voffA);
;             PG8_WAIT_V(8); PG8_WAIT_L(0); PG8_BAR; PG8_MMA(1, 0, At, B0); PG8_MMA(1, 1, At, B1); PG8_BAR; PG8_SCHED;
;             } else {
;             PG8_LDB(B0, 0, 0); PG8_SCHED; PG8_LDA(At, 0, 0); PG8_STAGE(PG8_SA(1, 1), a1 + hstep, voffA);
;             PG8_WAIT_L(8); PG8_BAR; PG8_WAIT_L(0); PG8_MMA(0, 0, At, B0); PG8_BAR; PG8_SCHED;
;             PG8_LDB(B1, 0, 1); PG8_STAGE(PG8_SB(0, 0), b2, voffB);
;             PG8_BAR; PG8_WAIT_L(0); PG8_MMA(0, 1, At, B1); PG8_BAR;
;             PG8_LDA(At, 0, 1); PG8_STAGE(PG8_SA(0, 0), a2, voffA);
;             PG8_BAR; PG8_WAIT_L(0); PG8_MMA(1, 0, At, B0); PG8_BAR; PG8_SCHED;
;             PG8_STAGE(PG8_SB(0, 1), b2 + hstep, voffB);
;             PG8_WAIT_V(6); PG8_BAR; PG8_MMA(1, 1, At, B1); PG8_BAR;
;             PG8_LDB(B0, 1, 0); PG8_SCHED; PG8_LDA(At, 1, 0); PG8_STAGE(PG8_SA(0, 1), a2 + hstep, voffA);
;             PG8_WAIT_L(8); PG8_BAR; PG8_WAIT_L(0); PG8_MMA(0, 0, At, B0); PG8_BAR; PG8_SCHED;
;             PG8_LDB(B1, 1, 1); PG8_STAGE(PG8_SB(1, 0), b3, voffB);
;             PG8_BAR; PG8_WAIT_L(0); PG8_MMA(0, 1, At, B1); PG8_BAR;
;             PG8_LDA(At, 1, 1); PG8_STAGE(PG8_SA(1, 0), a3, voffA);
;             PG8_BAR; PG8_WAIT_L(0); PG8_MMA(1, 0, At, B0); PG8_BAR; PG8_SCHED;
;             PG8_STAGE(PG8_SB(1, 1), b3 + hstep, voffB);
;             PG8_WAIT_V(6); PG8_BAR; PG8_MMA(1, 1, At, B1); PG8_BAR;
;             }
;         }
;         if constexpr (ALIGN_EPI) { if (wr == 0) PG8_BAR; }
;         if constexpr (!Epi::AFTER_DRAIN) { E(acc, cur, wr, wc, fr, fq); S.done(cur); }
;         if (!has_next) break;
	s_setprio 2
	v_mfma_f32_16x16x32_bf16 v[98:101], v[174:177], v[192:195], v[98:101]
	v_mfma_f32_16x16x32_bf16 v[98:101], v[178:181], v[196:199], v[98:101]
	v_mfma_f32_16x16x32_bf16 v[118:121], v[178:181], v[188:191], v[118:121]
	v_mfma_f32_16x16x32_bf16 v[118:121], v[174:177], v[184:187], v[118:121]
	s_setprio 0
	s_add_i32 s39, s39, s55
	v_lshl_add_u64 v[218:219], v[162:163], 0, s[24:25]
	s_mov_b32 m0, s39
	ds_read_b128 v[184:187], v169 offset:49152
	ds_read_b128 v[188:191], v169 offset:50176
	ds_read_b128 v[192:195], v169 offset:51200
	ds_read_b128 v[196:199], v169 offset:52224
	ds_read_b128 v[200:203], v169 offset:53248
	ds_read_b128 v[204:207], v169 offset:54272
	ds_read_b128 v[208:211], v169 offset:55296
	ds_read_b128 v[212:215], v169 offset:56320
	global_load_lds_dwordx4 v[218:219], off
	v_lshl_add_u64 v[218:219], v[162:163], 0, s[26:27]
	s_add_i32 m0, s39, 0x2000
	s_add_i32 s39, s68, s55
	global_load_lds_dwordx4 v[218:219], off
	v_lshl_add_u64 v[218:219], v[162:163], 0, s[28:29]
	s_mov_b32 m0, s39
	v_lshl_add_u64 v[162:163], v[162:163], 0, s[30:31]
	global_load_lds_dwordx4 v[218:219], off
	s_add_i32 m0, s39, 0x2000
	s_nop 0
	global_load_lds_dwordx4 v[162:163], off
	v_lshl_add_u64 v[162:163], v[216:217], 0, s[24:25]
	s_mov_b32 m0, s62
	s_nop 0
	global_load_lds_dwordx4 v[162:163], off
	v_lshl_add_u64 v[162:163], v[216:217], 0, s[26:27]
	s_mov_b32 m0, s63
	s_nop 0
	global_load_lds_dwordx4 v[162:163], off
	s_waitcnt vmcnt(8)
	s_waitcnt lgkmcnt(0)
	s_barrier
	s_setprio 1
	v_mfma_f32_16x16x32_bf16 v[62:65], v[114:117], v[184:187], v[62:65]
	v_mfma_f32_16x16x32_bf16 v[62:65], v[126:129], v[188:191], v[62:65]
	v_mfma_f32_16x16x32_bf16 v[46:49], v[126:129], v[196:199], v[46:49]
	v_mfma_f32_16x16x32_bf16 v[46:49], v[114:117], v[192:195], v[46:49]
	v_mfma_f32_16x16x32_bf16 v[30:33], v[114:117], v[200:203], v[30:33]
	v_mfma_f32_16x16x32_bf16 v[30:33], v[126:129], v[204:207], v[30:33]
	v_mfma_f32_16x16x32_bf16 v[14:17], v[126:129], v[212:215], v[14:17]
	v_mfma_f32_16x16x32_bf16 v[14:17], v[114:117], v[208:211], v[14:17]
	v_mfma_f32_16x16x32_bf16 v[10:13], v[130:133], v[208:211], v[10:13]
	v_mfma_f32_16x16x32_bf16 v[10:13], v[142:145], v[212:215], v[10:13]
	v_mfma_f32_16x16x32_bf16 v[26:29], v[142:145], v[204:207], v[26:29]
	v_mfma_f32_16x16x32_bf16 v[26:29], v[130:133], v[200:203], v[26:29]
	v_mfma_f32_16x16x32_bf16 v[42:45], v[130:133], v[192:195], v[42:45]
	v_mfma_f32_16x16x32_bf16 v[42:45], v[142:145], v[196:199], v[42:45]
	v_mfma_f32_16x16x32_bf16 v[58:61], v[142:145], v[188:191], v[58:61]
	v_mfma_f32_16x16x32_bf16 v[58:61], v[130:133], v[184:187], v[58:61]
	v_mfma_f32_16x16x32_bf16 v[54:57], v[146:149], v[184:187], v[54:57]
	v_mfma_f32_16x16x32_bf16 v[54:57], v[150:153], v[188:191], v[54:57]
	v_mfma_f32_16x16x32_bf16 v[38:41], v[150:153], v[196:199], v[38:41]
	v_mfma_f32_16x16x32_bf16 v[38:41], v[146:149], v[192:195], v[38:41]
	v_mfma_f32_16x16x32_bf16 v[22:25], v[146:149], v[200:203], v[22:25]
	v_mfma_f32_16x16x32_bf16 v[22:25], v[150:153], v[204:207], v[22:25]
	v_mfma_f32_16x16x32_bf16 v[6:9], v[150:153], v[212:215], v[6:9]
	v_mfma_f32_16x16x32_bf16 v[6:9], v[146:149], v[208:211], v[6:9]
	v_mfma_f32_16x16x32_bf16 v[2:5], v[174:177], v[208:211], v[2:5]
	v_mfma_f32_16x16x32_bf16 v[2:5], v[178:181], v[212:215], v[2:5]
	v_mfma_f32_16x16x32_bf16 v[18:21], v[178:181], v[204:207], v[18:21]
	v_mfma_f32_16x16x32_bf16 v[18:21], v[174:177], v[200:203], v[18:21]
	s_barrier
	s_setprio 2
	v_mfma_f32_16x16x32_bf16 v[34:37], v[174:177], v[192:195], v[34:37]
	v_mfma_f32_16x16x32_bf16 v[34:37], v[178:181], v[196:199], v[34:37]
	v_mfma_f32_16x16x32_bf16 v[50:53], v[178:181], v[188:191], v[50:53]
	v_mfma_f32_16x16x32_bf16 v[50:53], v[174:177], v[184:187], v[50:53]
	s_setprio 0
	s_add_u32 s92, s92, 0x1000
	s_addc_u32 s93, s93, 0
	s_add_u32 s11, s11, 0x1000
	s_addc_u32 s37, s37, 0
	s_cmp_ge_i32 s65, s80
	s_mov_b32 s39, s65
	s_cbranch_scc0 .LBB0_487
	s_and_b64 vcc, exec, s[34:35]
	s_cbranch_vccnz .LBB0_492
	s_lshl_b32 s11, s2, 8
	s_cmp_gt_i32 s2, 63
	s_mov_b64 s[68:69], -1
	s_cbranch_scc1 .LBB0_493

; #define PG8_STAGE(bufoff, gbase, voff) do { if constexpr (!pg8_noload<Epi>::value) { _Pragma("unroll") for (int _i = 0; _i < 2; ++_i) \
;         __builtin_amdgcn_global_load_lds((const unsigned*)((const char*)(gbase) + (size_t)_i * pstep + (voff)[0]), (PG8_LAS unsigned*)(lds + (bufoff) + ldsw + _i * 8192), 16, 0, 0); } } while (0)
; #define PG8_LDA(dst, b, h) do { _Pragma("unroll") for (int m = 0; m < 4; ++m) _Pragma("unroll") for (int k = 0; k < 2; ++k) dst[m][k] = *(const PG8_LAS bf16x8*)(lds + PG8_SA(b, h) + aoff + m * 2048 + k * 1024); } while (0)
; #define PG8_LDB(dst, b, h) do { _Pragma("unroll") for (int n = 0; n < 2; ++n) _Pragma("unroll") for (int k = 0; k < 2; ++k) dst[n][k] = *(const PG8_LAS bf16x8*)(lds + PG8_SB(b, h) + boff + n * 2048 + k * 1024); } while (0)
; #define PG8_MMA(ai, bj, At, Bt) do { __builtin_amdgcn_s_setprio(1); _Pragma("unroll") for (int m = 0; m < 4; ++m) _Pragma("unroll") for (int n = 0; n < 2; ++n) _Pragma("unroll") for (int k = 0; k < 2; ++k) \
;         acc[ai][bj][m][n] = __builtin_amdgcn_mfma_f32_16x16x32_bf16(Bt[n][k], At[m][k], acc[ai][bj][m][n], 0, 0, 0); __builtin_amdgcn_s_setprio(0); } while (0)
; #define PG8_BAR __builtin_amdgcn_s_barrier()
; template <class Epi, class Sched, bool ALIGN_EPI = false, bool SP2 = false, bool ABLK = false>
; __device__ __forceinline__ void gemm_phase(PG8_LAS unsigned char* lds, const Gemm g, const Sched& S, const Epi& E) {
;     ...
;         for (int t = 0; t < nt; t += 2) {
;             const bool last = (t == nt - 2);
;             const char* a1 = cA + (size_t)(t + 1) * kstep;
;             const char* a2 = last ? nA : cA + (size_t)(t + 2) * kstep; const char* b2 = last ? nB : cB + (size_t)(t + 2) * kstepB;
;             const char* a3 = a2 + kstep; const char* b3 = b2 + kstepB;
;             if (last && has_next) S.a_ready(nxt);
;             if constexpr (SP2) {
;             PG8_LDB(B0, 0, 0); PG8_LDB(B1, 0, 1); PG8_SCHED; PG8_LDA(At, 0, 0); PG8_STAGE(PG8_SA(1, 1), a1 + hstep, voffA);
;             PG8_WAIT_V(8); PG8_WAIT_L(0); PG8_BAR; PG8_MMA(0, 0, At, B0); PG8_MMA(0, 1, At, B1); PG8_BAR; PG8_SCHED;
;             PG8_LDA(At, 0, 1); PG8_STAGE(PG8_SB(0, 0), b2, voffB); PG8_STAGE(PG8_SB(0, 1), b2 + hstep, voffB); PG8_STAGE(PG8_SA(0, 0), a2, voffA);
;             PG8_WAIT_V(8); PG8_WAIT_L(0); PG8_BAR; PG8_MMA(1, 0, At, B0); PG8_MMA(1, 1, At, B1); PG8_BAR; PG8_SCHED;
.LBB0_619:
	s_or_b32 s28, s57, 1
	s_lshl_b64 s[58:59], s[28:29], 11
	s_add_u32 s58, s2, s58
	s_addc_u32 s59, s3, s59
	s_add_i32 s28, s57, 2
	v_add_u32_e32 v160, s78, v168
	v_add_u32_e32 v180, s79, v168
	s_lshl_b64 s[60:61], s[28:29], 11
	ds_read_b128 v[130:133], v160
	ds_read_b128 v[134:137], v160 offset:1024
	ds_read_b128 v[156:159], v160 offset:2048
	ds_read_b128 v[160:163], v160 offset:3072
	ds_read_b128 v[164:167], v180
	ds_read_b128 v[176:179], v180 offset:1024
	ds_read_b128 v[184:187], v180 offset:2048
	ds_read_b128 v[188:191], v180 offset:3072
	s_add_u32 s66, s2, s60
	s_addc_u32 s67, s3, s61
	s_and_b64 s[62:63], s[68:69], exec
	s_cselect_b32 s73, s67, s7
	s_cselect_b32 s72, s66, s15
	s_add_u32 s62, s16, s60
	s_addc_u32 s63, s17, s61
	s_and_b64 s[60:61], s[68:69], exec
	s_cselect_b32 s61, s63, s9
	s_cselect_b32 s60, s62, s56
	v_lshl_add_u64 v[180:181], s[58:59], 0, v[138:139]
	v_lshl_add_u64 v[224:225], v[180:181], 0, s[24:25]
	s_add_i32 m0, s70, 0xc000
	ds_read_b128 v[192:195], v173
	ds_read_b128 v[196:199], v173 offset:1024
	ds_read_b128 v[200:203], v173 offset:2048
	ds_read_b128 v[204:207], v173 offset:3072
	ds_read_b128 v[208:211], v173 offset:4096
	ds_read_b128 v[212:215], v173 offset:5120
	ds_read_b128 v[216:219], v173 offset:6144
	ds_read_b128 v[220:223], v173 offset:7168
	global_load_lds_dwordx4 v[224:225], off
	v_lshl_add_u64 v[180:181], v[180:181], 0, s[26:27]
	s_add_i32 m0, s70, 0xe000
	s_nop 0
	global_load_lds_dwordx4 v[180:181], off
	s_waitcnt vmcnt(8)
	s_waitcnt lgkmcnt(0)
	s_barrier
	s_setprio 1
	v_mfma_f32_16x16x32_bf16 v[126:129], v[130:133], v[192:195], v[126:129]
	v_mfma_f32_16x16x32_bf16 v[126:129], v[134:137], v[196:199], v[126:129]
	v_mfma_f32_16x16x32_bf16 v[110:113], v[134:137], v[204:207], v[110:113]
	v_mfma_f32_16x16x32_bf16 v[110:113], v[130:133], v[200:203], v[110:113]
	v_mfma_f32_16x16x32_bf16 v[94:97], v[130:133], v[208:211], v[94:97]
	v_mfma_f32_16x16x32_bf16 v[94:97], v[134:137], v[212:215], v[94:97]
	v_mfma_f32_16x16x32_bf16 v[78:81], v[134:137], v[220:223], v[78:81]
	v_mfma_f32_16x16x32_bf16 v[78:81], v[130:133], v[216:219], v[78:81]
	v_mfma_f32_16x16x32_bf16 v[74:77], v[156:159], v[216:219], v[74:77]
	v_mfma_f32_16x16x32_bf16 v[74:77], v[160:163], v[220:223], v[74:77]
	v_mfma_f32_16x16x32_bf16 v[90:93], v[160:163], v[212:215], v[90:93]
	v_mfma_f32_16x16x32_bf16 v[90:93], v[156:159], v[208:211], v[90:93]
	v_mfma_f32_16x16x32_bf16 v[106:109], v[156:159], v[200:203], v[106:109]
	v_mfma_f32_16x16x32_bf16 v[106:109], v[160:163], v[204:207], v[106:109]
	v_mfma_f32_16x16x32_bf16 v[122:125], v[160:163], v[196:199], v[122:125]
	v_mfma_f32_16x16x32_bf16 v[122:125], v[156:159], v[192:195], v[122:125]
	v_mfma_f32_16x16x32_bf16 v[118:121], v[164:167], v[192:195], v[118:121]
	v_mfma_f32_16x16x32_bf16 v[118:121], v[176:179], v[196:199], v[118:121]
	v_mfma_f32_16x16x32_bf16 v[102:105], v[176:179], v[204:207], v[102:105]
	v_mfma_f32_16x16x32_bf16 v[102:105], v[164:167], v[200:203], v[102:105]
	v_mfma_f32_16x16x32_bf16 v[86:89], v[164:167], v[208:211], v[86:89]
	v_mfma_f32_16x16x32_bf16 v[86:89], v[176:179], v[212:215], v[86:89]
	v_mfma_f32_16x16x32_bf16 v[70:73], v[176:179], v[220:223], v[70:73]
	v_mfma_f32_16x16x32_bf16 v[70:73], v[164:167], v[216:219], v[70:73]
	v_mfma_f32_16x16x32_bf16 v[66:69], v[184:187], v[216:219], v[66:69]
	v_mfma_f32_16x16x32_bf16 v[66:69], v[188:191], v[220:223], v[66:69]
	v_mfma_f32_16x16x32_bf16 v[82:85], v[188:191], v[212:215], v[82:85]
	v_mfma_f32_16x16x32_bf16 v[82:85], v[184:187], v[208:211], v[82:85]
	s_barrier
	s_setprio 2
	v_mfma_f32_16x16x32_bf16 v[98:101], v[184:187], v[200:203], v[98:101]
	v_mfma_f32_16x16x32_bf16 v[98:101], v[188:191], v[204:207], v[98:101]
	v_mfma_f32_16x16x32_bf16 v[114:117], v[188:191], v[196:199], v[114:117]
	v_mfma_f32_16x16x32_bf16 v[114:117], v[184:187], v[192:195], v[114:117]
	s_setprio 0
	s_add_i32 s58, s78, s91
	v_lshl_add_u64 v[180:181], s[60:61], 0, v[138:139]
	s_mov_b32 m0, s58
	ds_read_b128 v[192:195], v173 offset:16384
	ds_read_b128 v[196:199], v173 offset:17408
	ds_read_b128 v[200:203], v173 offset:18432
	ds_read_b128 v[204:207], v173 offset:19456
	ds_read_b128 v[208:211], v173 offset:20480
	ds_read_b128 v[212:215], v173 offset:21504
	ds_read_b128 v[216:219], v173 offset:22528
	ds_read_b128 v[220:223], v173 offset:23552
	global_load_lds_dwordx4 v[180:181], off
	v_lshl_add_u64 v[224:225], v[180:181], 0, s[22:23]
	s_add_i32 m0, s58, 0x2000
	s_add_i32 s58, s79, s91
	global_load_lds_dwordx4 v[224:225], off
	v_lshl_add_u64 v[224:225], v[180:181], 0, s[24:25]
	s_mov_b32 m0, s58
	s_nop 0
	global_load_lds_dwordx4 v[224:225], off
	v_lshl_add_u64 v[224:225], v[180:181], 0, s[26:27]
	s_add_i32 m0, s58, 0x2000
	s_nop 0
	global_load_lds_dwordx4 v[224:225], off
	v_lshl_add_u64 v[224:225], s[72:73], 0, v[138:139]
	s_mov_b32 m0, s70
	v_lshl_add_u64 v[226:227], v[224:225], 0, s[22:23]
	global_load_lds_dwordx4 v[224:225], off
	s_mov_b32 m0, s71
	s_nop 0
	global_load_lds_dwordx4 v[226:227], off
	s_waitcnt vmcnt(8)
	s_waitcnt lgkmcnt(0)
	s_barrier
; #define PG8_STAGE(bufoff, gbase, voff) do { if constexpr (!pg8_noload<Epi>::value) { _Pragma("unroll") for (int _i = 0; _i < 2; ++_i) \
;         __builtin_amdgcn_global_load_lds((const unsigned*)((const char*)(gbase) + (size_t)_i * pstep + (voff)[0]), (PG8_LAS unsigned*)(lds + (bufoff) + ldsw + _i * 8192), 16, 0, 0); } } while (0)
; #define PG8_LDA(dst, b, h) do { _Pragma("unroll") for (int m = 0; m < 4; ++m) _Pragma("unroll") for (int k = 0; k < 2; ++k) dst[m][k] = *(const PG8_LAS bf16x8*)(lds + PG8_SA(b, h) + aoff + m * 2048 + k * 1024); } while (0)
; #define PG8_LDB(dst, b, h) do { _Pragma("unroll") for (int n = 0; n < 2; ++n) _Pragma("unroll") for (int k = 0; k < 2; ++k) dst[n][k] = *(const PG8_LAS bf16x8*)(lds + PG8_SB(b, h) + boff + n * 2048 + k * 1024); } while (0)
; #define PG8_MMA(ai, bj, At, Bt) do { __builtin_amdgcn_s_setprio(1); _Pragma("unroll") for (int m = 0; m < 4; ++m) _Pragma("unroll") for (int n = 0; n < 2; ++n) _Pragma("unroll") for (int k = 0; k < 2; ++k) \
;         acc[ai][bj][m][n] = __builtin_amdgcn_mfma_f32_16x16x32_bf16(Bt[n][k], At[m][k], acc[ai][bj][m][n], 0, 0, 0); __builtin_amdgcn_s_setprio(0); } while (0)
; #define PG8_WAIT_V(n) asm volatile("s_waitcnt vmcnt(" #n ")" ::: "memory")
; #define PG8_WAIT_L(n) asm volatile("s_waitcnt lgkmcnt(" #n ")" ::: "memory")
; #define PG8_BAR __builtin_amdgcn_s_barrier()
; #define PG8_SCHED __builtin_amdgcn_sched_barrier(0)
; template <class Epi, class Sched, bool ALIGN_EPI = false, bool SP2 = false, bool ABLK = false>
; __device__ __forceinline__ void gemm_phase(PG8_LAS unsigned char* lds, const Gemm g, const Sched& S, const Epi& E) {
;     ...
;             PG8_WAIT_V(8); PG8_WAIT_L(0); PG8_BAR; PG8_MMA(1, 0, At, B0); PG8_MMA(1, 1, At, B1); PG8_BAR; PG8_SCHED;
;             PG8_LDB(B0, 1, 0); PG8_LDB(B1, 1, 1); PG8_SCHED; PG8_LDA(At, 1, 0); PG8_STAGE(PG8_SA(0, 1), a2 + hstep, voffA);
;             PG8_WAIT_V(8); PG8_WAIT_L(0); PG8_BAR; PG8_MMA(0, 0, At, B0); PG8_MMA(0, 1, At, B1); PG8_BAR; PG8_SCHED;
	s_setprio 1
	v_mfma_f32_16x16x32_bf16 v[62:65], v[130:133], v[192:195], v[62:65]
	v_mfma_f32_16x16x32_bf16 v[62:65], v[134:137], v[196:199], v[62:65]
	v_mfma_f32_16x16x32_bf16 v[46:49], v[134:137], v[204:207], v[46:49]
	v_mfma_f32_16x16x32_bf16 v[46:49], v[130:133], v[200:203], v[46:49]
	v_mfma_f32_16x16x32_bf16 v[30:33], v[130:133], v[208:211], v[30:33]
	v_mfma_f32_16x16x32_bf16 v[30:33], v[134:137], v[212:215], v[30:33]
	v_mfma_f32_16x16x32_bf16 v[14:17], v[134:137], v[220:223], v[14:17]
	v_mfma_f32_16x16x32_bf16 v[14:17], v[130:133], v[216:219], v[14:17]
	v_mfma_f32_16x16x32_bf16 v[10:13], v[156:159], v[216:219], v[10:13]
	v_mfma_f32_16x16x32_bf16 v[10:13], v[160:163], v[220:223], v[10:13]
	v_mfma_f32_16x16x32_bf16 v[26:29], v[160:163], v[212:215], v[26:29]
	v_mfma_f32_16x16x32_bf16 v[26:29], v[156:159], v[208:211], v[26:29]
	v_mfma_f32_16x16x32_bf16 v[42:45], v[156:159], v[200:203], v[42:45]
	v_mfma_f32_16x16x32_bf16 v[42:45], v[160:163], v[204:207], v[42:45]
	v_mfma_f32_16x16x32_bf16 v[58:61], v[160:163], v[196:199], v[58:61]
	v_mfma_f32_16x16x32_bf16 v[58:61], v[156:159], v[192:195], v[58:61]
	v_mfma_f32_16x16x32_bf16 v[54:57], v[164:167], v[192:195], v[54:57]
	v_mfma_f32_16x16x32_bf16 v[54:57], v[176:179], v[196:199], v[54:57]
	v_mfma_f32_16x16x32_bf16 v[38:41], v[176:179], v[204:207], v[38:41]
	v_mfma_f32_16x16x32_bf16 v[38:41], v[164:167], v[200:203], v[38:41]
	v_mfma_f32_16x16x32_bf16 v[22:25], v[164:167], v[208:211], v[22:25]
	v_mfma_f32_16x16x32_bf16 v[22:25], v[176:179], v[212:215], v[22:25]
	v_mfma_f32_16x16x32_bf16 v[6:9], v[176:179], v[220:223], v[6:9]
	v_mfma_f32_16x16x32_bf16 v[6:9], v[164:167], v[216:219], v[6:9]
	v_mfma_f32_16x16x32_bf16 v[2:5], v[184:187], v[216:219], v[2:5]
	v_mfma_f32_16x16x32_bf16 v[2:5], v[188:191], v[220:223], v[2:5]
	v_mfma_f32_16x16x32_bf16 v[18:21], v[188:191], v[212:215], v[18:21]
	v_mfma_f32_16x16x32_bf16 v[18:21], v[184:187], v[208:211], v[18:21]
	s_barrier
	s_setprio 2
	v_mfma_f32_16x16x32_bf16 v[34:37], v[184:187], v[200:203], v[34:37]
	v_mfma_f32_16x16x32_bf16 v[34:37], v[188:191], v[204:207], v[34:37]
	v_mfma_f32_16x16x32_bf16 v[50:53], v[188:191], v[196:199], v[50:53]
	v_mfma_f32_16x16x32_bf16 v[50:53], v[184:187], v[192:195], v[50:53]
	s_setprio 0
	s_add_i32 s58, 0, 0x18000
	s_add_i32 s59, 0, 0x1c000
	v_add_u32_e32 v160, s58, v168
	v_add_u32_e32 v188, s59, v168
	ds_read_b128 v[130:133], v160
	ds_read_b128 v[134:137], v160 offset:1024
	ds_read_b128 v[156:159], v160 offset:2048
	ds_read_b128 v[160:163], v160 offset:3072
	ds_read_b128 v[164:167], v188
	ds_read_b128 v[176:179], v188 offset:1024
	ds_read_b128 v[184:187], v188 offset:2048
	ds_read_b128 v[188:191], v188 offset:3072
	s_mov_b32 m0, s34
	v_lshl_add_u64 v[226:227], v[224:225], 0, s[24:25]
	ds_read_b128 v[192:195], v173 offset:32768
	ds_read_b128 v[196:199], v173 offset:33792
	ds_read_b128 v[200:203], v173 offset:34816
	ds_read_b128 v[204:207], v173 offset:35840
	ds_read_b128 v[208:211], v173 offset:36864
	ds_read_b128 v[212:215], v173 offset:37888
	ds_read_b128 v[216:219], v173 offset:38912
	ds_read_b128 v[220:223], v173 offset:39936
	global_load_lds_dwordx4 v[226:227], off
	v_lshl_add_u64 v[226:227], v[224:225], 0, s[26:27]
	s_mov_b32 m0, s35
	s_nop 0
	global_load_lds_dwordx4 v[226:227], off
	s_waitcnt vmcnt(8)
	s_waitcnt lgkmcnt(0)
	s_barrier
	s_setprio 1
	v_mfma_f32_16x16x32_bf16 v[126:129], v[130:133], v[192:195], v[126:129]
	v_mfma_f32_16x16x32_bf16 v[126:129], v[134:137], v[196:199], v[126:129]
	v_mfma_f32_16x16x32_bf16 v[110:113], v[134:137], v[204:207], v[110:113]
	v_mfma_f32_16x16x32_bf16 v[110:113], v[130:133], v[200:203], v[110:113]
	v_mfma_f32_16x16x32_bf16 v[94:97], v[130:133], v[208:211], v[94:97]
	v_mfma_f32_16x16x32_bf16 v[94:97], v[134:137], v[212:215], v[94:97]
	v_mfma_f32_16x16x32_bf16 v[78:81], v[134:137], v[220:223], v[78:81]
	v_mfma_f32_16x16x32_bf16 v[78:81], v[130:133], v[216:219], v[78:81]
	v_mfma_f32_16x16x32_bf16 v[74:77], v[156:159], v[216:219], v[74:77]
	v_mfma_f32_16x16x32_bf16 v[74:77], v[160:163], v[220:223], v[74:77]
	v_mfma_f32_16x16x32_bf16 v[90:93], v[160:163], v[212:215], v[90:93]
	v_mfma_f32_16x16x32_bf16 v[90:93], v[156:159], v[208:211], v[90:93]
	v_mfma_f32_16x16x32_bf16 v[106:109], v[156:159], v[200:203], v[106:109]
	v_mfma_f32_16x16x32_bf16 v[106:109], v[160:163], v[204:207], v[106:109]
	v_mfma_f32_16x16x32_bf16 v[122:125], v[160:163], v[196:199], v[122:125]
	v_mfma_f32_16x16x32_bf16 v[122:125], v[156:159], v[192:195], v[122:125]
	v_mfma_f32_16x16x32_bf16 v[118:121], v[164:167], v[192:195], v[118:121]
	v_mfma_f32_16x16x32_bf16 v[118:121], v[176:179], v[196:199], v[118:121]
	v_mfma_f32_16x16x32_bf16 v[102:105], v[176:179], v[204:207], v[102:105]
	v_mfma_f32_16x16x32_bf16 v[102:105], v[164:167], v[200:203], v[102:105]
	v_mfma_f32_16x16x32_bf16 v[86:89], v[164:167], v[208:211], v[86:89]
	v_mfma_f32_16x16x32_bf16 v[86:89], v[176:179], v[212:215], v[86:89]
	v_mfma_f32_16x16x32_bf16 v[70:73], v[176:179], v[220:223], v[70:73]
	v_mfma_f32_16x16x32_bf16 v[70:73], v[164:167], v[216:219], v[70:73]
	v_mfma_f32_16x16x32_bf16 v[66:69], v[184:187], v[216:219], v[66:69]
	v_mfma_f32_16x16x32_bf16 v[66:69], v[188:191], v[220:223], v[66:69]
	v_mfma_f32_16x16x32_bf16 v[82:85], v[188:191], v[212:215], v[82:85]
	v_mfma_f32_16x16x32_bf16 v[82:85], v[184:187], v[208:211], v[82:85]
	s_barrier
; #define PG8_STAGE(bufoff, gbase, voff) do { if constexpr (!pg8_noload<Epi>::value) { _Pragma("unroll") for (int _i = 0; _i < 2; ++_i) \
;         __builtin_amdgcn_global_load_lds((const unsigned*)((const char*)(gbase) + (size_t)_i * pstep + (voff)[0]), (PG8_LAS unsigned*)(lds + (bufoff) + ldsw + _i * 8192), 16, 0, 0); } } while (0)
; #define PG8_LDA(dst, b, h) do { _Pragma("unroll") for (int m = 0; m < 4; ++m) _Pragma("unroll") for (int k = 0; k < 2; ++k) dst[m][k] = *(const PG8_LAS bf16x8*)(lds + PG8_SA(b, h) + aoff + m * 2048 + k * 1024); } while (0)
; #define PG8_MMA(ai, bj, At, Bt) do { __builtin_amdgcn_s_setprio(1); _Pragma("unroll") for (int m = 0; m < 4; ++m) _Pragma("unroll") for (int n = 0; n < 2; ++n) _Pragma("unroll") for (int k = 0; k < 2; ++k) \
;         acc[ai][bj][m][n] = __builtin_amdgcn_mfma_f32_16x16x32_bf16(Bt[n][k], At[m][k], acc[ai][bj][m][n], 0, 0, 0); __builtin_amdgcn_s_setprio(0); } while (0)
; #define PG8_WAIT_V(n) asm volatile("s_waitcnt vmcnt(" #n ")" ::: "memory")
; #define PG8_WAIT_L(n) asm volatile("s_waitcnt lgkmcnt(" #n ")" ::: "memory")
; #define PG8_BAR __builtin_amdgcn_s_barrier()
; #define PG8_SCHED __builtin_amdgcn_sched_barrier(0)
; template <class Epi, class Sched, bool ALIGN_EPI = false, bool SP2 = false, bool ABLK = false>
; __device__ __forceinline__ void gemm_phase(PG8_LAS unsigned char* lds, const Gemm g, const Sched& S, const Epi& E) {
;     ...
;         for (int t = 0; t < nt; t += 2) {
;             const bool last = (t == nt - 2);
;     ...
;             PG8_WAIT_V(8); PG8_WAIT_L(0); PG8_BAR; PG8_MMA(0, 0, At, B0); PG8_MMA(0, 1, At, B1); PG8_BAR; PG8_SCHED;
;             PG8_LDA(At, 1, 1); PG8_STAGE(PG8_SB(1, 0), b3, voffB); PG8_STAGE(PG8_SB(1, 1), b3 + hstep, voffB); PG8_STAGE(PG8_SA(1, 0), a3, voffA);
;             PG8_WAIT_V(8); PG8_WAIT_L(0); PG8_BAR; PG8_MMA(1, 0, At, B0); PG8_MMA(1, 1, At, B1); PG8_BAR; PG8_SCHED;
	s_setprio 2
	v_mfma_f32_16x16x32_bf16 v[98:101], v[184:187], v[200:203], v[98:101]
	v_mfma_f32_16x16x32_bf16 v[98:101], v[188:191], v[204:207], v[98:101]
	v_mfma_f32_16x16x32_bf16 v[114:117], v[188:191], v[196:199], v[114:117]
	v_mfma_f32_16x16x32_bf16 v[114:117], v[184:187], v[192:195], v[114:117]
	s_setprio 0
	s_add_i32 s58, s58, s91
	v_lshl_add_u64 v[226:227], v[180:181], 0, s[92:93]
	s_mov_b32 m0, s58
	ds_read_b128 v[192:195], v173 offset:49152
	ds_read_b128 v[196:199], v173 offset:50176
	ds_read_b128 v[200:203], v173 offset:51200
	ds_read_b128 v[204:207], v173 offset:52224
	ds_read_b128 v[208:211], v173 offset:53248
	ds_read_b128 v[212:215], v173 offset:54272
	ds_read_b128 v[216:219], v173 offset:55296
	ds_read_b128 v[220:223], v173 offset:56320
	global_load_lds_dwordx4 v[226:227], off
	v_lshl_add_u64 v[226:227], v[180:181], 0, s[94:95]
	s_add_i32 m0, s58, 0x2000
	s_add_i32 s58, s59, s91
	global_load_lds_dwordx4 v[226:227], off
	v_lshl_add_u64 v[226:227], v[180:181], 0, s[96:97]
	s_mov_b32 m0, s58
	v_lshl_add_u64 v[180:181], v[180:181], 0, s[88:89]
	global_load_lds_dwordx4 v[226:227], off
	s_add_i32 m0, s58, 0x2000
	s_nop 0
	global_load_lds_dwordx4 v[180:181], off
	v_lshl_add_u64 v[180:181], v[224:225], 0, s[92:93]
	s_mov_b32 m0, s10
	s_nop 0
	global_load_lds_dwordx4 v[180:181], off
	v_lshl_add_u64 v[180:181], v[224:225], 0, s[94:95]
	s_mov_b32 m0, s11
	s_nop 0
	global_load_lds_dwordx4 v[180:181], off
	s_waitcnt vmcnt(8)
	s_waitcnt lgkmcnt(0)
	s_barrier
	s_setprio 1
	v_mfma_f32_16x16x32_bf16 v[62:65], v[130:133], v[192:195], v[62:65]
	v_mfma_f32_16x16x32_bf16 v[62:65], v[134:137], v[196:199], v[62:65]
	v_mfma_f32_16x16x32_bf16 v[46:49], v[134:137], v[204:207], v[46:49]
	v_mfma_f32_16x16x32_bf16 v[46:49], v[130:133], v[200:203], v[46:49]
	v_mfma_f32_16x16x32_bf16 v[30:33], v[130:133], v[208:211], v[30:33]
	v_mfma_f32_16x16x32_bf16 v[30:33], v[134:137], v[212:215], v[30:33]
	v_mfma_f32_16x16x32_bf16 v[14:17], v[134:137], v[220:223], v[14:17]
	v_mfma_f32_16x16x32_bf16 v[14:17], v[130:133], v[216:219], v[14:17]
	v_mfma_f32_16x16x32_bf16 v[10:13], v[156:159], v[216:219], v[10:13]
	v_mfma_f32_16x16x32_bf16 v[10:13], v[160:163], v[220:223], v[10:13]
	v_mfma_f32_16x16x32_bf16 v[26:29], v[160:163], v[212:215], v[26:29]
	v_mfma_f32_16x16x32_bf16 v[26:29], v[156:159], v[208:211], v[26:29]
	v_mfma_f32_16x16x32_bf16 v[42:45], v[156:159], v[200:203], v[42:45]
	v_mfma_f32_16x16x32_bf16 v[42:45], v[160:163], v[204:207], v[42:45]
	v_mfma_f32_16x16x32_bf16 v[58:61], v[160:163], v[196:199], v[58:61]
	v_mfma_f32_16x16x32_bf16 v[58:61], v[156:159], v[192:195], v[58:61]
	v_mfma_f32_16x16x32_bf16 v[54:57], v[164:167], v[192:195], v[54:57]
	v_mfma_f32_16x16x32_bf16 v[54:57], v[176:179], v[196:199], v[54:57]
	v_mfma_f32_16x16x32_bf16 v[38:41], v[176:179], v[204:207], v[38:41]
	v_mfma_f32_16x16x32_bf16 v[38:41], v[164:167], v[200:203], v[38:41]
	v_mfma_f32_16x16x32_bf16 v[22:25], v[164:167], v[208:211], v[22:25]
	v_mfma_f32_16x16x32_bf16 v[22:25], v[176:179], v[212:215], v[22:25]
	v_mfma_f32_16x16x32_bf16 v[6:9], v[176:179], v[220:223], v[6:9]
	v_mfma_f32_16x16x32_bf16 v[6:9], v[164:167], v[216:219], v[6:9]
	v_mfma_f32_16x16x32_bf16 v[2:5], v[184:187], v[216:219], v[2:5]
	v_mfma_f32_16x16x32_bf16 v[2:5], v[188:191], v[220:223], v[2:5]
	v_mfma_f32_16x16x32_bf16 v[18:21], v[188:191], v[212:215], v[18:21]
	v_mfma_f32_16x16x32_bf16 v[18:21], v[184:187], v[208:211], v[18:21]
	s_barrier
	s_setprio 2
	v_mfma_f32_16x16x32_bf16 v[34:37], v[184:187], v[200:203], v[34:37]
	v_mfma_f32_16x16x32_bf16 v[34:37], v[188:191], v[204:207], v[34:37]
	v_mfma_f32_16x16x32_bf16 v[50:53], v[188:191], v[196:199], v[50:53]
	v_mfma_f32_16x16x32_bf16 v[50:53], v[184:187], v[192:195], v[50:53]
	s_setprio 0
	s_cmp_gt_u32 s57, 29
	s_mov_b32 s57, s28
	s_cbranch_scc1 .LBB0_631

; #define PG8_STAGE(bufoff, gbase, voff) do { if constexpr (!pg8_noload<Epi>::value) { _Pragma("unroll") for (int _i = 0; _i < 2; ++_i) \
;         __builtin_amdgcn_global_load_lds((const unsigned*)((const char*)(gbase) + (size_t)_i * pstep + (voff)[0]), (PG8_LAS unsigned*)(lds + (bufoff) + ldsw + _i * 8192), 16, 0, 0); } } while (0)
; #define PG8_LDA(dst, b, h) do { _Pragma("unroll") for (int m = 0; m < 4; ++m) _Pragma("unroll") for (int k = 0; k < 2; ++k) dst[m][k] = *(const PG8_LAS bf16x8*)(lds + PG8_SA(b, h) + aoff + m * 2048 + k * 1024); } while (0)
; #define PG8_LDB(dst, b, h) do { _Pragma("unroll") for (int n = 0; n < 2; ++n) _Pragma("unroll") for (int k = 0; k < 2; ++k) dst[n][k] = *(const PG8_LAS bf16x8*)(lds + PG8_SB(b, h) + boff + n * 2048 + k * 1024); } while (0)
; #define PG8_MMA(ai, bj, At, Bt) do { __builtin_amdgcn_s_setprio(1); _Pragma("unroll") for (int m = 0; m < 4; ++m) _Pragma("unroll") for (int n = 0; n < 2; ++n) _Pragma("unroll") for (int k = 0; k < 2; ++k) \
;         acc[ai][bj][m][n] = __builtin_amdgcn_mfma_f32_16x16x32_bf16(Bt[n][k], At[m][k], acc[ai][bj][m][n], 0, 0, 0); __builtin_amdgcn_s_setprio(0); } while (0)
; #define PG8_BAR __builtin_amdgcn_s_barrier()
; template <class Epi, class Sched, bool ALIGN_EPI = false, bool SP2 = false, bool ABLK = false>
; __device__ __forceinline__ void gemm_phase(PG8_LAS unsigned char* lds, const Gemm g, const Sched& S, const Epi& E) {
;     ...
;         for (int t = 0; t < nt; t += 2) {
;             const bool last = (t == nt - 2);
;             const char* a1 = cA + (size_t)(t + 1) * kstep;
;             const char* a2 = last ? nA : cA + (size_t)(t + 2) * kstep; const char* b2 = last ? nB : cB + (size_t)(t + 2) * kstepB;
;             const char* a3 = a2 + kstep; const char* b3 = b2 + kstepB;
;             if (last && has_next) S.a_ready(nxt);
;             if constexpr (SP2) {
;             PG8_LDB(B0, 0, 0); PG8_LDB(B1, 0, 1); PG8_SCHED; PG8_LDA(At, 0, 0); PG8_STAGE(PG8_SA(1, 1), a1 + hstep, voffA);
;             PG8_WAIT_V(8); PG8_WAIT_L(0); PG8_BAR; PG8_MMA(0, 0, At, B0); PG8_MMA(0, 1, At, B1); PG8_BAR; PG8_SCHED;
;             PG8_LDA(At, 0, 1); PG8_STAGE(PG8_SB(0, 0), b2, voffB); PG8_STAGE(PG8_SB(0, 1), b2 + hstep, voffB); PG8_STAGE(PG8_SA(0, 0), a2, voffA);
;             PG8_WAIT_V(8); PG8_WAIT_L(0); PG8_BAR; PG8_MMA(1, 0, At, B0); PG8_MMA(1, 1, At, B1); PG8_BAR; PG8_SCHED;
.LBB0_1533:
	ds_read_b128 v[114:117], v167
	ds_read_b128 v[126:129], v167 offset:1024
	ds_read_b128 v[130:133], v167 offset:2048
	ds_read_b128 v[142:145], v167 offset:3072
	ds_read_b128 v[146:149], v168
	ds_read_b128 v[150:153], v168 offset:1024
	ds_read_b128 v[174:177], v168 offset:2048
	ds_read_b128 v[178:181], v168 offset:3072
	s_add_i32 s41, s39, 2
	s_add_u32 s70, s68, 0xfff00800
	s_addc_u32 s71, s69, -1
	s_cmp_eq_u32 s3, s39
	s_cselect_b32 s71, s43, s71
	s_cselect_b32 s70, s42, s70
	s_cselect_b32 s81, s65, s37
	s_cselect_b32 s80, s64, s11
	v_lshl_add_u64 v[162:163], s[68:69], 0, v[158:159]
	s_add_i32 m0, s56, 0xc000
	ds_read_b128 v[184:187], v169
	ds_read_b128 v[188:191], v169 offset:1024
	ds_read_b128 v[192:195], v169 offset:2048
	ds_read_b128 v[196:199], v169 offset:3072
	ds_read_b128 v[200:203], v169 offset:4096
	ds_read_b128 v[204:207], v169 offset:5120
	ds_read_b128 v[208:211], v169 offset:6144
	ds_read_b128 v[212:215], v169 offset:7168
	global_load_lds_dwordx4 v[162:163], off
	v_lshl_add_u64 v[162:163], v[162:163], 0, s[12:13]
	s_add_i32 m0, s56, 0xe000
	s_nop 0
	global_load_lds_dwordx4 v[162:163], off
	s_waitcnt vmcnt(8)
	s_waitcnt lgkmcnt(0)
	s_barrier
	s_setprio 1
	v_mfma_f32_16x16x32_bf16 v[138:141], v[114:117], v[184:187], v[138:141]
	v_mfma_f32_16x16x32_bf16 v[138:141], v[126:129], v[188:191], v[138:141]
	v_mfma_f32_16x16x32_bf16 v[110:113], v[126:129], v[196:199], v[110:113]
	v_mfma_f32_16x16x32_bf16 v[110:113], v[114:117], v[192:195], v[110:113]
	v_mfma_f32_16x16x32_bf16 v[94:97], v[114:117], v[200:203], v[94:97]
	v_mfma_f32_16x16x32_bf16 v[94:97], v[126:129], v[204:207], v[94:97]
	v_mfma_f32_16x16x32_bf16 v[78:81], v[126:129], v[212:215], v[78:81]
	v_mfma_f32_16x16x32_bf16 v[78:81], v[114:117], v[208:211], v[78:81]
	v_mfma_f32_16x16x32_bf16 v[74:77], v[130:133], v[208:211], v[74:77]
	v_mfma_f32_16x16x32_bf16 v[74:77], v[142:145], v[212:215], v[74:77]
	v_mfma_f32_16x16x32_bf16 v[90:93], v[142:145], v[204:207], v[90:93]
	v_mfma_f32_16x16x32_bf16 v[90:93], v[130:133], v[200:203], v[90:93]
	v_mfma_f32_16x16x32_bf16 v[106:109], v[130:133], v[192:195], v[106:109]
	v_mfma_f32_16x16x32_bf16 v[106:109], v[142:145], v[196:199], v[106:109]
	v_mfma_f32_16x16x32_bf16 v[134:137], v[142:145], v[188:191], v[134:137]
	v_mfma_f32_16x16x32_bf16 v[134:137], v[130:133], v[184:187], v[134:137]
	v_mfma_f32_16x16x32_bf16 v[122:125], v[146:149], v[184:187], v[122:125]
	v_mfma_f32_16x16x32_bf16 v[122:125], v[150:153], v[188:191], v[122:125]
	v_mfma_f32_16x16x32_bf16 v[102:105], v[150:153], v[196:199], v[102:105]
	v_mfma_f32_16x16x32_bf16 v[102:105], v[146:149], v[192:195], v[102:105]
	v_mfma_f32_16x16x32_bf16 v[86:89], v[146:149], v[200:203], v[86:89]
	v_mfma_f32_16x16x32_bf16 v[86:89], v[150:153], v[204:207], v[86:89]
	v_mfma_f32_16x16x32_bf16 v[70:73], v[150:153], v[212:215], v[70:73]
	v_mfma_f32_16x16x32_bf16 v[70:73], v[146:149], v[208:211], v[70:73]
	v_mfma_f32_16x16x32_bf16 v[66:69], v[174:177], v[208:211], v[66:69]
	v_mfma_f32_16x16x32_bf16 v[66:69], v[178:181], v[212:215], v[66:69]
	v_mfma_f32_16x16x32_bf16 v[82:85], v[178:181], v[204:207], v[82:85]
	v_mfma_f32_16x16x32_bf16 v[82:85], v[174:177], v[200:203], v[82:85]
	s_barrier
	s_setprio 2
	v_mfma_f32_16x16x32_bf16 v[98:101], v[174:177], v[192:195], v[98:101]
	v_mfma_f32_16x16x32_bf16 v[98:101], v[178:181], v[196:199], v[98:101]
	v_mfma_f32_16x16x32_bf16 v[118:121], v[178:181], v[188:191], v[118:121]
	v_mfma_f32_16x16x32_bf16 v[118:121], v[174:177], v[184:187], v[118:121]
	s_setprio 0
	s_add_i32 s39, s74, s55
	v_lshl_add_u64 v[162:163], s[80:81], 0, v[154:155]
	s_mov_b32 m0, s39
	ds_read_b128 v[184:187], v169 offset:16384
	ds_read_b128 v[188:191], v169 offset:17408
	ds_read_b128 v[192:195], v169 offset:18432
	ds_read_b128 v[196:199], v169 offset:19456
	ds_read_b128 v[200:203], v169 offset:20480
	ds_read_b128 v[204:207], v169 offset:21504
	ds_read_b128 v[208:211], v169 offset:22528
	ds_read_b128 v[212:215], v169 offset:23552
	global_load_lds_dwordx4 v[162:163], off
	v_lshl_add_u64 v[216:217], v[162:163], 0, s[12:13]
	s_add_i32 m0, s39, 0x2000
	s_add_i32 s39, s75, s55
	global_load_lds_dwordx4 v[216:217], off
	v_lshl_add_u64 v[216:217], v[162:163], 0, s[14:15]
	s_mov_b32 m0, s39
	s_nop 0
	global_load_lds_dwordx4 v[216:217], off
	v_lshl_add_u64 v[216:217], v[162:163], 0, s[16:17]
	s_add_i32 m0, s39, 0x2000
	s_nop 0
	global_load_lds_dwordx4 v[216:217], off
	v_lshl_add_u64 v[216:217], s[70:71], 0, v[154:155]
	s_mov_b32 m0, s56
	v_lshl_add_u64 v[218:219], v[216:217], 0, s[12:13]
	global_load_lds_dwordx4 v[216:217], off
	s_mov_b32 m0, s57
	s_nop 0
	global_load_lds_dwordx4 v[218:219], off
	s_waitcnt vmcnt(8)
	s_waitcnt lgkmcnt(0)
	s_barrier
; #define PG8_STAGE(bufoff, gbase, voff) do { if constexpr (!pg8_noload<Epi>::value) { _Pragma("unroll") for (int _i = 0; _i < 2; ++_i) \
;         __builtin_amdgcn_global_load_lds((const unsigned*)((const char*)(gbase) + (size_t)_i * pstep + (voff)[0]), (PG8_LAS unsigned*)(lds + (bufoff) + ldsw + _i * 8192), 16, 0, 0); } } while (0)
; #define PG8_LDA(dst, b, h) do { _Pragma("unroll") for (int m = 0; m < 4; ++m) _Pragma("unroll") for (int k = 0; k < 2; ++k) dst[m][k] = *(const PG8_LAS bf16x8*)(lds + PG8_SA(b, h) + aoff + m * 2048 + k * 1024); } while (0)
; #define PG8_LDB(dst, b, h) do { _Pragma("unroll") for (int n = 0; n < 2; ++n) _Pragma("unroll") for (int k = 0; k < 2; ++k) dst[n][k] = *(const PG8_LAS bf16x8*)(lds + PG8_SB(b, h) + boff + n * 2048 + k * 1024); } while (0)
; #define PG8_MMA(ai, bj, At, Bt) do { __builtin_amdgcn_s_setprio(1); _Pragma("unroll") for (int m = 0; m < 4; ++m) _Pragma("unroll") for (int n = 0; n < 2; ++n) _Pragma("unroll") for (int k = 0; k < 2; ++k) \
;         acc[ai][bj][m][n] = __builtin_amdgcn_mfma_f32_16x16x32_bf16(Bt[n][k], At[m][k], acc[ai][bj][m][n], 0, 0, 0); __builtin_amdgcn_s_setprio(0); } while (0)
; #define PG8_WAIT_V(n) asm volatile("s_waitcnt vmcnt(" #n ")" ::: "memory")
; #define PG8_WAIT_L(n) asm volatile("s_waitcnt lgkmcnt(" #n ")" ::: "memory")
; #define PG8_BAR __builtin_amdgcn_s_barrier()
; #define PG8_SCHED __builtin_amdgcn_sched_barrier(0)
; template <class Epi, class Sched, bool ALIGN_EPI = false, bool SP2 = false, bool ABLK = false>
; __device__ __forceinline__ void gemm_phase(PG8_LAS unsigned char* lds, const Gemm g, const Sched& S, const Epi& E) {
;     ...
;             PG8_WAIT_V(8); PG8_WAIT_L(0); PG8_BAR; PG8_MMA(1, 0, At, B0); PG8_MMA(1, 1, At, B1); PG8_BAR; PG8_SCHED;
;             PG8_LDB(B0, 1, 0); PG8_LDB(B1, 1, 1); PG8_SCHED; PG8_LDA(At, 1, 0); PG8_STAGE(PG8_SA(0, 1), a2 + hstep, voffA);
;             PG8_WAIT_V(8); PG8_WAIT_L(0); PG8_BAR; PG8_MMA(0, 0, At, B0); PG8_MMA(0, 1, At, B1); PG8_BAR; PG8_SCHED;
	s_setprio 1
	v_mfma_f32_16x16x32_bf16 v[62:65], v[114:117], v[184:187], v[62:65]
	v_mfma_f32_16x16x32_bf16 v[62:65], v[126:129], v[188:191], v[62:65]
	v_mfma_f32_16x16x32_bf16 v[46:49], v[126:129], v[196:199], v[46:49]
	v_mfma_f32_16x16x32_bf16 v[46:49], v[114:117], v[192:195], v[46:49]
	v_mfma_f32_16x16x32_bf16 v[30:33], v[114:117], v[200:203], v[30:33]
	v_mfma_f32_16x16x32_bf16 v[30:33], v[126:129], v[204:207], v[30:33]
	v_mfma_f32_16x16x32_bf16 v[14:17], v[126:129], v[212:215], v[14:17]
	v_mfma_f32_16x16x32_bf16 v[14:17], v[114:117], v[208:211], v[14:17]
	v_mfma_f32_16x16x32_bf16 v[10:13], v[130:133], v[208:211], v[10:13]
	v_mfma_f32_16x16x32_bf16 v[10:13], v[142:145], v[212:215], v[10:13]
	v_mfma_f32_16x16x32_bf16 v[26:29], v[142:145], v[204:207], v[26:29]
	v_mfma_f32_16x16x32_bf16 v[26:29], v[130:133], v[200:203], v[26:29]
	v_mfma_f32_16x16x32_bf16 v[42:45], v[130:133], v[192:195], v[42:45]
	v_mfma_f32_16x16x32_bf16 v[42:45], v[142:145], v[196:199], v[42:45]
	v_mfma_f32_16x16x32_bf16 v[58:61], v[142:145], v[188:191], v[58:61]
	v_mfma_f32_16x16x32_bf16 v[58:61], v[130:133], v[184:187], v[58:61]
	v_mfma_f32_16x16x32_bf16 v[54:57], v[146:149], v[184:187], v[54:57]
	v_mfma_f32_16x16x32_bf16 v[54:57], v[150:153], v[188:191], v[54:57]
	v_mfma_f32_16x16x32_bf16 v[38:41], v[150:153], v[196:199], v[38:41]
	v_mfma_f32_16x16x32_bf16 v[38:41], v[146:149], v[192:195], v[38:41]
	v_mfma_f32_16x16x32_bf16 v[22:25], v[146:149], v[200:203], v[22:25]
	v_mfma_f32_16x16x32_bf16 v[22:25], v[150:153], v[204:207], v[22:25]
	v_mfma_f32_16x16x32_bf16 v[6:9], v[150:153], v[212:215], v[6:9]
	v_mfma_f32_16x16x32_bf16 v[6:9], v[146:149], v[208:211], v[6:9]
	v_mfma_f32_16x16x32_bf16 v[2:5], v[174:177], v[208:211], v[2:5]
	v_mfma_f32_16x16x32_bf16 v[2:5], v[178:181], v[212:215], v[2:5]
	v_mfma_f32_16x16x32_bf16 v[18:21], v[178:181], v[204:207], v[18:21]
	v_mfma_f32_16x16x32_bf16 v[18:21], v[174:177], v[200:203], v[18:21]
	s_barrier
	s_setprio 2
	v_mfma_f32_16x16x32_bf16 v[34:37], v[174:177], v[192:195], v[34:37]
	v_mfma_f32_16x16x32_bf16 v[34:37], v[178:181], v[196:199], v[34:37]
	v_mfma_f32_16x16x32_bf16 v[50:53], v[178:181], v[188:191], v[50:53]
	v_mfma_f32_16x16x32_bf16 v[50:53], v[174:177], v[184:187], v[50:53]
	s_setprio 0
	s_add_i32 s39, 0, 0x18000
	s_add_i32 s70, 0, 0x1c000
	v_add_u32_e32 v142, s39, v1
	v_add_u32_e32 v173, s70, v1
	ds_read_b128 v[114:117], v142
	ds_read_b128 v[126:129], v142 offset:1024
	ds_read_b128 v[130:133], v142 offset:2048
	ds_read_b128 v[142:145], v142 offset:3072
	ds_read_b128 v[146:149], v173
	ds_read_b128 v[150:153], v173 offset:1024
	ds_read_b128 v[174:177], v173 offset:2048
	ds_read_b128 v[178:181], v173 offset:3072
	s_mov_b32 m0, s58
	v_lshl_add_u64 v[218:219], v[216:217], 0, s[14:15]
	ds_read_b128 v[184:187], v169 offset:32768
	ds_read_b128 v[188:191], v169 offset:33792
	ds_read_b128 v[192:195], v169 offset:34816
	ds_read_b128 v[196:199], v169 offset:35840
	ds_read_b128 v[200:203], v169 offset:36864
	ds_read_b128 v[204:207], v169 offset:37888
	ds_read_b128 v[208:211], v169 offset:38912
	ds_read_b128 v[212:215], v169 offset:39936
	global_load_lds_dwordx4 v[218:219], off
	v_lshl_add_u64 v[218:219], v[216:217], 0, s[16:17]
	s_mov_b32 m0, s59
	s_nop 0
	global_load_lds_dwordx4 v[218:219], off
	s_waitcnt vmcnt(8)
	s_waitcnt lgkmcnt(0)
	s_barrier
	s_setprio 1
	v_mfma_f32_16x16x32_bf16 v[138:141], v[114:117], v[184:187], v[138:141]
	v_mfma_f32_16x16x32_bf16 v[138:141], v[126:129], v[188:191], v[138:141]
	v_mfma_f32_16x16x32_bf16 v[110:113], v[126:129], v[196:199], v[110:113]
	v_mfma_f32_16x16x32_bf16 v[110:113], v[114:117], v[192:195], v[110:113]
	v_mfma_f32_16x16x32_bf16 v[94:97], v[114:117], v[200:203], v[94:97]
	v_mfma_f32_16x16x32_bf16 v[94:97], v[126:129], v[204:207], v[94:97]
	v_mfma_f32_16x16x32_bf16 v[78:81], v[126:129], v[212:215], v[78:81]
	v_mfma_f32_16x16x32_bf16 v[78:81], v[114:117], v[208:211], v[78:81]
	v_mfma_f32_16x16x32_bf16 v[74:77], v[130:133], v[208:211], v[74:77]
	v_mfma_f32_16x16x32_bf16 v[74:77], v[142:145], v[212:215], v[74:77]
	v_mfma_f32_16x16x32_bf16 v[90:93], v[142:145], v[204:207], v[90:93]
	v_mfma_f32_16x16x32_bf16 v[90:93], v[130:133], v[200:203], v[90:93]
	v_mfma_f32_16x16x32_bf16 v[106:109], v[130:133], v[192:195], v[106:109]
	v_mfma_f32_16x16x32_bf16 v[106:109], v[142:145], v[196:199], v[106:109]
	v_mfma_f32_16x16x32_bf16 v[134:137], v[142:145], v[188:191], v[134:137]
	v_mfma_f32_16x16x32_bf16 v[134:137], v[130:133], v[184:187], v[134:137]
	v_mfma_f32_16x16x32_bf16 v[122:125], v[146:149], v[184:187], v[122:125]
	v_mfma_f32_16x16x32_bf16 v[122:125], v[150:153], v[188:191], v[122:125]
	v_mfma_f32_16x16x32_bf16 v[102:105], v[150:153], v[196:199], v[102:105]
	v_mfma_f32_16x16x32_bf16 v[102:105], v[146:149], v[192:195], v[102:105]
	v_mfma_f32_16x16x32_bf16 v[86:89], v[146:149], v[200:203], v[86:89]
	v_mfma_f32_16x16x32_bf16 v[86:89], v[150:153], v[204:207], v[86:89]
	v_mfma_f32_16x16x32_bf16 v[70:73], v[150:153], v[212:215], v[70:73]
	v_mfma_f32_16x16x32_bf16 v[70:73], v[146:149], v[208:211], v[70:73]
	v_mfma_f32_16x16x32_bf16 v[66:69], v[174:177], v[208:211], v[66:69]
	v_mfma_f32_16x16x32_bf16 v[66:69], v[178:181], v[212:215], v[66:69]
	v_mfma_f32_16x16x32_bf16 v[82:85], v[178:181], v[204:207], v[82:85]
	v_mfma_f32_16x16x32_bf16 v[82:85], v[174:177], v[200:203], v[82:85]
	s_barrier
; #define PG8_LDA(dst, b, h) do { _Pragma("unroll") for (int m = 0; m < 4; ++m) _Pragma("unroll") for (int k = 0; k < 2; ++k) dst[m][k] = *(const PG8_LAS bf16x8*)(lds + PG8_SA(b, h) + aoff + m * 2048 + k * 1024); } while (0)
; #define PG8_WAIT_V(n) asm volatile("s_waitcnt vmcnt(" #n ")" ::: "memory")
; template <class Epi, class Sched, bool ALIGN_EPI = false, bool SP2 = false, bool ABLK = false>
; __device__ __forceinline__ void gemm_phase(PG8_LAS unsigned char* lds, const Gemm g, const Sched& S, const Epi& E) {
;     ...
;             PG8_WAIT_V(8); PG8_WAIT_L(0); PG8_BAR; PG8_MMA(0, 0, At, B0); PG8_MMA(0, 1, At, B1); PG8_BAR; PG8_SCHED;
;             PG8_LDA(At, 1, 1); PG8_STAGE(PG8_SB(1, 0), b3, voffB); PG8_STAGE(PG8_SB(1, 1), b3 + hstep, voffB); PG8_STAGE(PG8_SA(1, 0), a3, voffA);
;             PG8_WAIT_V(8); PG8_WAIT_L(0); PG8_BAR; PG8_MMA(1, 0, At, B0); PG8_MMA(1, 1, At, B1); PG8_BAR; PG8_SCHED;
;             } else {
;             PG8_LDB(B0, 0, 0); PG8_SCHED; PG8_LDA(At, 0, 0); PG8_STAGE(PG8_SA(1, 1), a1 + hstep, voffA);
;             PG8_WAIT_L(8); PG8_BAR; PG8_WAIT_L(0); PG8_MMA(0, 0, At, B0); PG8_BAR; PG8_SCHED;
;             PG8_LDB(B1, 0, 1); PG8_STAGE(PG8_SB(0, 0), b2, voffB);
;             PG8_BAR; PG8_WAIT_L(0); PG8_MMA(0, 1, At, B1); PG8_BAR;
;             PG8_LDA(At, 0, 1); PG8_STAGE(PG8_SA(0, 0), a2, voffA);
;             PG8_BAR; PG8_WAIT_L(0); PG8_MMA(1, 0, At, B0); PG8_BAR; PG8_SCHED;
;             PG8_STAGE(PG8_SB(0, 1), b2 + hstep, voffB);
;             PG8_WAIT_V(6); PG8_BAR; PG8_MMA(1, 1, At, B1); PG8_BAR;
;             PG8_LDB(B0, 1, 0); PG8_SCHED; PG8_LDA(At, 1, 0); PG8_STAGE(PG8_SA(0, 1), a2 + hstep, voffA);
;             PG8_WAIT_L(8); PG8_BAR; PG8_WAIT_L(0); PG8_MMA(0, 0, At, B0); PG8_BAR; PG8_SCHED;
;             PG8_LDB(B1, 1, 1); PG8_STAGE(PG8_SB(1, 0), b3, voffB);
;             PG8_BAR; PG8_WAIT_L(0); PG8_MMA(0, 1, At, B1); PG8_BAR;
;             PG8_LDA(At, 1, 1); PG8_STAGE(PG8_SA(1, 0), a3, voffA);
;             PG8_BAR; PG8_WAIT_L(0); PG8_MMA(1, 0, At, B0); PG8_BAR; PG8_SCHED;
;             PG8_STAGE(PG8_SB(1, 1), b3 + hstep, voffB);
;             PG8_WAIT_V(6); PG8_BAR; PG8_MMA(1, 1, At, B1); PG8_BAR;
;             }
;         }
;         if constexpr (ALIGN_EPI) { if (wr == 0) PG8_BAR; }
;         if constexpr (!Epi::AFTER_DRAIN) { E(acc, cur, wr, wc, fr, fq); S.done(cur); }
;         if (!has_next) break;
	s_setprio 2
	v_mfma_f32_16x16x32_bf16 v[98:101], v[174:177], v[192:195], v[98:101]
	v_mfma_f32_16x16x32_bf16 v[98:101], v[178:181], v[196:199], v[98:101]
	v_mfma_f32_16x16x32_bf16 v[118:121], v[178:181], v[188:191], v[118:121]
	v_mfma_f32_16x16x32_bf16 v[118:121], v[174:177], v[184:187], v[118:121]
	s_setprio 0
	s_add_i32 s39, s39, s55
	v_lshl_add_u64 v[218:219], v[162:163], 0, s[24:25]
	s_mov_b32 m0, s39
	ds_read_b128 v[184:187], v169 offset:49152
	ds_read_b128 v[188:191], v169 offset:50176
	ds_read_b128 v[192:195], v169 offset:51200
	ds_read_b128 v[196:199], v169 offset:52224
	ds_read_b128 v[200:203], v169 offset:53248
	ds_read_b128 v[204:207], v169 offset:54272
	ds_read_b128 v[208:211], v169 offset:55296
	ds_read_b128 v[212:215], v169 offset:56320
	global_load_lds_dwordx4 v[218:219], off
	v_lshl_add_u64 v[218:219], v[162:163], 0, s[26:27]
	s_add_i32 m0, s39, 0x2000
	s_add_i32 s39, s70, s55
	global_load_lds_dwordx4 v[218:219], off
	v_lshl_add_u64 v[218:219], v[162:163], 0, s[28:29]
	s_mov_b32 m0, s39
	v_lshl_add_u64 v[162:163], v[162:163], 0, s[30:31]
	global_load_lds_dwordx4 v[218:219], off
	s_add_i32 m0, s39, 0x2000
	s_nop 0
	global_load_lds_dwordx4 v[162:163], off
	v_lshl_add_u64 v[162:163], v[216:217], 0, s[24:25]
	s_mov_b32 m0, s62
	s_nop 0
	global_load_lds_dwordx4 v[162:163], off
	v_lshl_add_u64 v[162:163], v[216:217], 0, s[26:27]
	s_mov_b32 m0, s63
	s_nop 0
	global_load_lds_dwordx4 v[162:163], off
	s_waitcnt vmcnt(8)
	s_waitcnt lgkmcnt(0)
	s_barrier
	s_setprio 1
	v_mfma_f32_16x16x32_bf16 v[62:65], v[114:117], v[184:187], v[62:65]
	v_mfma_f32_16x16x32_bf16 v[62:65], v[126:129], v[188:191], v[62:65]
	v_mfma_f32_16x16x32_bf16 v[46:49], v[126:129], v[196:199], v[46:49]
	v_mfma_f32_16x16x32_bf16 v[46:49], v[114:117], v[192:195], v[46:49]
	v_mfma_f32_16x16x32_bf16 v[30:33], v[114:117], v[200:203], v[30:33]
	v_mfma_f32_16x16x32_bf16 v[30:33], v[126:129], v[204:207], v[30:33]
	v_mfma_f32_16x16x32_bf16 v[14:17], v[126:129], v[212:215], v[14:17]
	v_mfma_f32_16x16x32_bf16 v[14:17], v[114:117], v[208:211], v[14:17]
	v_mfma_f32_16x16x32_bf16 v[10:13], v[130:133], v[208:211], v[10:13]
	v_mfma_f32_16x16x32_bf16 v[10:13], v[142:145], v[212:215], v[10:13]
	v_mfma_f32_16x16x32_bf16 v[26:29], v[142:145], v[204:207], v[26:29]
	v_mfma_f32_16x16x32_bf16 v[26:29], v[130:133], v[200:203], v[26:29]
	v_mfma_f32_16x16x32_bf16 v[42:45], v[130:133], v[192:195], v[42:45]
	v_mfma_f32_16x16x32_bf16 v[42:45], v[142:145], v[196:199], v[42:45]
	v_mfma_f32_16x16x32_bf16 v[58:61], v[142:145], v[188:191], v[58:61]
	v_mfma_f32_16x16x32_bf16 v[58:61], v[130:133], v[184:187], v[58:61]
	v_mfma_f32_16x16x32_bf16 v[54:57], v[146:149], v[184:187], v[54:57]
	v_mfma_f32_16x16x32_bf16 v[54:57], v[150:153], v[188:191], v[54:57]
	v_mfma_f32_16x16x32_bf16 v[38:41], v[150:153], v[196:199], v[38:41]
	v_mfma_f32_16x16x32_bf16 v[38:41], v[146:149], v[192:195], v[38:41]
	v_mfma_f32_16x16x32_bf16 v[22:25], v[146:149], v[200:203], v[22:25]
	v_mfma_f32_16x16x32_bf16 v[22:25], v[150:153], v[204:207], v[22:25]
	v_mfma_f32_16x16x32_bf16 v[6:9], v[150:153], v[212:215], v[6:9]
	v_mfma_f32_16x16x32_bf16 v[6:9], v[146:149], v[208:211], v[6:9]
	v_mfma_f32_16x16x32_bf16 v[2:5], v[174:177], v[208:211], v[2:5]
	v_mfma_f32_16x16x32_bf16 v[2:5], v[178:181], v[212:215], v[2:5]
	v_mfma_f32_16x16x32_bf16 v[18:21], v[178:181], v[204:207], v[18:21]
	v_mfma_f32_16x16x32_bf16 v[18:21], v[174:177], v[200:203], v[18:21]
	s_barrier
	s_setprio 2
	v_mfma_f32_16x16x32_bf16 v[34:37], v[174:177], v[192:195], v[34:37]
	v_mfma_f32_16x16x32_bf16 v[34:37], v[178:181], v[196:199], v[34:37]
	v_mfma_f32_16x16x32_bf16 v[50:53], v[178:181], v[188:191], v[50:53]
	v_mfma_f32_16x16x32_bf16 v[50:53], v[174:177], v[184:187], v[50:53]
	s_setprio 0
	s_add_u32 s68, s68, 0x1000
	s_addc_u32 s69, s69, 0
	s_add_u32 s11, s11, 0x1000
	s_addc_u32 s37, s37, 0
	s_cmp_ge_i32 s41, s79
	s_mov_b32 s39, s41
	s_cbranch_scc0 .LBB0_1533
	s_and_b64 vcc, exec, s[34:35]
	s_cbranch_vccnz .LBB0_1538
	s_lshl_b32 s11, s2, 8
	s_cmp_gt_i32 s2, 63
	s_mov_b64 s[68:69], -1
	s_cbranch_scc1 .LBB0_1539

; #define PG8_STAGE(bufoff, gbase, voff) do { if constexpr (!pg8_noload<Epi>::value) { _Pragma("unroll") for (int _i = 0; _i < 2; ++_i) \
;         __builtin_amdgcn_global_load_lds((const unsigned*)((const char*)(gbase) + (size_t)_i * pstep + (voff)[0]), (PG8_LAS unsigned*)(lds + (bufoff) + ldsw + _i * 8192), 16, 0, 0); } } while (0)
; #define PG8_LDA(dst, b, h) do { _Pragma("unroll") for (int m = 0; m < 4; ++m) _Pragma("unroll") for (int k = 0; k < 2; ++k) dst[m][k] = *(const PG8_LAS bf16x8*)(lds + PG8_SA(b, h) + aoff + m * 2048 + k * 1024); } while (0)
; #define PG8_LDB(dst, b, h) do { _Pragma("unroll") for (int n = 0; n < 2; ++n) _Pragma("unroll") for (int k = 0; k < 2; ++k) dst[n][k] = *(const PG8_LAS bf16x8*)(lds + PG8_SB(b, h) + boff + n * 2048 + k * 1024); } while (0)
; #define PG8_MMA(ai, bj, At, Bt) do { __builtin_amdgcn_s_setprio(1); _Pragma("unroll") for (int m = 0; m < 4; ++m) _Pragma("unroll") for (int n = 0; n < 2; ++n) _Pragma("unroll") for (int k = 0; k < 2; ++k) \
;         acc[ai][bj][m][n] = __builtin_amdgcn_mfma_f32_16x16x32_bf16(Bt[n][k], At[m][k], acc[ai][bj][m][n], 0, 0, 0); __builtin_amdgcn_s_setprio(0); } while (0)
; #define PG8_BAR __builtin_amdgcn_s_barrier()
; template <class Epi, class Sched, bool ALIGN_EPI = false, bool SP2 = false, bool ABLK = false>
; __device__ __forceinline__ void gemm_phase(PG8_LAS unsigned char* lds, const Gemm g, const Sched& S, const Epi& E) {
;     ...
;         for (int t = 0; t < nt; t += 2) {
;             const bool last = (t == nt - 2);
;             const char* a1 = cA + (size_t)(t + 1) * kstep;
;             const char* a2 = last ? nA : cA + (size_t)(t + 2) * kstep; const char* b2 = last ? nB : cB + (size_t)(t + 2) * kstepB;
;             const char* a3 = a2 + kstep; const char* b3 = b2 + kstepB;
;             if (last && has_next) S.a_ready(nxt);
;             if constexpr (SP2) {
;             PG8_LDB(B0, 0, 0); PG8_LDB(B1, 0, 1); PG8_SCHED; PG8_LDA(At, 0, 0); PG8_STAGE(PG8_SA(1, 1), a1 + hstep, voffA);
;             PG8_WAIT_V(8); PG8_WAIT_L(0); PG8_BAR; PG8_MMA(0, 0, At, B0); PG8_MMA(0, 1, At, B1); PG8_BAR; PG8_SCHED;
;             PG8_LDA(At, 0, 1); PG8_STAGE(PG8_SB(0, 0), b2, voffB); PG8_STAGE(PG8_SB(0, 1), b2 + hstep, voffB); PG8_STAGE(PG8_SA(0, 0), a2, voffA);
;             PG8_WAIT_V(8); PG8_WAIT_L(0); PG8_BAR; PG8_MMA(1, 0, At, B0); PG8_MMA(1, 1, At, B1); PG8_BAR; PG8_SCHED;
.LBB0_1657:
	s_or_b32 s26, s94, 1
	s_lshl_b64 s[82:83], s[26:27], 11
	s_add_u32 s88, s74, s82
	v_add_u32_e32 v140, s12, v173
	s_addc_u32 s89, s75, s83
	s_add_i32 s26, s94, 2
	ds_read_b128 v[130:133], v140
	ds_read_b128 v[134:137], v140 offset:1024
	ds_read_b128 v[154:157], v140 offset:2048
	ds_read_b128 v[158:161], v140 offset:3072
	v_add_u32_e32 v140, s13, v173
	s_lshl_b64 s[90:91], s[26:27], 11
	ds_read_b128 v[162:165], v140
	ds_read_b128 v[166:169], v140 offset:1024
	ds_read_b128 v[184:187], v140 offset:2048
	ds_read_b128 v[188:191], v140 offset:3072
	s_add_u32 s92, s74, s90
	s_addc_u32 s93, s75, s91
	s_and_b64 s[82:83], s[80:81], exec
	s_cselect_b32 s83, s93, s3
	s_cselect_b32 s82, s92, s25
	s_add_u32 s90, s76, s90
	s_addc_u32 s91, s77, s91
	s_and_b64 s[80:81], s[80:81], exec
	s_cselect_b32 s81, s91, s65
	s_cselect_b32 s80, s90, s67
	v_lshl_add_u64 v[170:171], s[88:89], 0, v[138:139]
	v_lshl_add_u64 v[224:225], v[170:171], 0, s[20:21]
	s_add_i32 m0, s56, 0xc000
	ds_read_b128 v[192:195], v178
	ds_read_b128 v[196:199], v178 offset:1024
	ds_read_b128 v[200:203], v178 offset:2048
	ds_read_b128 v[204:207], v178 offset:3072
	ds_read_b128 v[208:211], v178 offset:4096
	ds_read_b128 v[212:215], v178 offset:5120
	ds_read_b128 v[216:219], v178 offset:6144
	ds_read_b128 v[220:223], v178 offset:7168
	global_load_lds_dwordx4 v[224:225], off
	v_lshl_add_u64 v[170:171], v[170:171], 0, s[22:23]
	s_add_i32 m0, s56, 0xe000
	s_nop 0
	global_load_lds_dwordx4 v[170:171], off
	s_waitcnt vmcnt(8)
	s_waitcnt lgkmcnt(0)
	s_barrier
	s_setprio 1
	v_mfma_f32_16x16x32_bf16 v[126:129], v[130:133], v[192:195], v[126:129]
	v_mfma_f32_16x16x32_bf16 v[126:129], v[134:137], v[196:199], v[126:129]
	v_mfma_f32_16x16x32_bf16 v[110:113], v[134:137], v[204:207], v[110:113]
	v_mfma_f32_16x16x32_bf16 v[110:113], v[130:133], v[200:203], v[110:113]
	v_mfma_f32_16x16x32_bf16 v[94:97], v[130:133], v[208:211], v[94:97]
	v_mfma_f32_16x16x32_bf16 v[94:97], v[134:137], v[212:215], v[94:97]
	v_mfma_f32_16x16x32_bf16 v[78:81], v[134:137], v[220:223], v[78:81]
	v_mfma_f32_16x16x32_bf16 v[78:81], v[130:133], v[216:219], v[78:81]
	v_mfma_f32_16x16x32_bf16 v[74:77], v[154:157], v[216:219], v[74:77]
	v_mfma_f32_16x16x32_bf16 v[74:77], v[158:161], v[220:223], v[74:77]
	v_mfma_f32_16x16x32_bf16 v[90:93], v[158:161], v[212:215], v[90:93]
	v_mfma_f32_16x16x32_bf16 v[90:93], v[154:157], v[208:211], v[90:93]
	v_mfma_f32_16x16x32_bf16 v[106:109], v[154:157], v[200:203], v[106:109]
	v_mfma_f32_16x16x32_bf16 v[106:109], v[158:161], v[204:207], v[106:109]
	v_mfma_f32_16x16x32_bf16 v[122:125], v[158:161], v[196:199], v[122:125]
	v_mfma_f32_16x16x32_bf16 v[122:125], v[154:157], v[192:195], v[122:125]
	v_mfma_f32_16x16x32_bf16 v[118:121], v[162:165], v[192:195], v[118:121]
	v_mfma_f32_16x16x32_bf16 v[118:121], v[166:169], v[196:199], v[118:121]
	v_mfma_f32_16x16x32_bf16 v[102:105], v[166:169], v[204:207], v[102:105]
	v_mfma_f32_16x16x32_bf16 v[102:105], v[162:165], v[200:203], v[102:105]
	v_mfma_f32_16x16x32_bf16 v[86:89], v[162:165], v[208:211], v[86:89]
	v_mfma_f32_16x16x32_bf16 v[86:89], v[166:169], v[212:215], v[86:89]
	v_mfma_f32_16x16x32_bf16 v[70:73], v[166:169], v[220:223], v[70:73]
	v_mfma_f32_16x16x32_bf16 v[70:73], v[162:165], v[216:219], v[70:73]
	v_mfma_f32_16x16x32_bf16 v[66:69], v[184:187], v[216:219], v[66:69]
	v_mfma_f32_16x16x32_bf16 v[66:69], v[188:191], v[220:223], v[66:69]
	v_mfma_f32_16x16x32_bf16 v[82:85], v[188:191], v[212:215], v[82:85]
	v_mfma_f32_16x16x32_bf16 v[82:85], v[184:187], v[208:211], v[82:85]
	s_barrier
	s_setprio 2
	v_mfma_f32_16x16x32_bf16 v[98:101], v[184:187], v[200:203], v[98:101]
	v_mfma_f32_16x16x32_bf16 v[98:101], v[188:191], v[204:207], v[98:101]
	v_mfma_f32_16x16x32_bf16 v[114:117], v[188:191], v[196:199], v[114:117]
	v_mfma_f32_16x16x32_bf16 v[114:117], v[184:187], v[192:195], v[114:117]
	s_setprio 0
	v_lshl_add_u64 v[170:171], s[80:81], 0, v[138:139]
	s_add_i32 s80, s12, s55
	s_mov_b32 m0, s80
	ds_read_b128 v[192:195], v178 offset:16384
	ds_read_b128 v[196:199], v178 offset:17408
	ds_read_b128 v[200:203], v178 offset:18432
	ds_read_b128 v[204:207], v178 offset:19456
	ds_read_b128 v[208:211], v178 offset:20480
	ds_read_b128 v[212:215], v178 offset:21504
	ds_read_b128 v[216:219], v178 offset:22528
	ds_read_b128 v[220:223], v178 offset:23552
	global_load_lds_dwordx4 v[170:171], off
	v_lshl_add_u64 v[224:225], v[170:171], 0, s[18:19]
	s_add_i32 m0, s80, 0x2000
	s_add_i32 s80, s13, s55
	global_load_lds_dwordx4 v[224:225], off
	v_lshl_add_u64 v[224:225], v[170:171], 0, s[20:21]
	s_mov_b32 m0, s80
	s_nop 0
	global_load_lds_dwordx4 v[224:225], off
	v_lshl_add_u64 v[224:225], v[170:171], 0, s[22:23]
	s_add_i32 m0, s80, 0x2000
	s_nop 0
	global_load_lds_dwordx4 v[224:225], off
	v_lshl_add_u64 v[224:225], s[82:83], 0, v[138:139]
	s_mov_b32 m0, s56
	v_lshl_add_u64 v[226:227], v[224:225], 0, s[18:19]
	global_load_lds_dwordx4 v[224:225], off
	s_mov_b32 m0, s57
	s_nop 0
	global_load_lds_dwordx4 v[226:227], off
	s_waitcnt vmcnt(8)
	s_waitcnt lgkmcnt(0)
	s_barrier
; #define PG8_STAGE(bufoff, gbase, voff) do { if constexpr (!pg8_noload<Epi>::value) { _Pragma("unroll") for (int _i = 0; _i < 2; ++_i) \
;         __builtin_amdgcn_global_load_lds((const unsigned*)((const char*)(gbase) + (size_t)_i * pstep + (voff)[0]), (PG8_LAS unsigned*)(lds + (bufoff) + ldsw + _i * 8192), 16, 0, 0); } } while (0)
; #define PG8_LDA(dst, b, h) do { _Pragma("unroll") for (int m = 0; m < 4; ++m) _Pragma("unroll") for (int k = 0; k < 2; ++k) dst[m][k] = *(const PG8_LAS bf16x8*)(lds + PG8_SA(b, h) + aoff + m * 2048 + k * 1024); } while (0)
; #define PG8_LDB(dst, b, h) do { _Pragma("unroll") for (int n = 0; n < 2; ++n) _Pragma("unroll") for (int k = 0; k < 2; ++k) dst[n][k] = *(const PG8_LAS bf16x8*)(lds + PG8_SB(b, h) + boff + n * 2048 + k * 1024); } while (0)
; #define PG8_MMA(ai, bj, At, Bt) do { __builtin_amdgcn_s_setprio(1); _Pragma("unroll") for (int m = 0; m < 4; ++m) _Pragma("unroll") for (int n = 0; n < 2; ++n) _Pragma("unroll") for (int k = 0; k < 2; ++k) \
;         acc[ai][bj][m][n] = __builtin_amdgcn_mfma_f32_16x16x32_bf16(Bt[n][k], At[m][k], acc[ai][bj][m][n], 0, 0, 0); __builtin_amdgcn_s_setprio(0); } while (0)
; #define PG8_WAIT_V(n) asm volatile("s_waitcnt vmcnt(" #n ")" ::: "memory")
; #define PG8_WAIT_L(n) asm volatile("s_waitcnt lgkmcnt(" #n ")" ::: "memory")
; #define PG8_BAR __builtin_amdgcn_s_barrier()
; #define PG8_SCHED __builtin_amdgcn_sched_barrier(0)
; template <class Epi, class Sched, bool ALIGN_EPI = false, bool SP2 = false, bool ABLK = false>
; __device__ __forceinline__ void gemm_phase(PG8_LAS unsigned char* lds, const Gemm g, const Sched& S, const Epi& E) {
;     ...
;             PG8_WAIT_V(8); PG8_WAIT_L(0); PG8_BAR; PG8_MMA(1, 0, At, B0); PG8_MMA(1, 1, At, B1); PG8_BAR; PG8_SCHED;
;             PG8_LDB(B0, 1, 0); PG8_LDB(B1, 1, 1); PG8_SCHED; PG8_LDA(At, 1, 0); PG8_STAGE(PG8_SA(0, 1), a2 + hstep, voffA);
;             PG8_WAIT_V(8); PG8_WAIT_L(0); PG8_BAR; PG8_MMA(0, 0, At, B0); PG8_MMA(0, 1, At, B1); PG8_BAR; PG8_SCHED;
	s_setprio 1
	v_mfma_f32_16x16x32_bf16 v[62:65], v[130:133], v[192:195], v[62:65]
	v_mfma_f32_16x16x32_bf16 v[62:65], v[134:137], v[196:199], v[62:65]
	v_mfma_f32_16x16x32_bf16 v[46:49], v[134:137], v[204:207], v[46:49]
	v_mfma_f32_16x16x32_bf16 v[46:49], v[130:133], v[200:203], v[46:49]
	v_mfma_f32_16x16x32_bf16 v[30:33], v[130:133], v[208:211], v[30:33]
	v_mfma_f32_16x16x32_bf16 v[30:33], v[134:137], v[212:215], v[30:33]
	v_mfma_f32_16x16x32_bf16 v[14:17], v[134:137], v[220:223], v[14:17]
	v_mfma_f32_16x16x32_bf16 v[14:17], v[130:133], v[216:219], v[14:17]
	v_mfma_f32_16x16x32_bf16 v[10:13], v[154:157], v[216:219], v[10:13]
	v_mfma_f32_16x16x32_bf16 v[10:13], v[158:161], v[220:223], v[10:13]
	v_mfma_f32_16x16x32_bf16 v[26:29], v[158:161], v[212:215], v[26:29]
	v_mfma_f32_16x16x32_bf16 v[26:29], v[154:157], v[208:211], v[26:29]
	v_mfma_f32_16x16x32_bf16 v[42:45], v[154:157], v[200:203], v[42:45]
	v_mfma_f32_16x16x32_bf16 v[42:45], v[158:161], v[204:207], v[42:45]
	v_mfma_f32_16x16x32_bf16 v[58:61], v[158:161], v[196:199], v[58:61]
	v_mfma_f32_16x16x32_bf16 v[58:61], v[154:157], v[192:195], v[58:61]
	v_mfma_f32_16x16x32_bf16 v[54:57], v[162:165], v[192:195], v[54:57]
	v_mfma_f32_16x16x32_bf16 v[54:57], v[166:169], v[196:199], v[54:57]
	v_mfma_f32_16x16x32_bf16 v[38:41], v[166:169], v[204:207], v[38:41]
	v_mfma_f32_16x16x32_bf16 v[38:41], v[162:165], v[200:203], v[38:41]
	v_mfma_f32_16x16x32_bf16 v[22:25], v[162:165], v[208:211], v[22:25]
	v_mfma_f32_16x16x32_bf16 v[22:25], v[166:169], v[212:215], v[22:25]
	v_mfma_f32_16x16x32_bf16 v[6:9], v[166:169], v[220:223], v[6:9]
	v_mfma_f32_16x16x32_bf16 v[6:9], v[162:165], v[216:219], v[6:9]
	v_mfma_f32_16x16x32_bf16 v[2:5], v[184:187], v[216:219], v[2:5]
	v_mfma_f32_16x16x32_bf16 v[2:5], v[188:191], v[220:223], v[2:5]
	v_mfma_f32_16x16x32_bf16 v[18:21], v[188:191], v[212:215], v[18:21]
	v_mfma_f32_16x16x32_bf16 v[18:21], v[184:187], v[208:211], v[18:21]
	s_barrier
	s_setprio 2
	v_mfma_f32_16x16x32_bf16 v[34:37], v[184:187], v[200:203], v[34:37]
	v_mfma_f32_16x16x32_bf16 v[34:37], v[188:191], v[204:207], v[34:37]
	v_mfma_f32_16x16x32_bf16 v[50:53], v[188:191], v[196:199], v[50:53]
	v_mfma_f32_16x16x32_bf16 v[50:53], v[184:187], v[192:195], v[50:53]
	s_setprio 0
	s_add_i32 s80, 0, 0x18000
	v_add_u32_e32 v140, s80, v173
	s_add_i32 s81, 0, 0x1c000
	ds_read_b128 v[130:133], v140
	ds_read_b128 v[134:137], v140 offset:1024
	ds_read_b128 v[154:157], v140 offset:2048
	ds_read_b128 v[158:161], v140 offset:3072
	v_add_u32_e32 v140, s81, v173
	ds_read_b128 v[162:165], v140
	ds_read_b128 v[166:169], v140 offset:1024
	ds_read_b128 v[184:187], v140 offset:2048
	ds_read_b128 v[188:191], v140 offset:3072
	s_mov_b32 m0, s58
	v_lshl_add_u64 v[226:227], v[224:225], 0, s[20:21]
	ds_read_b128 v[192:195], v178 offset:32768
	ds_read_b128 v[196:199], v178 offset:33792
	ds_read_b128 v[200:203], v178 offset:34816
	ds_read_b128 v[204:207], v178 offset:35840
	ds_read_b128 v[208:211], v178 offset:36864
	ds_read_b128 v[212:215], v178 offset:37888
	ds_read_b128 v[216:219], v178 offset:38912
	ds_read_b128 v[220:223], v178 offset:39936
	global_load_lds_dwordx4 v[226:227], off
	v_lshl_add_u64 v[226:227], v[224:225], 0, s[22:23]
	s_mov_b32 m0, s59
	s_nop 0
	global_load_lds_dwordx4 v[226:227], off
	s_waitcnt vmcnt(8)
	s_waitcnt lgkmcnt(0)
	s_barrier
	s_setprio 1
	v_mfma_f32_16x16x32_bf16 v[126:129], v[130:133], v[192:195], v[126:129]
	v_mfma_f32_16x16x32_bf16 v[126:129], v[134:137], v[196:199], v[126:129]
	v_mfma_f32_16x16x32_bf16 v[110:113], v[134:137], v[204:207], v[110:113]
	v_mfma_f32_16x16x32_bf16 v[110:113], v[130:133], v[200:203], v[110:113]
	v_mfma_f32_16x16x32_bf16 v[94:97], v[130:133], v[208:211], v[94:97]
	v_mfma_f32_16x16x32_bf16 v[94:97], v[134:137], v[212:215], v[94:97]
	v_mfma_f32_16x16x32_bf16 v[78:81], v[134:137], v[220:223], v[78:81]
	v_mfma_f32_16x16x32_bf16 v[78:81], v[130:133], v[216:219], v[78:81]
	v_mfma_f32_16x16x32_bf16 v[74:77], v[154:157], v[216:219], v[74:77]
	v_mfma_f32_16x16x32_bf16 v[74:77], v[158:161], v[220:223], v[74:77]
	v_mfma_f32_16x16x32_bf16 v[90:93], v[158:161], v[212:215], v[90:93]
	v_mfma_f32_16x16x32_bf16 v[90:93], v[154:157], v[208:211], v[90:93]
	v_mfma_f32_16x16x32_bf16 v[106:109], v[154:157], v[200:203], v[106:109]
	v_mfma_f32_16x16x32_bf16 v[106:109], v[158:161], v[204:207], v[106:109]
	v_mfma_f32_16x16x32_bf16 v[122:125], v[158:161], v[196:199], v[122:125]
	v_mfma_f32_16x16x32_bf16 v[122:125], v[154:157], v[192:195], v[122:125]
	v_mfma_f32_16x16x32_bf16 v[118:121], v[162:165], v[192:195], v[118:121]
	v_mfma_f32_16x16x32_bf16 v[118:121], v[166:169], v[196:199], v[118:121]
	v_mfma_f32_16x16x32_bf16 v[102:105], v[166:169], v[204:207], v[102:105]
	v_mfma_f32_16x16x32_bf16 v[102:105], v[162:165], v[200:203], v[102:105]
	v_mfma_f32_16x16x32_bf16 v[86:89], v[162:165], v[208:211], v[86:89]
	v_mfma_f32_16x16x32_bf16 v[86:89], v[166:169], v[212:215], v[86:89]
	v_mfma_f32_16x16x32_bf16 v[70:73], v[166:169], v[220:223], v[70:73]
	v_mfma_f32_16x16x32_bf16 v[70:73], v[162:165], v[216:219], v[70:73]
	v_mfma_f32_16x16x32_bf16 v[66:69], v[184:187], v[216:219], v[66:69]
	v_mfma_f32_16x16x32_bf16 v[66:69], v[188:191], v[220:223], v[66:69]
	v_mfma_f32_16x16x32_bf16 v[82:85], v[188:191], v[212:215], v[82:85]
	v_mfma_f32_16x16x32_bf16 v[82:85], v[184:187], v[208:211], v[82:85]
	s_barrier
; #define PG8_STAGE(bufoff, gbase, voff) do { if constexpr (!pg8_noload<Epi>::value) { _Pragma("unroll") for (int _i = 0; _i < 2; ++_i) \
;         __builtin_amdgcn_global_load_lds((const unsigned*)((const char*)(gbase) + (size_t)_i * pstep + (voff)[0]), (PG8_LAS unsigned*)(lds + (bufoff) + ldsw + _i * 8192), 16, 0, 0); } } while (0)
; #define PG8_LDA(dst, b, h) do { _Pragma("unroll") for (int m = 0; m < 4; ++m) _Pragma("unroll") for (int k = 0; k < 2; ++k) dst[m][k] = *(const PG8_LAS bf16x8*)(lds + PG8_SA(b, h) + aoff + m * 2048 + k * 1024); } while (0)
; #define PG8_MMA(ai, bj, At, Bt) do { __builtin_amdgcn_s_setprio(1); _Pragma("unroll") for (int m = 0; m < 4; ++m) _Pragma("unroll") for (int n = 0; n < 2; ++n) _Pragma("unroll") for (int k = 0; k < 2; ++k) \
;         acc[ai][bj][m][n] = __builtin_amdgcn_mfma_f32_16x16x32_bf16(Bt[n][k], At[m][k], acc[ai][bj][m][n], 0, 0, 0); __builtin_amdgcn_s_setprio(0); } while (0)
; #define PG8_WAIT_V(n) asm volatile("s_waitcnt vmcnt(" #n ")" ::: "memory")
; #define PG8_WAIT_L(n) asm volatile("s_waitcnt lgkmcnt(" #n ")" ::: "memory")
; #define PG8_BAR __builtin_amdgcn_s_barrier()
; #define PG8_SCHED __builtin_amdgcn_sched_barrier(0)
; template <class Epi, class Sched, bool ALIGN_EPI = false, bool SP2 = false, bool ABLK = false>
; __device__ __forceinline__ void gemm_phase(PG8_LAS unsigned char* lds, const Gemm g, const Sched& S, const Epi& E) {
;     ...
;         for (int t = 0; t < nt; t += 2) {
;             const bool last = (t == nt - 2);
;     ...
;             PG8_WAIT_V(8); PG8_WAIT_L(0); PG8_BAR; PG8_MMA(0, 0, At, B0); PG8_MMA(0, 1, At, B1); PG8_BAR; PG8_SCHED;
;             PG8_LDA(At, 1, 1); PG8_STAGE(PG8_SB(1, 0), b3, voffB); PG8_STAGE(PG8_SB(1, 1), b3 + hstep, voffB); PG8_STAGE(PG8_SA(1, 0), a3, voffA);
;             PG8_WAIT_V(8); PG8_WAIT_L(0); PG8_BAR; PG8_MMA(1, 0, At, B0); PG8_MMA(1, 1, At, B1); PG8_BAR; PG8_SCHED;
	s_setprio 2
	v_mfma_f32_16x16x32_bf16 v[98:101], v[184:187], v[200:203], v[98:101]
	v_mfma_f32_16x16x32_bf16 v[98:101], v[188:191], v[204:207], v[98:101]
	v_mfma_f32_16x16x32_bf16 v[114:117], v[188:191], v[196:199], v[114:117]
	v_mfma_f32_16x16x32_bf16 v[114:117], v[184:187], v[192:195], v[114:117]
	s_setprio 0
	s_add_i32 s80, s80, s55
	v_lshl_add_u64 v[226:227], v[170:171], 0, s[30:31]
	s_mov_b32 m0, s80
	ds_read_b128 v[192:195], v178 offset:49152
	ds_read_b128 v[196:199], v178 offset:50176
	ds_read_b128 v[200:203], v178 offset:51200
	ds_read_b128 v[204:207], v178 offset:52224
	ds_read_b128 v[208:211], v178 offset:53248
	ds_read_b128 v[212:215], v178 offset:54272
	ds_read_b128 v[216:219], v178 offset:55296
	ds_read_b128 v[220:223], v178 offset:56320
	global_load_lds_dwordx4 v[226:227], off
	v_lshl_add_u64 v[226:227], v[170:171], 0, s[34:35]
	s_add_i32 m0, s80, 0x2000
	s_add_i32 s80, s81, s55
	global_load_lds_dwordx4 v[226:227], off
	v_lshl_add_u64 v[226:227], v[170:171], 0, s[36:37]
	s_mov_b32 m0, s80
	v_lshl_add_u64 v[170:171], v[170:171], 0, s[38:39]
	global_load_lds_dwordx4 v[226:227], off
	s_add_i32 m0, s80, 0x2000
	s_nop 0
	global_load_lds_dwordx4 v[170:171], off
	v_lshl_add_u64 v[170:171], v[224:225], 0, s[30:31]
	s_mov_b32 m0, s63
	s_nop 0
	global_load_lds_dwordx4 v[170:171], off
	v_lshl_add_u64 v[170:171], v[224:225], 0, s[34:35]
	s_mov_b32 m0, s73
	s_nop 0
	global_load_lds_dwordx4 v[170:171], off
	s_waitcnt vmcnt(8)
	s_waitcnt lgkmcnt(0)
	s_barrier
	s_setprio 1
	v_mfma_f32_16x16x32_bf16 v[62:65], v[130:133], v[192:195], v[62:65]
	v_mfma_f32_16x16x32_bf16 v[62:65], v[134:137], v[196:199], v[62:65]
	v_mfma_f32_16x16x32_bf16 v[46:49], v[134:137], v[204:207], v[46:49]
	v_mfma_f32_16x16x32_bf16 v[46:49], v[130:133], v[200:203], v[46:49]
	v_mfma_f32_16x16x32_bf16 v[30:33], v[130:133], v[208:211], v[30:33]
	v_mfma_f32_16x16x32_bf16 v[30:33], v[134:137], v[212:215], v[30:33]
	v_mfma_f32_16x16x32_bf16 v[14:17], v[134:137], v[220:223], v[14:17]
	v_mfma_f32_16x16x32_bf16 v[14:17], v[130:133], v[216:219], v[14:17]
	v_mfma_f32_16x16x32_bf16 v[10:13], v[154:157], v[216:219], v[10:13]
	v_mfma_f32_16x16x32_bf16 v[10:13], v[158:161], v[220:223], v[10:13]
	v_mfma_f32_16x16x32_bf16 v[26:29], v[158:161], v[212:215], v[26:29]
	v_mfma_f32_16x16x32_bf16 v[26:29], v[154:157], v[208:211], v[26:29]
	v_mfma_f32_16x16x32_bf16 v[42:45], v[154:157], v[200:203], v[42:45]
	v_mfma_f32_16x16x32_bf16 v[42:45], v[158:161], v[204:207], v[42:45]
	v_mfma_f32_16x16x32_bf16 v[58:61], v[158:161], v[196:199], v[58:61]
	v_mfma_f32_16x16x32_bf16 v[58:61], v[154:157], v[192:195], v[58:61]
	v_mfma_f32_16x16x32_bf16 v[54:57], v[162:165], v[192:195], v[54:57]
	v_mfma_f32_16x16x32_bf16 v[54:57], v[166:169], v[196:199], v[54:57]
	v_mfma_f32_16x16x32_bf16 v[38:41], v[166:169], v[204:207], v[38:41]
	v_mfma_f32_16x16x32_bf16 v[38:41], v[162:165], v[200:203], v[38:41]
	v_mfma_f32_16x16x32_bf16 v[22:25], v[162:165], v[208:211], v[22:25]
	v_mfma_f32_16x16x32_bf16 v[22:25], v[166:169], v[212:215], v[22:25]
	v_mfma_f32_16x16x32_bf16 v[6:9], v[166:169], v[220:223], v[6:9]
	v_mfma_f32_16x16x32_bf16 v[6:9], v[162:165], v[216:219], v[6:9]
	v_mfma_f32_16x16x32_bf16 v[2:5], v[184:187], v[216:219], v[2:5]
	v_mfma_f32_16x16x32_bf16 v[2:5], v[188:191], v[220:223], v[2:5]
	v_mfma_f32_16x16x32_bf16 v[18:21], v[188:191], v[212:215], v[18:21]
	v_mfma_f32_16x16x32_bf16 v[18:21], v[184:187], v[208:211], v[18:21]
	s_barrier
	s_setprio 2
	v_mfma_f32_16x16x32_bf16 v[34:37], v[184:187], v[200:203], v[34:37]
	v_mfma_f32_16x16x32_bf16 v[34:37], v[188:191], v[204:207], v[34:37]
	v_mfma_f32_16x16x32_bf16 v[50:53], v[188:191], v[196:199], v[50:53]
	v_mfma_f32_16x16x32_bf16 v[50:53], v[184:187], v[192:195], v[50:53]
	s_setprio 0
	s_cmp_gt_u32 s94, 29
	s_mov_b32 s94, s26
	s_cbranch_scc1 .LBB0_1669

; #define PG8_STAGE(bufoff, gbase, voff) do { if constexpr (!pg8_noload<Epi>::value) { _Pragma("unroll") for (int _i = 0; _i < 2; ++_i) \
;         __builtin_amdgcn_global_load_lds((const unsigned*)((const char*)(gbase) + (size_t)_i * pstep + (voff)[0]), (PG8_LAS unsigned*)(lds + (bufoff) + ldsw + _i * 8192), 16, 0, 0); } } while (0)
; #define PG8_LDA(dst, b, h) do { _Pragma("unroll") for (int m = 0; m < 4; ++m) _Pragma("unroll") for (int k = 0; k < 2; ++k) dst[m][k] = *(const PG8_LAS bf16x8*)(lds + PG8_SA(b, h) + aoff + m * 2048 + k * 1024); } while (0)
; #define PG8_LDB(dst, b, h) do { _Pragma("unroll") for (int n = 0; n < 2; ++n) _Pragma("unroll") for (int k = 0; k < 2; ++k) dst[n][k] = *(const PG8_LAS bf16x8*)(lds + PG8_SB(b, h) + boff + n * 2048 + k * 1024); } while (0)
; #define PG8_MMA(ai, bj, At, Bt) do { __builtin_amdgcn_s_setprio(1); _Pragma("unroll") for (int m = 0; m < 4; ++m) _Pragma("unroll") for (int n = 0; n < 2; ++n) _Pragma("unroll") for (int k = 0; k < 2; ++k) \
;         acc[ai][bj][m][n] = __builtin_amdgcn_mfma_f32_16x16x32_bf16(Bt[n][k], At[m][k], acc[ai][bj][m][n], 0, 0, 0); __builtin_amdgcn_s_setprio(0); } while (0)
; #define PG8_BAR __builtin_amdgcn_s_barrier()
; template <class Epi, class Sched, bool ALIGN_EPI = false, bool SP2 = false, bool ABLK = false>
; __device__ __forceinline__ void gemm_phase(PG8_LAS unsigned char* lds, const Gemm g, const Sched& S, const Epi& E) {
;     ...
;         for (int t = 0; t < nt; t += 2) {
;             const bool last = (t == nt - 2);
;             const char* a1 = cA + (size_t)(t + 1) * kstep;
;             const char* a2 = last ? nA : cA + (size_t)(t + 2) * kstep; const char* b2 = last ? nB : cB + (size_t)(t + 2) * kstepB;
;             const char* a3 = a2 + kstep; const char* b3 = b2 + kstepB;
;             if (last && has_next) S.a_ready(nxt);
;             if constexpr (SP2) {
;             PG8_LDB(B0, 0, 0); PG8_LDB(B1, 0, 1); PG8_SCHED; PG8_LDA(At, 0, 0); PG8_STAGE(PG8_SA(1, 1), a1 + hstep, voffA);
;             PG8_WAIT_V(8); PG8_WAIT_L(0); PG8_BAR; PG8_MMA(0, 0, At, B0); PG8_MMA(0, 1, At, B1); PG8_BAR; PG8_SCHED;
;             PG8_LDA(At, 0, 1); PG8_STAGE(PG8_SB(0, 0), b2, voffB); PG8_STAGE(PG8_SB(0, 1), b2 + hstep, voffB); PG8_STAGE(PG8_SA(0, 0), a2, voffA);
;             PG8_WAIT_V(8); PG8_WAIT_L(0); PG8_BAR; PG8_MMA(1, 0, At, B0); PG8_MMA(1, 1, At, B1); PG8_BAR; PG8_SCHED;
.LBB0_1997:
	ds_read_b128 v[130:133], v175
	ds_read_b128 v[134:137], v175 offset:1024
	ds_read_b128 v[138:141], v175 offset:2048
	ds_read_b128 v[142:145], v175 offset:3072
	ds_read_b128 v[146:149], v176
	ds_read_b128 v[150:153], v176 offset:1024
	ds_read_b128 v[154:157], v176 offset:2048
	ds_read_b128 v[158:161], v176 offset:3072
	s_add_i32 s43, s41, 2
	s_add_u32 s62, s52, 0xfff80800
	s_addc_u32 s63, s53, -1
	s_cmp_eq_u32 s3, s41
	s_cselect_b32 s63, s45, s63
	s_cselect_b32 s62, s44, s62
	s_cselect_b32 s77, s47, s39
	s_cselect_b32 s76, s46, s11
	v_lshl_add_u64 v[170:171], s[52:53], 0, v[166:167]
	s_add_i32 m0, s49, 0xc000
	ds_read_b128 v[184:187], v177
	ds_read_b128 v[188:191], v177 offset:1024
	ds_read_b128 v[192:195], v177 offset:2048
	ds_read_b128 v[196:199], v177 offset:3072
	ds_read_b128 v[200:203], v177 offset:4096
	ds_read_b128 v[204:207], v177 offset:5120
	ds_read_b128 v[208:211], v177 offset:6144
	ds_read_b128 v[212:215], v177 offset:7168
	global_load_lds_dwordx4 v[170:171], off
	v_lshl_add_u64 v[170:171], v[170:171], 0, s[12:13]
	s_add_i32 m0, s49, 0xe000
	s_nop 0
	global_load_lds_dwordx4 v[170:171], off
	s_waitcnt vmcnt(8)
	s_waitcnt lgkmcnt(0)
	s_barrier
	s_setprio 1
	v_mfma_f32_16x16x32_bf16 v[126:129], v[130:133], v[184:187], v[126:129]
	v_mfma_f32_16x16x32_bf16 v[126:129], v[134:137], v[188:191], v[126:129]
	v_mfma_f32_16x16x32_bf16 v[110:113], v[134:137], v[196:199], v[110:113]
	v_mfma_f32_16x16x32_bf16 v[110:113], v[130:133], v[192:195], v[110:113]
	v_mfma_f32_16x16x32_bf16 v[94:97], v[130:133], v[200:203], v[94:97]
	v_mfma_f32_16x16x32_bf16 v[94:97], v[134:137], v[204:207], v[94:97]
	v_mfma_f32_16x16x32_bf16 v[78:81], v[134:137], v[212:215], v[78:81]
	v_mfma_f32_16x16x32_bf16 v[78:81], v[130:133], v[208:211], v[78:81]
	v_mfma_f32_16x16x32_bf16 v[74:77], v[138:141], v[208:211], v[74:77]
	v_mfma_f32_16x16x32_bf16 v[74:77], v[142:145], v[212:215], v[74:77]
	v_mfma_f32_16x16x32_bf16 v[90:93], v[142:145], v[204:207], v[90:93]
	v_mfma_f32_16x16x32_bf16 v[90:93], v[138:141], v[200:203], v[90:93]
	v_mfma_f32_16x16x32_bf16 v[106:109], v[138:141], v[192:195], v[106:109]
	v_mfma_f32_16x16x32_bf16 v[106:109], v[142:145], v[196:199], v[106:109]
	v_mfma_f32_16x16x32_bf16 v[122:125], v[142:145], v[188:191], v[122:125]
	v_mfma_f32_16x16x32_bf16 v[122:125], v[138:141], v[184:187], v[122:125]
	v_mfma_f32_16x16x32_bf16 v[118:121], v[146:149], v[184:187], v[118:121]
	v_mfma_f32_16x16x32_bf16 v[118:121], v[150:153], v[188:191], v[118:121]
	v_mfma_f32_16x16x32_bf16 v[102:105], v[150:153], v[196:199], v[102:105]
	v_mfma_f32_16x16x32_bf16 v[102:105], v[146:149], v[192:195], v[102:105]
	v_mfma_f32_16x16x32_bf16 v[86:89], v[146:149], v[200:203], v[86:89]
	v_mfma_f32_16x16x32_bf16 v[86:89], v[150:153], v[204:207], v[86:89]
	v_mfma_f32_16x16x32_bf16 v[70:73], v[150:153], v[212:215], v[70:73]
	v_mfma_f32_16x16x32_bf16 v[70:73], v[146:149], v[208:211], v[70:73]
	v_mfma_f32_16x16x32_bf16 v[66:69], v[154:157], v[208:211], v[66:69]
	v_mfma_f32_16x16x32_bf16 v[66:69], v[158:161], v[212:215], v[66:69]
	v_mfma_f32_16x16x32_bf16 v[82:85], v[158:161], v[204:207], v[82:85]
	v_mfma_f32_16x16x32_bf16 v[82:85], v[154:157], v[200:203], v[82:85]
	s_barrier
	s_setprio 2
	v_mfma_f32_16x16x32_bf16 v[98:101], v[154:157], v[192:195], v[98:101]
	v_mfma_f32_16x16x32_bf16 v[98:101], v[158:161], v[196:199], v[98:101]
	v_mfma_f32_16x16x32_bf16 v[114:117], v[158:161], v[188:191], v[114:117]
	v_mfma_f32_16x16x32_bf16 v[114:117], v[154:157], v[184:187], v[114:117]
	s_setprio 0
	s_add_i32 s41, s70, s57
	v_lshl_add_u64 v[170:171], s[76:77], 0, v[162:163]
	s_mov_b32 m0, s41
	ds_read_b128 v[184:187], v177 offset:16384
	ds_read_b128 v[188:191], v177 offset:17408
	ds_read_b128 v[192:195], v177 offset:18432
	ds_read_b128 v[196:199], v177 offset:19456
	ds_read_b128 v[200:203], v177 offset:20480
	ds_read_b128 v[204:207], v177 offset:21504
	ds_read_b128 v[208:211], v177 offset:22528
	ds_read_b128 v[212:215], v177 offset:23552
	global_load_lds_dwordx4 v[170:171], off
	v_lshl_add_u64 v[216:217], v[170:171], 0, s[12:13]
	s_add_i32 m0, s41, 0x2000
	s_add_i32 s41, s71, s57
	global_load_lds_dwordx4 v[216:217], off
	v_lshl_add_u64 v[216:217], v[170:171], 0, s[14:15]
	s_mov_b32 m0, s41
	s_nop 0
	global_load_lds_dwordx4 v[216:217], off
	v_lshl_add_u64 v[216:217], v[170:171], 0, s[16:17]
	s_add_i32 m0, s41, 0x2000
	s_nop 0
	global_load_lds_dwordx4 v[216:217], off
	v_lshl_add_u64 v[216:217], s[62:63], 0, v[162:163]
	s_mov_b32 m0, s49
	v_lshl_add_u64 v[218:219], v[216:217], 0, s[12:13]
	global_load_lds_dwordx4 v[216:217], off
	s_mov_b32 m0, s58
	s_nop 0
	global_load_lds_dwordx4 v[218:219], off
	s_waitcnt vmcnt(8)
	s_waitcnt lgkmcnt(0)
	s_barrier
; #define PG8_STAGE(bufoff, gbase, voff) do { if constexpr (!pg8_noload<Epi>::value) { _Pragma("unroll") for (int _i = 0; _i < 2; ++_i) \
;         __builtin_amdgcn_global_load_lds((const unsigned*)((const char*)(gbase) + (size_t)_i * pstep + (voff)[0]), (PG8_LAS unsigned*)(lds + (bufoff) + ldsw + _i * 8192), 16, 0, 0); } } while (0)
; #define PG8_LDA(dst, b, h) do { _Pragma("unroll") for (int m = 0; m < 4; ++m) _Pragma("unroll") for (int k = 0; k < 2; ++k) dst[m][k] = *(const PG8_LAS bf16x8*)(lds + PG8_SA(b, h) + aoff + m * 2048 + k * 1024); } while (0)
; #define PG8_LDB(dst, b, h) do { _Pragma("unroll") for (int n = 0; n < 2; ++n) _Pragma("unroll") for (int k = 0; k < 2; ++k) dst[n][k] = *(const PG8_LAS bf16x8*)(lds + PG8_SB(b, h) + boff + n * 2048 + k * 1024); } while (0)
; #define PG8_MMA(ai, bj, At, Bt) do { __builtin_amdgcn_s_setprio(1); _Pragma("unroll") for (int m = 0; m < 4; ++m) _Pragma("unroll") for (int n = 0; n < 2; ++n) _Pragma("unroll") for (int k = 0; k < 2; ++k) \
;         acc[ai][bj][m][n] = __builtin_amdgcn_mfma_f32_16x16x32_bf16(Bt[n][k], At[m][k], acc[ai][bj][m][n], 0, 0, 0); __builtin_amdgcn_s_setprio(0); } while (0)
; #define PG8_WAIT_V(n) asm volatile("s_waitcnt vmcnt(" #n ")" ::: "memory")
; #define PG8_WAIT_L(n) asm volatile("s_waitcnt lgkmcnt(" #n ")" ::: "memory")
; #define PG8_BAR __builtin_amdgcn_s_barrier()
; #define PG8_SCHED __builtin_amdgcn_sched_barrier(0)
; template <class Epi, class Sched, bool ALIGN_EPI = false, bool SP2 = false, bool ABLK = false>
; __device__ __forceinline__ void gemm_phase(PG8_LAS unsigned char* lds, const Gemm g, const Sched& S, const Epi& E) {
;     ...
;             PG8_WAIT_V(8); PG8_WAIT_L(0); PG8_BAR; PG8_MMA(1, 0, At, B0); PG8_MMA(1, 1, At, B1); PG8_BAR; PG8_SCHED;
;             PG8_LDB(B0, 1, 0); PG8_LDB(B1, 1, 1); PG8_SCHED; PG8_LDA(At, 1, 0); PG8_STAGE(PG8_SA(0, 1), a2 + hstep, voffA);
;             PG8_WAIT_V(8); PG8_WAIT_L(0); PG8_BAR; PG8_MMA(0, 0, At, B0); PG8_MMA(0, 1, At, B1); PG8_BAR; PG8_SCHED;
	s_setprio 1
	v_mfma_f32_16x16x32_bf16 v[62:65], v[130:133], v[184:187], v[62:65]
	v_mfma_f32_16x16x32_bf16 v[62:65], v[134:137], v[188:191], v[62:65]
	v_mfma_f32_16x16x32_bf16 v[46:49], v[134:137], v[196:199], v[46:49]
	v_mfma_f32_16x16x32_bf16 v[46:49], v[130:133], v[192:195], v[46:49]
	v_mfma_f32_16x16x32_bf16 v[30:33], v[130:133], v[200:203], v[30:33]
	v_mfma_f32_16x16x32_bf16 v[30:33], v[134:137], v[204:207], v[30:33]
	v_mfma_f32_16x16x32_bf16 v[14:17], v[134:137], v[212:215], v[14:17]
	v_mfma_f32_16x16x32_bf16 v[14:17], v[130:133], v[208:211], v[14:17]
	v_mfma_f32_16x16x32_bf16 v[10:13], v[138:141], v[208:211], v[10:13]
	v_mfma_f32_16x16x32_bf16 v[10:13], v[142:145], v[212:215], v[10:13]
	v_mfma_f32_16x16x32_bf16 v[26:29], v[142:145], v[204:207], v[26:29]
	v_mfma_f32_16x16x32_bf16 v[26:29], v[138:141], v[200:203], v[26:29]
	v_mfma_f32_16x16x32_bf16 v[42:45], v[138:141], v[192:195], v[42:45]
	v_mfma_f32_16x16x32_bf16 v[42:45], v[142:145], v[196:199], v[42:45]
	v_mfma_f32_16x16x32_bf16 v[58:61], v[142:145], v[188:191], v[58:61]
	v_mfma_f32_16x16x32_bf16 v[58:61], v[138:141], v[184:187], v[58:61]
	v_mfma_f32_16x16x32_bf16 v[54:57], v[146:149], v[184:187], v[54:57]
	v_mfma_f32_16x16x32_bf16 v[54:57], v[150:153], v[188:191], v[54:57]
	v_mfma_f32_16x16x32_bf16 v[38:41], v[150:153], v[196:199], v[38:41]
	v_mfma_f32_16x16x32_bf16 v[38:41], v[146:149], v[192:195], v[38:41]
	v_mfma_f32_16x16x32_bf16 v[22:25], v[146:149], v[200:203], v[22:25]
	v_mfma_f32_16x16x32_bf16 v[22:25], v[150:153], v[204:207], v[22:25]
	v_mfma_f32_16x16x32_bf16 v[6:9], v[150:153], v[212:215], v[6:9]
	v_mfma_f32_16x16x32_bf16 v[6:9], v[146:149], v[208:211], v[6:9]
	v_mfma_f32_16x16x32_bf16 v[2:5], v[154:157], v[208:211], v[2:5]
	v_mfma_f32_16x16x32_bf16 v[2:5], v[158:161], v[212:215], v[2:5]
	v_mfma_f32_16x16x32_bf16 v[18:21], v[158:161], v[204:207], v[18:21]
	v_mfma_f32_16x16x32_bf16 v[18:21], v[154:157], v[200:203], v[18:21]
	s_barrier
	s_setprio 2
	v_mfma_f32_16x16x32_bf16 v[34:37], v[154:157], v[192:195], v[34:37]
	v_mfma_f32_16x16x32_bf16 v[34:37], v[158:161], v[196:199], v[34:37]
	v_mfma_f32_16x16x32_bf16 v[50:53], v[158:161], v[188:191], v[50:53]
	v_mfma_f32_16x16x32_bf16 v[50:53], v[154:157], v[184:187], v[50:53]
	s_setprio 0
	s_add_i32 s41, 0, 0x18000
	s_add_i32 s62, 0, 0x1c000
	v_add_u32_e32 v142, s41, v1
	v_add_u32_e32 v158, s62, v1
	ds_read_b128 v[130:133], v142
	ds_read_b128 v[134:137], v142 offset:1024
	ds_read_b128 v[138:141], v142 offset:2048
	ds_read_b128 v[142:145], v142 offset:3072
	ds_read_b128 v[146:149], v158
	ds_read_b128 v[150:153], v158 offset:1024
	ds_read_b128 v[154:157], v158 offset:2048
	ds_read_b128 v[158:161], v158 offset:3072
	s_mov_b32 m0, s59
	v_lshl_add_u64 v[218:219], v[216:217], 0, s[14:15]
	ds_read_b128 v[184:187], v177 offset:32768
	ds_read_b128 v[188:191], v177 offset:33792
	ds_read_b128 v[192:195], v177 offset:34816
	ds_read_b128 v[196:199], v177 offset:35840
	ds_read_b128 v[200:203], v177 offset:36864
	ds_read_b128 v[204:207], v177 offset:37888
	ds_read_b128 v[208:211], v177 offset:38912
	ds_read_b128 v[212:215], v177 offset:39936
	global_load_lds_dwordx4 v[218:219], off
	v_lshl_add_u64 v[218:219], v[216:217], 0, s[16:17]
	s_mov_b32 m0, s60
	s_nop 0
	global_load_lds_dwordx4 v[218:219], off
	s_waitcnt vmcnt(8)
	s_waitcnt lgkmcnt(0)
	s_barrier
	s_setprio 1
	v_mfma_f32_16x16x32_bf16 v[126:129], v[130:133], v[184:187], v[126:129]
	v_mfma_f32_16x16x32_bf16 v[126:129], v[134:137], v[188:191], v[126:129]
	v_mfma_f32_16x16x32_bf16 v[110:113], v[134:137], v[196:199], v[110:113]
	v_mfma_f32_16x16x32_bf16 v[110:113], v[130:133], v[192:195], v[110:113]
	v_mfma_f32_16x16x32_bf16 v[94:97], v[130:133], v[200:203], v[94:97]
	v_mfma_f32_16x16x32_bf16 v[94:97], v[134:137], v[204:207], v[94:97]
	v_mfma_f32_16x16x32_bf16 v[78:81], v[134:137], v[212:215], v[78:81]
	v_mfma_f32_16x16x32_bf16 v[78:81], v[130:133], v[208:211], v[78:81]
	v_mfma_f32_16x16x32_bf16 v[74:77], v[138:141], v[208:211], v[74:77]
	v_mfma_f32_16x16x32_bf16 v[74:77], v[142:145], v[212:215], v[74:77]
	v_mfma_f32_16x16x32_bf16 v[90:93], v[142:145], v[204:207], v[90:93]
	v_mfma_f32_16x16x32_bf16 v[90:93], v[138:141], v[200:203], v[90:93]
	v_mfma_f32_16x16x32_bf16 v[106:109], v[138:141], v[192:195], v[106:109]
	v_mfma_f32_16x16x32_bf16 v[106:109], v[142:145], v[196:199], v[106:109]
	v_mfma_f32_16x16x32_bf16 v[122:125], v[142:145], v[188:191], v[122:125]
	v_mfma_f32_16x16x32_bf16 v[122:125], v[138:141], v[184:187], v[122:125]
	v_mfma_f32_16x16x32_bf16 v[118:121], v[146:149], v[184:187], v[118:121]
	v_mfma_f32_16x16x32_bf16 v[118:121], v[150:153], v[188:191], v[118:121]
	v_mfma_f32_16x16x32_bf16 v[102:105], v[150:153], v[196:199], v[102:105]
	v_mfma_f32_16x16x32_bf16 v[102:105], v[146:149], v[192:195], v[102:105]
	v_mfma_f32_16x16x32_bf16 v[86:89], v[146:149], v[200:203], v[86:89]
	v_mfma_f32_16x16x32_bf16 v[86:89], v[150:153], v[204:207], v[86:89]
	v_mfma_f32_16x16x32_bf16 v[70:73], v[150:153], v[212:215], v[70:73]
	v_mfma_f32_16x16x32_bf16 v[70:73], v[146:149], v[208:211], v[70:73]
	v_mfma_f32_16x16x32_bf16 v[66:69], v[154:157], v[208:211], v[66:69]
	v_mfma_f32_16x16x32_bf16 v[66:69], v[158:161], v[212:215], v[66:69]
	v_mfma_f32_16x16x32_bf16 v[82:85], v[158:161], v[204:207], v[82:85]
	v_mfma_f32_16x16x32_bf16 v[82:85], v[154:157], v[200:203], v[82:85]
	s_barrier
; #define PG8_LDA(dst, b, h) do { _Pragma("unroll") for (int m = 0; m < 4; ++m) _Pragma("unroll") for (int k = 0; k < 2; ++k) dst[m][k] = *(const PG8_LAS bf16x8*)(lds + PG8_SA(b, h) + aoff + m * 2048 + k * 1024); } while (0)
; #define PG8_WAIT_V(n) asm volatile("s_waitcnt vmcnt(" #n ")" ::: "memory")
; template <class Epi, class Sched, bool ALIGN_EPI = false, bool SP2 = false, bool ABLK = false>
; __device__ __forceinline__ void gemm_phase(PG8_LAS unsigned char* lds, const Gemm g, const Sched& S, const Epi& E) {
;     ...
;             PG8_WAIT_V(8); PG8_WAIT_L(0); PG8_BAR; PG8_MMA(0, 0, At, B0); PG8_MMA(0, 1, At, B1); PG8_BAR; PG8_SCHED;
;             PG8_LDA(At, 1, 1); PG8_STAGE(PG8_SB(1, 0), b3, voffB); PG8_STAGE(PG8_SB(1, 1), b3 + hstep, voffB); PG8_STAGE(PG8_SA(1, 0), a3, voffA);
;             PG8_WAIT_V(8); PG8_WAIT_L(0); PG8_BAR; PG8_MMA(1, 0, At, B0); PG8_MMA(1, 1, At, B1); PG8_BAR; PG8_SCHED;
;             } else {
;             PG8_LDB(B0, 0, 0); PG8_SCHED; PG8_LDA(At, 0, 0); PG8_STAGE(PG8_SA(1, 1), a1 + hstep, voffA);
;             PG8_WAIT_L(8); PG8_BAR; PG8_WAIT_L(0); PG8_MMA(0, 0, At, B0); PG8_BAR; PG8_SCHED;
;             PG8_LDB(B1, 0, 1); PG8_STAGE(PG8_SB(0, 0), b2, voffB);
;             PG8_BAR; PG8_WAIT_L(0); PG8_MMA(0, 1, At, B1); PG8_BAR;
;             PG8_LDA(At, 0, 1); PG8_STAGE(PG8_SA(0, 0), a2, voffA);
;             PG8_BAR; PG8_WAIT_L(0); PG8_MMA(1, 0, At, B0); PG8_BAR; PG8_SCHED;
;             PG8_STAGE(PG8_SB(0, 1), b2 + hstep, voffB);
;             PG8_WAIT_V(6); PG8_BAR; PG8_MMA(1, 1, At, B1); PG8_BAR;
;             PG8_LDB(B0, 1, 0); PG8_SCHED; PG8_LDA(At, 1, 0); PG8_STAGE(PG8_SA(0, 1), a2 + hstep, voffA);
;             PG8_WAIT_L(8); PG8_BAR; PG8_WAIT_L(0); PG8_MMA(0, 0, At, B0); PG8_BAR; PG8_SCHED;
;             PG8_LDB(B1, 1, 1); PG8_STAGE(PG8_SB(1, 0), b3, voffB);
;             PG8_BAR; PG8_WAIT_L(0); PG8_MMA(0, 1, At, B1); PG8_BAR;
;             PG8_LDA(At, 1, 1); PG8_STAGE(PG8_SA(1, 0), a3, voffA);
;             PG8_BAR; PG8_WAIT_L(0); PG8_MMA(1, 0, At, B0); PG8_BAR; PG8_SCHED;
;             PG8_STAGE(PG8_SB(1, 1), b3 + hstep, voffB);
;             PG8_WAIT_V(6); PG8_BAR; PG8_MMA(1, 1, At, B1); PG8_BAR;
;             }
;         }
;         if constexpr (ALIGN_EPI) { if (wr == 0) PG8_BAR; }
;         if constexpr (!Epi::AFTER_DRAIN) { E(acc, cur, wr, wc, fr, fq); S.done(cur); }
;         if (!has_next) break;
	s_setprio 2
	v_mfma_f32_16x16x32_bf16 v[98:101], v[154:157], v[192:195], v[98:101]
	v_mfma_f32_16x16x32_bf16 v[98:101], v[158:161], v[196:199], v[98:101]
	v_mfma_f32_16x16x32_bf16 v[114:117], v[158:161], v[188:191], v[114:117]
	v_mfma_f32_16x16x32_bf16 v[114:117], v[154:157], v[184:187], v[114:117]
	s_setprio 0
	s_add_i32 s41, s41, s57
	v_lshl_add_u64 v[218:219], v[170:171], 0, s[24:25]
	s_mov_b32 m0, s41
	ds_read_b128 v[184:187], v177 offset:49152
	ds_read_b128 v[188:191], v177 offset:50176
	ds_read_b128 v[192:195], v177 offset:51200
	ds_read_b128 v[196:199], v177 offset:52224
	ds_read_b128 v[200:203], v177 offset:53248
	ds_read_b128 v[204:207], v177 offset:54272
	ds_read_b128 v[208:211], v177 offset:55296
	ds_read_b128 v[212:215], v177 offset:56320
	global_load_lds_dwordx4 v[218:219], off
	v_lshl_add_u64 v[218:219], v[170:171], 0, s[26:27]
	s_add_i32 m0, s41, 0x2000
	s_add_i32 s41, s62, s57
	global_load_lds_dwordx4 v[218:219], off
	v_lshl_add_u64 v[218:219], v[170:171], 0, s[28:29]
	s_mov_b32 m0, s41
	v_lshl_add_u64 v[170:171], v[170:171], 0, s[30:31]
	global_load_lds_dwordx4 v[218:219], off
	s_add_i32 m0, s41, 0x2000
	s_nop 0
	global_load_lds_dwordx4 v[170:171], off
	v_lshl_add_u64 v[170:171], v[216:217], 0, s[24:25]
	s_mov_b32 m0, s65
	s_nop 0
	global_load_lds_dwordx4 v[170:171], off
	v_lshl_add_u64 v[170:171], v[216:217], 0, s[26:27]
	s_mov_b32 m0, s66
	s_nop 0
	global_load_lds_dwordx4 v[170:171], off
	s_waitcnt vmcnt(8)
	s_waitcnt lgkmcnt(0)
	s_barrier
	s_setprio 1
	v_mfma_f32_16x16x32_bf16 v[62:65], v[130:133], v[184:187], v[62:65]
	v_mfma_f32_16x16x32_bf16 v[62:65], v[134:137], v[188:191], v[62:65]
	v_mfma_f32_16x16x32_bf16 v[46:49], v[134:137], v[196:199], v[46:49]
	v_mfma_f32_16x16x32_bf16 v[46:49], v[130:133], v[192:195], v[46:49]
	v_mfma_f32_16x16x32_bf16 v[30:33], v[130:133], v[200:203], v[30:33]
	v_mfma_f32_16x16x32_bf16 v[30:33], v[134:137], v[204:207], v[30:33]
	v_mfma_f32_16x16x32_bf16 v[14:17], v[134:137], v[212:215], v[14:17]
	v_mfma_f32_16x16x32_bf16 v[14:17], v[130:133], v[208:211], v[14:17]
	v_mfma_f32_16x16x32_bf16 v[10:13], v[138:141], v[208:211], v[10:13]
	v_mfma_f32_16x16x32_bf16 v[10:13], v[142:145], v[212:215], v[10:13]
	v_mfma_f32_16x16x32_bf16 v[26:29], v[142:145], v[204:207], v[26:29]
	v_mfma_f32_16x16x32_bf16 v[26:29], v[138:141], v[200:203], v[26:29]
	v_mfma_f32_16x16x32_bf16 v[42:45], v[138:141], v[192:195], v[42:45]
	v_mfma_f32_16x16x32_bf16 v[42:45], v[142:145], v[196:199], v[42:45]
	v_mfma_f32_16x16x32_bf16 v[58:61], v[142:145], v[188:191], v[58:61]
	v_mfma_f32_16x16x32_bf16 v[58:61], v[138:141], v[184:187], v[58:61]
	v_mfma_f32_16x16x32_bf16 v[54:57], v[146:149], v[184:187], v[54:57]
	v_mfma_f32_16x16x32_bf16 v[54:57], v[150:153], v[188:191], v[54:57]
	v_mfma_f32_16x16x32_bf16 v[38:41], v[150:153], v[196:199], v[38:41]
	v_mfma_f32_16x16x32_bf16 v[38:41], v[146:149], v[192:195], v[38:41]
	v_mfma_f32_16x16x32_bf16 v[22:25], v[146:149], v[200:203], v[22:25]
	v_mfma_f32_16x16x32_bf16 v[22:25], v[150:153], v[204:207], v[22:25]
	v_mfma_f32_16x16x32_bf16 v[6:9], v[150:153], v[212:215], v[6:9]
	v_mfma_f32_16x16x32_bf16 v[6:9], v[146:149], v[208:211], v[6:9]
	v_mfma_f32_16x16x32_bf16 v[2:5], v[154:157], v[208:211], v[2:5]
	v_mfma_f32_16x16x32_bf16 v[2:5], v[158:161], v[212:215], v[2:5]
	v_mfma_f32_16x16x32_bf16 v[18:21], v[158:161], v[204:207], v[18:21]
	v_mfma_f32_16x16x32_bf16 v[18:21], v[154:157], v[200:203], v[18:21]
	s_barrier
	s_setprio 2
	v_mfma_f32_16x16x32_bf16 v[34:37], v[154:157], v[192:195], v[34:37]
	v_mfma_f32_16x16x32_bf16 v[34:37], v[158:161], v[196:199], v[34:37]
	v_mfma_f32_16x16x32_bf16 v[50:53], v[158:161], v[188:191], v[50:53]
	v_mfma_f32_16x16x32_bf16 v[50:53], v[154:157], v[184:187], v[50:53]
	s_setprio 0
	s_add_u32 s52, s52, 0x1000
	s_addc_u32 s53, s53, 0
	s_add_u32 s11, s11, 0x1000
	s_addc_u32 s39, s39, 0
	s_cmp_ge_i32 s43, s75
	s_mov_b32 s41, s43
	s_cbranch_scc0 .LBB0_1997
	s_and_b64 vcc, exec, s[34:35]
	s_cbranch_vccnz .LBB0_2002
	s_lshl_b32 s11, s2, 8
	s_cmp_gt_i32 s2, 63
	s_mov_b64 s[52:53], -1
	s_cbranch_scc1 .LBB0_2003

; #define PG8_STAGE(bufoff, gbase, voff) do { if constexpr (!pg8_noload<Epi>::value) { _Pragma("unroll") for (int _i = 0; _i < 2; ++_i) \
;         __builtin_amdgcn_global_load_lds((const unsigned*)((const char*)(gbase) + (size_t)_i * pstep + (voff)[0]), (PG8_LAS unsigned*)(lds + (bufoff) + ldsw + _i * 8192), 16, 0, 0); } } while (0)
; #define PG8_LDA(dst, b, h) do { _Pragma("unroll") for (int m = 0; m < 4; ++m) _Pragma("unroll") for (int k = 0; k < 2; ++k) dst[m][k] = *(const PG8_LAS bf16x8*)(lds + PG8_SA(b, h) + aoff + m * 2048 + k * 1024); } while (0)
; #define PG8_LDB(dst, b, h) do { _Pragma("unroll") for (int n = 0; n < 2; ++n) _Pragma("unroll") for (int k = 0; k < 2; ++k) dst[n][k] = *(const PG8_LAS bf16x8*)(lds + PG8_SB(b, h) + boff + n * 2048 + k * 1024); } while (0)
; #define PG8_MMA(ai, bj, At, Bt) do { __builtin_amdgcn_s_setprio(1); _Pragma("unroll") for (int m = 0; m < 4; ++m) _Pragma("unroll") for (int n = 0; n < 2; ++n) _Pragma("unroll") for (int k = 0; k < 2; ++k) \
;         acc[ai][bj][m][n] = __builtin_amdgcn_mfma_f32_16x16x32_bf16(Bt[n][k], At[m][k], acc[ai][bj][m][n], 0, 0, 0); __builtin_amdgcn_s_setprio(0); } while (0)
; #define PG8_BAR __builtin_amdgcn_s_barrier()
; template <class Epi, class Sched, bool ALIGN_EPI = false, bool SP2 = false, bool ABLK = false>
; __device__ __forceinline__ void gemm_phase(PG8_LAS unsigned char* lds, const Gemm g, const Sched& S, const Epi& E) {
;     ...
;         for (int t = 0; t < nt; t += 2) {
;             const bool last = (t == nt - 2);
;             const char* a1 = cA + (size_t)(t + 1) * kstep;
;             const char* a2 = last ? nA : cA + (size_t)(t + 2) * kstep; const char* b2 = last ? nB : cB + (size_t)(t + 2) * kstepB;
;             const char* a3 = a2 + kstep; const char* b3 = b2 + kstepB;
;             if (last && has_next) S.a_ready(nxt);
;             if constexpr (SP2) {
;             PG8_LDB(B0, 0, 0); PG8_LDB(B1, 0, 1); PG8_SCHED; PG8_LDA(At, 0, 0); PG8_STAGE(PG8_SA(1, 1), a1 + hstep, voffA);
;             PG8_WAIT_V(8); PG8_WAIT_L(0); PG8_BAR; PG8_MMA(0, 0, At, B0); PG8_MMA(0, 1, At, B1); PG8_BAR; PG8_SCHED;
;             PG8_LDA(At, 0, 1); PG8_STAGE(PG8_SB(0, 0), b2, voffB); PG8_STAGE(PG8_SB(0, 1), b2 + hstep, voffB); PG8_STAGE(PG8_SA(0, 0), a2, voffA);
;             PG8_WAIT_V(8); PG8_WAIT_L(0); PG8_BAR; PG8_MMA(1, 0, At, B0); PG8_MMA(1, 1, At, B1); PG8_BAR; PG8_SCHED;
.LBB0_2119:
	s_or_b32 s30, s59, 1
	s_lshl_b64 s[14:15], s[30:31], 11
	s_add_u32 s14, s82, s14
	v_add_u32_e32 v133, s71, v148
	s_addc_u32 s15, s83, s15
	s_add_i32 s30, s59, 2
	ds_read_b128 v[144:147], v133
	ds_read_b128 v[184:187], v133 offset:1024
	ds_read_b128 v[188:191], v133 offset:2048
	ds_read_b128 v[192:195], v133 offset:3072
	v_add_u32_e32 v133, s73, v148
	s_lshl_b64 s[34:35], s[30:31], 11
	ds_read_b128 v[196:199], v133
	ds_read_b128 v[200:203], v133 offset:1024
	ds_read_b128 v[204:207], v133 offset:2048
	ds_read_b128 v[208:211], v133 offset:3072
	s_add_u32 s96, s82, s34
	s_addc_u32 s97, s83, s35
	s_and_b64 s[94:95], s[92:93], exec
	s_cselect_b32 s95, s97, s77
	s_cselect_b32 s94, s96, s28
	s_add_u32 s96, s88, s34
	s_addc_u32 s97, s89, s35
	s_and_b64 s[34:35], s[92:93], exec
	s_cselect_b32 s35, s97, s29
	s_cselect_b32 s34, s96, s75
	v_lshl_add_u64 v[180:181], s[14:15], 0, v[130:131]
	v_lshl_add_u64 v[244:245], v[180:181], 0, s[24:25]
	s_add_i32 m0, s17, 0xc000
	ds_read_b128 v[212:215], v168
	ds_read_b128 v[216:219], v168 offset:1024
	ds_read_b128 v[220:223], v168 offset:2048
	ds_read_b128 v[224:227], v168 offset:3072
	ds_read_b128 v[228:231], v168 offset:4096
	ds_read_b128 v[232:235], v168 offset:5120
	ds_read_b128 v[236:239], v168 offset:6144
	ds_read_b128 v[240:243], v168 offset:7168
	global_load_lds_dwordx4 v[244:245], off
	v_lshl_add_u64 v[180:181], v[180:181], 0, s[26:27]
	s_add_i32 m0, s17, 0xe000
	s_nop 0
	global_load_lds_dwordx4 v[180:181], off
	s_waitcnt vmcnt(8)
	s_waitcnt lgkmcnt(0)
	s_barrier
	s_setprio 1
	v_mfma_f32_16x16x32_bf16 v[126:129], v[144:147], v[212:215], v[126:129]
	v_mfma_f32_16x16x32_bf16 v[126:129], v[184:187], v[216:219], v[126:129]
	v_mfma_f32_16x16x32_bf16 v[110:113], v[184:187], v[224:227], v[110:113]
	v_mfma_f32_16x16x32_bf16 v[110:113], v[144:147], v[220:223], v[110:113]
	v_mfma_f32_16x16x32_bf16 v[94:97], v[144:147], v[228:231], v[94:97]
	v_mfma_f32_16x16x32_bf16 v[94:97], v[184:187], v[232:235], v[94:97]
	v_mfma_f32_16x16x32_bf16 v[78:81], v[184:187], v[240:243], v[78:81]
	v_mfma_f32_16x16x32_bf16 v[78:81], v[144:147], v[236:239], v[78:81]
	v_mfma_f32_16x16x32_bf16 v[74:77], v[188:191], v[236:239], v[74:77]
	v_mfma_f32_16x16x32_bf16 v[74:77], v[192:195], v[240:243], v[74:77]
	v_mfma_f32_16x16x32_bf16 v[90:93], v[192:195], v[232:235], v[90:93]
	v_mfma_f32_16x16x32_bf16 v[90:93], v[188:191], v[228:231], v[90:93]
	v_mfma_f32_16x16x32_bf16 v[106:109], v[188:191], v[220:223], v[106:109]
	v_mfma_f32_16x16x32_bf16 v[106:109], v[192:195], v[224:227], v[106:109]
	v_mfma_f32_16x16x32_bf16 v[122:125], v[192:195], v[216:219], v[122:125]
	v_mfma_f32_16x16x32_bf16 v[122:125], v[188:191], v[212:215], v[122:125]
	v_mfma_f32_16x16x32_bf16 v[118:121], v[196:199], v[212:215], v[118:121]
	v_mfma_f32_16x16x32_bf16 v[118:121], v[200:203], v[216:219], v[118:121]
	v_mfma_f32_16x16x32_bf16 v[102:105], v[200:203], v[224:227], v[102:105]
	v_mfma_f32_16x16x32_bf16 v[102:105], v[196:199], v[220:223], v[102:105]
	v_mfma_f32_16x16x32_bf16 v[86:89], v[196:199], v[228:231], v[86:89]
	v_mfma_f32_16x16x32_bf16 v[86:89], v[200:203], v[232:235], v[86:89]
	v_mfma_f32_16x16x32_bf16 v[70:73], v[200:203], v[240:243], v[70:73]
	v_mfma_f32_16x16x32_bf16 v[70:73], v[196:199], v[236:239], v[70:73]
	v_mfma_f32_16x16x32_bf16 v[66:69], v[204:207], v[236:239], v[66:69]
	v_mfma_f32_16x16x32_bf16 v[66:69], v[208:211], v[240:243], v[66:69]
	v_mfma_f32_16x16x32_bf16 v[82:85], v[208:211], v[232:235], v[82:85]
	v_mfma_f32_16x16x32_bf16 v[82:85], v[204:207], v[228:231], v[82:85]
	s_barrier
	s_setprio 2
	v_mfma_f32_16x16x32_bf16 v[98:101], v[204:207], v[220:223], v[98:101]
	v_mfma_f32_16x16x32_bf16 v[98:101], v[208:211], v[224:227], v[98:101]
	v_mfma_f32_16x16x32_bf16 v[114:117], v[208:211], v[216:219], v[114:117]
	v_mfma_f32_16x16x32_bf16 v[114:117], v[204:207], v[212:215], v[114:117]
	s_setprio 0
	s_add_i32 s14, s71, s3
	v_lshl_add_u64 v[180:181], s[34:35], 0, v[130:131]
	s_mov_b32 m0, s14
	ds_read_b128 v[212:215], v168 offset:16384
	ds_read_b128 v[216:219], v168 offset:17408
	ds_read_b128 v[220:223], v168 offset:18432
	ds_read_b128 v[224:227], v168 offset:19456
	ds_read_b128 v[228:231], v168 offset:20480
	ds_read_b128 v[232:235], v168 offset:21504
	ds_read_b128 v[236:239], v168 offset:22528
	ds_read_b128 v[240:243], v168 offset:23552
	global_load_lds_dwordx4 v[180:181], off
	v_lshl_add_u64 v[244:245], v[180:181], 0, s[22:23]
	s_add_i32 m0, s14, 0x2000
	s_add_i32 s14, s73, s3
	global_load_lds_dwordx4 v[244:245], off
	v_lshl_add_u64 v[244:245], v[180:181], 0, s[24:25]
	s_mov_b32 m0, s14
	s_nop 0
	global_load_lds_dwordx4 v[244:245], off
	v_lshl_add_u64 v[244:245], v[180:181], 0, s[26:27]
	s_add_i32 m0, s14, 0x2000
	s_nop 0
	global_load_lds_dwordx4 v[244:245], off
	v_lshl_add_u64 v[244:245], s[94:95], 0, v[130:131]
	s_mov_b32 m0, s17
	v_lshl_add_u64 v[246:247], v[244:245], 0, s[22:23]
	global_load_lds_dwordx4 v[244:245], off
	s_mov_b32 m0, s56
	s_nop 0
	global_load_lds_dwordx4 v[246:247], off
	s_waitcnt vmcnt(8)
	s_waitcnt lgkmcnt(0)
	s_barrier
; #define PG8_STAGE(bufoff, gbase, voff) do { if constexpr (!pg8_noload<Epi>::value) { _Pragma("unroll") for (int _i = 0; _i < 2; ++_i) \
;         __builtin_amdgcn_global_load_lds((const unsigned*)((const char*)(gbase) + (size_t)_i * pstep + (voff)[0]), (PG8_LAS unsigned*)(lds + (bufoff) + ldsw + _i * 8192), 16, 0, 0); } } while (0)
; #define PG8_LDA(dst, b, h) do { _Pragma("unroll") for (int m = 0; m < 4; ++m) _Pragma("unroll") for (int k = 0; k < 2; ++k) dst[m][k] = *(const PG8_LAS bf16x8*)(lds + PG8_SA(b, h) + aoff + m * 2048 + k * 1024); } while (0)
; #define PG8_LDB(dst, b, h) do { _Pragma("unroll") for (int n = 0; n < 2; ++n) _Pragma("unroll") for (int k = 0; k < 2; ++k) dst[n][k] = *(const PG8_LAS bf16x8*)(lds + PG8_SB(b, h) + boff + n * 2048 + k * 1024); } while (0)
; #define PG8_MMA(ai, bj, At, Bt) do { __builtin_amdgcn_s_setprio(1); _Pragma("unroll") for (int m = 0; m < 4; ++m) _Pragma("unroll") for (int n = 0; n < 2; ++n) _Pragma("unroll") for (int k = 0; k < 2; ++k) \
;         acc[ai][bj][m][n] = __builtin_amdgcn_mfma_f32_16x16x32_bf16(Bt[n][k], At[m][k], acc[ai][bj][m][n], 0, 0, 0); __builtin_amdgcn_s_setprio(0); } while (0)
; #define PG8_WAIT_V(n) asm volatile("s_waitcnt vmcnt(" #n ")" ::: "memory")
; #define PG8_WAIT_L(n) asm volatile("s_waitcnt lgkmcnt(" #n ")" ::: "memory")
; #define PG8_BAR __builtin_amdgcn_s_barrier()
; #define PG8_SCHED __builtin_amdgcn_sched_barrier(0)
; template <class Epi, class Sched, bool ALIGN_EPI = false, bool SP2 = false, bool ABLK = false>
; __device__ __forceinline__ void gemm_phase(PG8_LAS unsigned char* lds, const Gemm g, const Sched& S, const Epi& E) {
;     ...
;             PG8_WAIT_V(8); PG8_WAIT_L(0); PG8_BAR; PG8_MMA(1, 0, At, B0); PG8_MMA(1, 1, At, B1); PG8_BAR; PG8_SCHED;
;             PG8_LDB(B0, 1, 0); PG8_LDB(B1, 1, 1); PG8_SCHED; PG8_LDA(At, 1, 0); PG8_STAGE(PG8_SA(0, 1), a2 + hstep, voffA);
;             PG8_WAIT_V(8); PG8_WAIT_L(0); PG8_BAR; PG8_MMA(0, 0, At, B0); PG8_MMA(0, 1, At, B1); PG8_BAR; PG8_SCHED;
	s_setprio 1
	v_mfma_f32_16x16x32_bf16 v[62:65], v[144:147], v[212:215], v[62:65]
	v_mfma_f32_16x16x32_bf16 v[62:65], v[184:187], v[216:219], v[62:65]
	v_mfma_f32_16x16x32_bf16 v[46:49], v[184:187], v[224:227], v[46:49]
	v_mfma_f32_16x16x32_bf16 v[46:49], v[144:147], v[220:223], v[46:49]
	v_mfma_f32_16x16x32_bf16 v[30:33], v[144:147], v[228:231], v[30:33]
	v_mfma_f32_16x16x32_bf16 v[30:33], v[184:187], v[232:235], v[30:33]
	v_mfma_f32_16x16x32_bf16 v[14:17], v[184:187], v[240:243], v[14:17]
	v_mfma_f32_16x16x32_bf16 v[14:17], v[144:147], v[236:239], v[14:17]
	v_mfma_f32_16x16x32_bf16 v[10:13], v[188:191], v[236:239], v[10:13]
	v_mfma_f32_16x16x32_bf16 v[10:13], v[192:195], v[240:243], v[10:13]
	v_mfma_f32_16x16x32_bf16 v[26:29], v[192:195], v[232:235], v[26:29]
	v_mfma_f32_16x16x32_bf16 v[26:29], v[188:191], v[228:231], v[26:29]
	v_mfma_f32_16x16x32_bf16 v[42:45], v[188:191], v[220:223], v[42:45]
	v_mfma_f32_16x16x32_bf16 v[42:45], v[192:195], v[224:227], v[42:45]
	v_mfma_f32_16x16x32_bf16 v[58:61], v[192:195], v[216:219], v[58:61]
	v_mfma_f32_16x16x32_bf16 v[58:61], v[188:191], v[212:215], v[58:61]
	v_mfma_f32_16x16x32_bf16 v[54:57], v[196:199], v[212:215], v[54:57]
	v_mfma_f32_16x16x32_bf16 v[54:57], v[200:203], v[216:219], v[54:57]
	v_mfma_f32_16x16x32_bf16 v[38:41], v[200:203], v[224:227], v[38:41]
	v_mfma_f32_16x16x32_bf16 v[38:41], v[196:199], v[220:223], v[38:41]
	v_mfma_f32_16x16x32_bf16 v[22:25], v[196:199], v[228:231], v[22:25]
	v_mfma_f32_16x16x32_bf16 v[22:25], v[200:203], v[232:235], v[22:25]
	v_mfma_f32_16x16x32_bf16 v[6:9], v[200:203], v[240:243], v[6:9]
	v_mfma_f32_16x16x32_bf16 v[6:9], v[196:199], v[236:239], v[6:9]
	v_mfma_f32_16x16x32_bf16 v[2:5], v[204:207], v[236:239], v[2:5]
	v_mfma_f32_16x16x32_bf16 v[2:5], v[208:211], v[240:243], v[2:5]
	v_mfma_f32_16x16x32_bf16 v[18:21], v[208:211], v[232:235], v[18:21]
	v_mfma_f32_16x16x32_bf16 v[18:21], v[204:207], v[228:231], v[18:21]
	s_barrier
	s_setprio 2
	v_mfma_f32_16x16x32_bf16 v[34:37], v[204:207], v[220:223], v[34:37]
	v_mfma_f32_16x16x32_bf16 v[34:37], v[208:211], v[224:227], v[34:37]
	v_mfma_f32_16x16x32_bf16 v[50:53], v[208:211], v[216:219], v[50:53]
	v_mfma_f32_16x16x32_bf16 v[50:53], v[204:207], v[212:215], v[50:53]
	s_setprio 0
	s_add_i32 s14, 0, 0x18000
	v_add_u32_e32 v133, s14, v148
	s_add_i32 s15, 0, 0x1c000
	ds_read_b128 v[144:147], v133
	ds_read_b128 v[184:187], v133 offset:1024
	ds_read_b128 v[188:191], v133 offset:2048
	ds_read_b128 v[192:195], v133 offset:3072
	v_add_u32_e32 v133, s15, v148
	ds_read_b128 v[196:199], v133
	ds_read_b128 v[200:203], v133 offset:1024
	ds_read_b128 v[204:207], v133 offset:2048
	ds_read_b128 v[208:211], v133 offset:3072
	s_mov_b32 m0, s57
	v_lshl_add_u64 v[246:247], v[244:245], 0, s[24:25]
	ds_read_b128 v[212:215], v168 offset:32768
	ds_read_b128 v[216:219], v168 offset:33792
	ds_read_b128 v[220:223], v168 offset:34816
	ds_read_b128 v[224:227], v168 offset:35840
	ds_read_b128 v[228:231], v168 offset:36864
	ds_read_b128 v[232:235], v168 offset:37888
	ds_read_b128 v[236:239], v168 offset:38912
	ds_read_b128 v[240:243], v168 offset:39936
	global_load_lds_dwordx4 v[246:247], off
	v_lshl_add_u64 v[246:247], v[244:245], 0, s[26:27]
	s_mov_b32 m0, s58
	s_nop 0
	global_load_lds_dwordx4 v[246:247], off
	s_waitcnt vmcnt(8)
	s_waitcnt lgkmcnt(0)
	s_barrier
	s_setprio 1
	v_mfma_f32_16x16x32_bf16 v[126:129], v[144:147], v[212:215], v[126:129]
	v_mfma_f32_16x16x32_bf16 v[126:129], v[184:187], v[216:219], v[126:129]
	v_mfma_f32_16x16x32_bf16 v[110:113], v[184:187], v[224:227], v[110:113]
	v_mfma_f32_16x16x32_bf16 v[110:113], v[144:147], v[220:223], v[110:113]
	v_mfma_f32_16x16x32_bf16 v[94:97], v[144:147], v[228:231], v[94:97]
	v_mfma_f32_16x16x32_bf16 v[94:97], v[184:187], v[232:235], v[94:97]
	v_mfma_f32_16x16x32_bf16 v[78:81], v[184:187], v[240:243], v[78:81]
	v_mfma_f32_16x16x32_bf16 v[78:81], v[144:147], v[236:239], v[78:81]
	v_mfma_f32_16x16x32_bf16 v[74:77], v[188:191], v[236:239], v[74:77]
	v_mfma_f32_16x16x32_bf16 v[74:77], v[192:195], v[240:243], v[74:77]
	v_mfma_f32_16x16x32_bf16 v[90:93], v[192:195], v[232:235], v[90:93]
	v_mfma_f32_16x16x32_bf16 v[90:93], v[188:191], v[228:231], v[90:93]
	v_mfma_f32_16x16x32_bf16 v[106:109], v[188:191], v[220:223], v[106:109]
	v_mfma_f32_16x16x32_bf16 v[106:109], v[192:195], v[224:227], v[106:109]
	v_mfma_f32_16x16x32_bf16 v[122:125], v[192:195], v[216:219], v[122:125]
	v_mfma_f32_16x16x32_bf16 v[122:125], v[188:191], v[212:215], v[122:125]
	v_mfma_f32_16x16x32_bf16 v[118:121], v[196:199], v[212:215], v[118:121]
	v_mfma_f32_16x16x32_bf16 v[118:121], v[200:203], v[216:219], v[118:121]
	v_mfma_f32_16x16x32_bf16 v[102:105], v[200:203], v[224:227], v[102:105]
	v_mfma_f32_16x16x32_bf16 v[102:105], v[196:199], v[220:223], v[102:105]
	v_mfma_f32_16x16x32_bf16 v[86:89], v[196:199], v[228:231], v[86:89]
	v_mfma_f32_16x16x32_bf16 v[86:89], v[200:203], v[232:235], v[86:89]
	v_mfma_f32_16x16x32_bf16 v[70:73], v[200:203], v[240:243], v[70:73]
	v_mfma_f32_16x16x32_bf16 v[70:73], v[196:199], v[236:239], v[70:73]
	v_mfma_f32_16x16x32_bf16 v[66:69], v[204:207], v[236:239], v[66:69]
	v_mfma_f32_16x16x32_bf16 v[66:69], v[208:211], v[240:243], v[66:69]
	v_mfma_f32_16x16x32_bf16 v[82:85], v[208:211], v[232:235], v[82:85]
	v_mfma_f32_16x16x32_bf16 v[82:85], v[204:207], v[228:231], v[82:85]
	s_barrier
; #define PG8_STAGE(bufoff, gbase, voff) do { if constexpr (!pg8_noload<Epi>::value) { _Pragma("unroll") for (int _i = 0; _i < 2; ++_i) \
;         __builtin_amdgcn_global_load_lds((const unsigned*)((const char*)(gbase) + (size_t)_i * pstep + (voff)[0]), (PG8_LAS unsigned*)(lds + (bufoff) + ldsw + _i * 8192), 16, 0, 0); } } while (0)
; #define PG8_LDA(dst, b, h) do { _Pragma("unroll") for (int m = 0; m < 4; ++m) _Pragma("unroll") for (int k = 0; k < 2; ++k) dst[m][k] = *(const PG8_LAS bf16x8*)(lds + PG8_SA(b, h) + aoff + m * 2048 + k * 1024); } while (0)
; #define PG8_MMA(ai, bj, At, Bt) do { __builtin_amdgcn_s_setprio(1); _Pragma("unroll") for (int m = 0; m < 4; ++m) _Pragma("unroll") for (int n = 0; n < 2; ++n) _Pragma("unroll") for (int k = 0; k < 2; ++k) \
;         acc[ai][bj][m][n] = __builtin_amdgcn_mfma_f32_16x16x32_bf16(Bt[n][k], At[m][k], acc[ai][bj][m][n], 0, 0, 0); __builtin_amdgcn_s_setprio(0); } while (0)
; #define PG8_WAIT_V(n) asm volatile("s_waitcnt vmcnt(" #n ")" ::: "memory")
; #define PG8_WAIT_L(n) asm volatile("s_waitcnt lgkmcnt(" #n ")" ::: "memory")
; #define PG8_BAR __builtin_amdgcn_s_barrier()
; #define PG8_SCHED __builtin_amdgcn_sched_barrier(0)
; template <class Epi, class Sched, bool ALIGN_EPI = false, bool SP2 = false, bool ABLK = false>
; __device__ __forceinline__ void gemm_phase(PG8_LAS unsigned char* lds, const Gemm g, const Sched& S, const Epi& E) {
;     ...
;         for (int t = 0; t < nt; t += 2) {
;             const bool last = (t == nt - 2);
;     ...
;             PG8_WAIT_V(8); PG8_WAIT_L(0); PG8_BAR; PG8_MMA(0, 0, At, B0); PG8_MMA(0, 1, At, B1); PG8_BAR; PG8_SCHED;
;             PG8_LDA(At, 1, 1); PG8_STAGE(PG8_SB(1, 0), b3, voffB); PG8_STAGE(PG8_SB(1, 1), b3 + hstep, voffB); PG8_STAGE(PG8_SA(1, 0), a3, voffA);
;             PG8_WAIT_V(8); PG8_WAIT_L(0); PG8_BAR; PG8_MMA(1, 0, At, B0); PG8_MMA(1, 1, At, B1); PG8_BAR; PG8_SCHED;
	s_setprio 2
	v_mfma_f32_16x16x32_bf16 v[98:101], v[204:207], v[220:223], v[98:101]
	v_mfma_f32_16x16x32_bf16 v[98:101], v[208:211], v[224:227], v[98:101]
	v_mfma_f32_16x16x32_bf16 v[114:117], v[208:211], v[216:219], v[114:117]
	v_mfma_f32_16x16x32_bf16 v[114:117], v[204:207], v[212:215], v[114:117]
	s_setprio 0
	s_add_i32 s14, s14, s3
	v_lshl_add_u64 v[246:247], v[180:181], 0, s[38:39]
	s_mov_b32 m0, s14
	ds_read_b128 v[212:215], v168 offset:49152
	ds_read_b128 v[216:219], v168 offset:50176
	ds_read_b128 v[220:223], v168 offset:51200
	ds_read_b128 v[224:227], v168 offset:52224
	ds_read_b128 v[228:231], v168 offset:53248
	ds_read_b128 v[232:235], v168 offset:54272
	ds_read_b128 v[236:239], v168 offset:55296
	ds_read_b128 v[240:243], v168 offset:56320
	global_load_lds_dwordx4 v[246:247], off
	v_lshl_add_u64 v[246:247], v[180:181], 0, s[40:41]
	s_add_i32 m0, s14, 0x2000
	s_add_i32 s14, s15, s3
	global_load_lds_dwordx4 v[246:247], off
	v_lshl_add_u64 v[246:247], v[180:181], 0, s[42:43]
	s_mov_b32 m0, s14
	v_lshl_add_u64 v[180:181], v[180:181], 0, s[44:45]
	global_load_lds_dwordx4 v[246:247], off
	s_add_i32 m0, s14, 0x2000
	s_nop 0
	global_load_lds_dwordx4 v[180:181], off
	v_lshl_add_u64 v[180:181], v[244:245], 0, s[38:39]
	s_mov_b32 m0, s61
	s_nop 0
	global_load_lds_dwordx4 v[180:181], off
	v_lshl_add_u64 v[180:181], v[244:245], 0, s[40:41]
	s_mov_b32 m0, s63
	s_nop 0
	global_load_lds_dwordx4 v[180:181], off
	s_waitcnt vmcnt(8)
	s_waitcnt lgkmcnt(0)
	s_barrier
	s_setprio 1
	v_mfma_f32_16x16x32_bf16 v[62:65], v[144:147], v[212:215], v[62:65]
	v_mfma_f32_16x16x32_bf16 v[62:65], v[184:187], v[216:219], v[62:65]
	v_mfma_f32_16x16x32_bf16 v[46:49], v[184:187], v[224:227], v[46:49]
	v_mfma_f32_16x16x32_bf16 v[46:49], v[144:147], v[220:223], v[46:49]
	v_mfma_f32_16x16x32_bf16 v[30:33], v[144:147], v[228:231], v[30:33]
	v_mfma_f32_16x16x32_bf16 v[30:33], v[184:187], v[232:235], v[30:33]
	v_mfma_f32_16x16x32_bf16 v[14:17], v[184:187], v[240:243], v[14:17]
	v_mfma_f32_16x16x32_bf16 v[14:17], v[144:147], v[236:239], v[14:17]
	v_mfma_f32_16x16x32_bf16 v[10:13], v[188:191], v[236:239], v[10:13]
	v_mfma_f32_16x16x32_bf16 v[10:13], v[192:195], v[240:243], v[10:13]
	v_mfma_f32_16x16x32_bf16 v[26:29], v[192:195], v[232:235], v[26:29]
	v_mfma_f32_16x16x32_bf16 v[26:29], v[188:191], v[228:231], v[26:29]
	v_mfma_f32_16x16x32_bf16 v[42:45], v[188:191], v[220:223], v[42:45]
	v_mfma_f32_16x16x32_bf16 v[42:45], v[192:195], v[224:227], v[42:45]
	v_mfma_f32_16x16x32_bf16 v[58:61], v[192:195], v[216:219], v[58:61]
	v_mfma_f32_16x16x32_bf16 v[58:61], v[188:191], v[212:215], v[58:61]
	v_mfma_f32_16x16x32_bf16 v[54:57], v[196:199], v[212:215], v[54:57]
	v_mfma_f32_16x16x32_bf16 v[54:57], v[200:203], v[216:219], v[54:57]
	v_mfma_f32_16x16x32_bf16 v[38:41], v[200:203], v[224:227], v[38:41]
	v_mfma_f32_16x16x32_bf16 v[38:41], v[196:199], v[220:223], v[38:41]
	v_mfma_f32_16x16x32_bf16 v[22:25], v[196:199], v[228:231], v[22:25]
	v_mfma_f32_16x16x32_bf16 v[22:25], v[200:203], v[232:235], v[22:25]
	v_mfma_f32_16x16x32_bf16 v[6:9], v[200:203], v[240:243], v[6:9]
	v_mfma_f32_16x16x32_bf16 v[6:9], v[196:199], v[236:239], v[6:9]
	v_mfma_f32_16x16x32_bf16 v[2:5], v[204:207], v[236:239], v[2:5]
	v_mfma_f32_16x16x32_bf16 v[2:5], v[208:211], v[240:243], v[2:5]
	v_mfma_f32_16x16x32_bf16 v[18:21], v[208:211], v[232:235], v[18:21]
	v_mfma_f32_16x16x32_bf16 v[18:21], v[204:207], v[228:231], v[18:21]
	s_barrier
	s_setprio 2
	v_mfma_f32_16x16x32_bf16 v[34:37], v[204:207], v[220:223], v[34:37]
	v_mfma_f32_16x16x32_bf16 v[34:37], v[208:211], v[224:227], v[34:37]
	v_mfma_f32_16x16x32_bf16 v[50:53], v[208:211], v[216:219], v[50:53]
	v_mfma_f32_16x16x32_bf16 v[50:53], v[204:207], v[212:215], v[50:53]
	s_setprio 0
	s_cmp_gt_u32 s59, 29
	s_mov_b32 s59, s30
	s_cbranch_scc1 .LBB0_2131

; #define PG8_STAGE(bufoff, gbase, voff) do { if constexpr (!pg8_noload<Epi>::value) { _Pragma("unroll") for (int _i = 0; _i < 2; ++_i) \
;         __builtin_amdgcn_global_load_lds((const unsigned*)((const char*)(gbase) + (size_t)_i * pstep + (voff)[0]), (PG8_LAS unsigned*)(lds + (bufoff) + ldsw + _i * 8192), 16, 0, 0); } } while (0)
; #define PG8_LDA(dst, b, h) do { _Pragma("unroll") for (int m = 0; m < 4; ++m) _Pragma("unroll") for (int k = 0; k < 2; ++k) dst[m][k] = *(const PG8_LAS bf16x8*)(lds + PG8_SA(b, h) + aoff + m * 2048 + k * 1024); } while (0)
; #define PG8_LDB(dst, b, h) do { _Pragma("unroll") for (int n = 0; n < 2; ++n) _Pragma("unroll") for (int k = 0; k < 2; ++k) dst[n][k] = *(const PG8_LAS bf16x8*)(lds + PG8_SB(b, h) + boff + n * 2048 + k * 1024); } while (0)
; #define PG8_MMA(ai, bj, At, Bt) do { __builtin_amdgcn_s_setprio(1); _Pragma("unroll") for (int m = 0; m < 4; ++m) _Pragma("unroll") for (int n = 0; n < 2; ++n) _Pragma("unroll") for (int k = 0; k < 2; ++k) \
;         acc[ai][bj][m][n] = __builtin_amdgcn_mfma_f32_16x16x32_bf16(Bt[n][k], At[m][k], acc[ai][bj][m][n], 0, 0, 0); __builtin_amdgcn_s_setprio(0); } while (0)
; #define PG8_BAR __builtin_amdgcn_s_barrier()
; template <class Epi, class Sched, bool ALIGN_EPI = false, bool SP2 = false, bool ABLK = false>
; __device__ __forceinline__ void gemm_phase(PG8_LAS unsigned char* lds, const Gemm g, const Sched& S, const Epi& E) {
;     ...
;         for (int t = 0; t < nt; t += 2) {
;             const bool last = (t == nt - 2);
;             const char* a1 = cA + (size_t)(t + 1) * kstep;
;             const char* a2 = last ? nA : cA + (size_t)(t + 2) * kstep; const char* b2 = last ? nB : cB + (size_t)(t + 2) * kstepB;
;             const char* a3 = a2 + kstep; const char* b3 = b2 + kstepB;
;             if (last && has_next) S.a_ready(nxt);
;             if constexpr (SP2) {
;             PG8_LDB(B0, 0, 0); PG8_LDB(B1, 0, 1); PG8_SCHED; PG8_LDA(At, 0, 0); PG8_STAGE(PG8_SA(1, 1), a1 + hstep, voffA);
;             PG8_WAIT_V(8); PG8_WAIT_L(0); PG8_BAR; PG8_MMA(0, 0, At, B0); PG8_MMA(0, 1, At, B1); PG8_BAR; PG8_SCHED;
;             PG8_LDA(At, 0, 1); PG8_STAGE(PG8_SB(0, 0), b2, voffB); PG8_STAGE(PG8_SB(0, 1), b2 + hstep, voffB); PG8_STAGE(PG8_SA(0, 0), a2, voffA);
;             PG8_WAIT_V(8); PG8_WAIT_L(0); PG8_BAR; PG8_MMA(1, 0, At, B0); PG8_MMA(1, 1, At, B1); PG8_BAR; PG8_SCHED;
.LBB0_2399:
	ds_read_b128 v[130:133], v175
	ds_read_b128 v[134:137], v175 offset:1024
	ds_read_b128 v[138:141], v175 offset:2048
	ds_read_b128 v[142:145], v175 offset:3072
	ds_read_b128 v[146:149], v176
	ds_read_b128 v[150:153], v176 offset:1024
	ds_read_b128 v[154:157], v176 offset:2048
	ds_read_b128 v[158:161], v176 offset:3072
	s_add_i32 s55, s53, 2
	s_add_u32 s64, s62, 0xfff00800
	s_addc_u32 s65, s63, -1
	s_cmp_eq_u32 s3, s53
	s_cselect_b32 s65, s57, s65
	s_cselect_b32 s64, s56, s64
	s_cselect_b32 s91, s59, s49
	s_cselect_b32 s90, s58, s11
	v_lshl_add_u64 v[170:171], s[62:63], 0, v[166:167]
	s_add_i32 m0, s61, 0xc000
	ds_read_b128 v[184:187], v177
	ds_read_b128 v[188:191], v177 offset:1024
	ds_read_b128 v[192:195], v177 offset:2048
	ds_read_b128 v[196:199], v177 offset:3072
	ds_read_b128 v[200:203], v177 offset:4096
	ds_read_b128 v[204:207], v177 offset:5120
	ds_read_b128 v[208:211], v177 offset:6144
	ds_read_b128 v[212:215], v177 offset:7168
	global_load_lds_dwordx4 v[170:171], off
	v_lshl_add_u64 v[170:171], v[170:171], 0, s[12:13]
	s_add_i32 m0, s61, 0xe000
	s_nop 0
	global_load_lds_dwordx4 v[170:171], off
	s_waitcnt vmcnt(8)
	s_waitcnt lgkmcnt(0)
	s_barrier
	s_setprio 1
	v_mfma_f32_16x16x32_bf16 v[126:129], v[130:133], v[184:187], v[126:129]
	v_mfma_f32_16x16x32_bf16 v[126:129], v[134:137], v[188:191], v[126:129]
	v_mfma_f32_16x16x32_bf16 v[110:113], v[134:137], v[196:199], v[110:113]
	v_mfma_f32_16x16x32_bf16 v[110:113], v[130:133], v[192:195], v[110:113]
	v_mfma_f32_16x16x32_bf16 v[94:97], v[130:133], v[200:203], v[94:97]
	v_mfma_f32_16x16x32_bf16 v[94:97], v[134:137], v[204:207], v[94:97]
	v_mfma_f32_16x16x32_bf16 v[78:81], v[134:137], v[212:215], v[78:81]
	v_mfma_f32_16x16x32_bf16 v[78:81], v[130:133], v[208:211], v[78:81]
	v_mfma_f32_16x16x32_bf16 v[74:77], v[138:141], v[208:211], v[74:77]
	v_mfma_f32_16x16x32_bf16 v[74:77], v[142:145], v[212:215], v[74:77]
	v_mfma_f32_16x16x32_bf16 v[90:93], v[142:145], v[204:207], v[90:93]
	v_mfma_f32_16x16x32_bf16 v[90:93], v[138:141], v[200:203], v[90:93]
	v_mfma_f32_16x16x32_bf16 v[106:109], v[138:141], v[192:195], v[106:109]
	v_mfma_f32_16x16x32_bf16 v[106:109], v[142:145], v[196:199], v[106:109]
	v_mfma_f32_16x16x32_bf16 v[122:125], v[142:145], v[188:191], v[122:125]
	v_mfma_f32_16x16x32_bf16 v[122:125], v[138:141], v[184:187], v[122:125]
	v_mfma_f32_16x16x32_bf16 v[118:121], v[146:149], v[184:187], v[118:121]
	v_mfma_f32_16x16x32_bf16 v[118:121], v[150:153], v[188:191], v[118:121]
	v_mfma_f32_16x16x32_bf16 v[102:105], v[150:153], v[196:199], v[102:105]
	v_mfma_f32_16x16x32_bf16 v[102:105], v[146:149], v[192:195], v[102:105]
	v_mfma_f32_16x16x32_bf16 v[86:89], v[146:149], v[200:203], v[86:89]
	v_mfma_f32_16x16x32_bf16 v[86:89], v[150:153], v[204:207], v[86:89]
	v_mfma_f32_16x16x32_bf16 v[70:73], v[150:153], v[212:215], v[70:73]
	v_mfma_f32_16x16x32_bf16 v[70:73], v[146:149], v[208:211], v[70:73]
	v_mfma_f32_16x16x32_bf16 v[66:69], v[154:157], v[208:211], v[66:69]
	v_mfma_f32_16x16x32_bf16 v[66:69], v[158:161], v[212:215], v[66:69]
	v_mfma_f32_16x16x32_bf16 v[82:85], v[158:161], v[204:207], v[82:85]
	v_mfma_f32_16x16x32_bf16 v[82:85], v[154:157], v[200:203], v[82:85]
	s_barrier
	s_setprio 2
	v_mfma_f32_16x16x32_bf16 v[98:101], v[154:157], v[192:195], v[98:101]
	v_mfma_f32_16x16x32_bf16 v[98:101], v[158:161], v[196:199], v[98:101]
	v_mfma_f32_16x16x32_bf16 v[114:117], v[158:161], v[188:191], v[114:117]
	v_mfma_f32_16x16x32_bf16 v[114:117], v[154:157], v[184:187], v[114:117]
	s_setprio 0
	s_add_i32 s53, s80, s69
	v_lshl_add_u64 v[170:171], s[90:91], 0, v[162:163]
	s_mov_b32 m0, s53
	ds_read_b128 v[184:187], v177 offset:16384
	ds_read_b128 v[188:191], v177 offset:17408
	ds_read_b128 v[192:195], v177 offset:18432
	ds_read_b128 v[196:199], v177 offset:19456
	ds_read_b128 v[200:203], v177 offset:20480
	ds_read_b128 v[204:207], v177 offset:21504
	ds_read_b128 v[208:211], v177 offset:22528
	ds_read_b128 v[212:215], v177 offset:23552
	global_load_lds_dwordx4 v[170:171], off
	v_lshl_add_u64 v[216:217], v[170:171], 0, s[12:13]
	s_add_i32 m0, s53, 0x2000
	s_add_i32 s53, s81, s69
	global_load_lds_dwordx4 v[216:217], off
	v_lshl_add_u64 v[216:217], v[170:171], 0, s[14:15]
	s_mov_b32 m0, s53
	s_nop 0
	global_load_lds_dwordx4 v[216:217], off
	v_lshl_add_u64 v[216:217], v[170:171], 0, s[16:17]
	s_add_i32 m0, s53, 0x2000
	s_nop 0
	global_load_lds_dwordx4 v[216:217], off
	v_lshl_add_u64 v[216:217], s[64:65], 0, v[162:163]
	s_mov_b32 m0, s61
	v_lshl_add_u64 v[218:219], v[216:217], 0, s[12:13]
	global_load_lds_dwordx4 v[216:217], off
	s_mov_b32 m0, s70
	s_nop 0
	global_load_lds_dwordx4 v[218:219], off
	s_waitcnt vmcnt(8)
	s_waitcnt lgkmcnt(0)
	s_barrier
; #define PG8_STAGE(bufoff, gbase, voff) do { if constexpr (!pg8_noload<Epi>::value) { _Pragma("unroll") for (int _i = 0; _i < 2; ++_i) \
;         __builtin_amdgcn_global_load_lds((const unsigned*)((const char*)(gbase) + (size_t)_i * pstep + (voff)[0]), (PG8_LAS unsigned*)(lds + (bufoff) + ldsw + _i * 8192), 16, 0, 0); } } while (0)
; #define PG8_LDA(dst, b, h) do { _Pragma("unroll") for (int m = 0; m < 4; ++m) _Pragma("unroll") for (int k = 0; k < 2; ++k) dst[m][k] = *(const PG8_LAS bf16x8*)(lds + PG8_SA(b, h) + aoff + m * 2048 + k * 1024); } while (0)
; #define PG8_LDB(dst, b, h) do { _Pragma("unroll") for (int n = 0; n < 2; ++n) _Pragma("unroll") for (int k = 0; k < 2; ++k) dst[n][k] = *(const PG8_LAS bf16x8*)(lds + PG8_SB(b, h) + boff + n * 2048 + k * 1024); } while (0)
; #define PG8_MMA(ai, bj, At, Bt) do { __builtin_amdgcn_s_setprio(1); _Pragma("unroll") for (int m = 0; m < 4; ++m) _Pragma("unroll") for (int n = 0; n < 2; ++n) _Pragma("unroll") for (int k = 0; k < 2; ++k) \
;         acc[ai][bj][m][n] = __builtin_amdgcn_mfma_f32_16x16x32_bf16(Bt[n][k], At[m][k], acc[ai][bj][m][n], 0, 0, 0); __builtin_amdgcn_s_setprio(0); } while (0)
; #define PG8_WAIT_V(n) asm volatile("s_waitcnt vmcnt(" #n ")" ::: "memory")
; #define PG8_WAIT_L(n) asm volatile("s_waitcnt lgkmcnt(" #n ")" ::: "memory")
; #define PG8_BAR __builtin_amdgcn_s_barrier()
; #define PG8_SCHED __builtin_amdgcn_sched_barrier(0)
; template <class Epi, class Sched, bool ALIGN_EPI = false, bool SP2 = false, bool ABLK = false>
; __device__ __forceinline__ void gemm_phase(PG8_LAS unsigned char* lds, const Gemm g, const Sched& S, const Epi& E) {
;     ...
;             PG8_WAIT_V(8); PG8_WAIT_L(0); PG8_BAR; PG8_MMA(1, 0, At, B0); PG8_MMA(1, 1, At, B1); PG8_BAR; PG8_SCHED;
;             PG8_LDB(B0, 1, 0); PG8_LDB(B1, 1, 1); PG8_SCHED; PG8_LDA(At, 1, 0); PG8_STAGE(PG8_SA(0, 1), a2 + hstep, voffA);
;             PG8_WAIT_V(8); PG8_WAIT_L(0); PG8_BAR; PG8_MMA(0, 0, At, B0); PG8_MMA(0, 1, At, B1); PG8_BAR; PG8_SCHED;
	s_setprio 1
	v_mfma_f32_16x16x32_bf16 v[62:65], v[130:133], v[184:187], v[62:65]
	v_mfma_f32_16x16x32_bf16 v[62:65], v[134:137], v[188:191], v[62:65]
	v_mfma_f32_16x16x32_bf16 v[46:49], v[134:137], v[196:199], v[46:49]
	v_mfma_f32_16x16x32_bf16 v[46:49], v[130:133], v[192:195], v[46:49]
	v_mfma_f32_16x16x32_bf16 v[30:33], v[130:133], v[200:203], v[30:33]
	v_mfma_f32_16x16x32_bf16 v[30:33], v[134:137], v[204:207], v[30:33]
	v_mfma_f32_16x16x32_bf16 v[14:17], v[134:137], v[212:215], v[14:17]
	v_mfma_f32_16x16x32_bf16 v[14:17], v[130:133], v[208:211], v[14:17]
	v_mfma_f32_16x16x32_bf16 v[10:13], v[138:141], v[208:211], v[10:13]
	v_mfma_f32_16x16x32_bf16 v[10:13], v[142:145], v[212:215], v[10:13]
	v_mfma_f32_16x16x32_bf16 v[26:29], v[142:145], v[204:207], v[26:29]
	v_mfma_f32_16x16x32_bf16 v[26:29], v[138:141], v[200:203], v[26:29]
	v_mfma_f32_16x16x32_bf16 v[42:45], v[138:141], v[192:195], v[42:45]
	v_mfma_f32_16x16x32_bf16 v[42:45], v[142:145], v[196:199], v[42:45]
	v_mfma_f32_16x16x32_bf16 v[58:61], v[142:145], v[188:191], v[58:61]
	v_mfma_f32_16x16x32_bf16 v[58:61], v[138:141], v[184:187], v[58:61]
	v_mfma_f32_16x16x32_bf16 v[54:57], v[146:149], v[184:187], v[54:57]
	v_mfma_f32_16x16x32_bf16 v[54:57], v[150:153], v[188:191], v[54:57]
	v_mfma_f32_16x16x32_bf16 v[38:41], v[150:153], v[196:199], v[38:41]
	v_mfma_f32_16x16x32_bf16 v[38:41], v[146:149], v[192:195], v[38:41]
	v_mfma_f32_16x16x32_bf16 v[22:25], v[146:149], v[200:203], v[22:25]
	v_mfma_f32_16x16x32_bf16 v[22:25], v[150:153], v[204:207], v[22:25]
	v_mfma_f32_16x16x32_bf16 v[6:9], v[150:153], v[212:215], v[6:9]
	v_mfma_f32_16x16x32_bf16 v[6:9], v[146:149], v[208:211], v[6:9]
	v_mfma_f32_16x16x32_bf16 v[2:5], v[154:157], v[208:211], v[2:5]
	v_mfma_f32_16x16x32_bf16 v[2:5], v[158:161], v[212:215], v[2:5]
	v_mfma_f32_16x16x32_bf16 v[18:21], v[158:161], v[204:207], v[18:21]
	v_mfma_f32_16x16x32_bf16 v[18:21], v[154:157], v[200:203], v[18:21]
	s_barrier
	s_setprio 2
	v_mfma_f32_16x16x32_bf16 v[34:37], v[154:157], v[192:195], v[34:37]
	v_mfma_f32_16x16x32_bf16 v[34:37], v[158:161], v[196:199], v[34:37]
	v_mfma_f32_16x16x32_bf16 v[50:53], v[158:161], v[188:191], v[50:53]
	v_mfma_f32_16x16x32_bf16 v[50:53], v[154:157], v[184:187], v[50:53]
	s_setprio 0
	s_add_i32 s53, 0, 0x18000
	s_add_i32 s64, 0, 0x1c000
	v_add_u32_e32 v142, s53, v1
	v_add_u32_e32 v158, s64, v1
	ds_read_b128 v[130:133], v142
	ds_read_b128 v[134:137], v142 offset:1024
	ds_read_b128 v[138:141], v142 offset:2048
	ds_read_b128 v[142:145], v142 offset:3072
	ds_read_b128 v[146:149], v158
	ds_read_b128 v[150:153], v158 offset:1024
	ds_read_b128 v[154:157], v158 offset:2048
	ds_read_b128 v[158:161], v158 offset:3072
	s_mov_b32 m0, s71
	v_lshl_add_u64 v[218:219], v[216:217], 0, s[14:15]
	ds_read_b128 v[184:187], v177 offset:32768
	ds_read_b128 v[188:191], v177 offset:33792
	ds_read_b128 v[192:195], v177 offset:34816
	ds_read_b128 v[196:199], v177 offset:35840
	ds_read_b128 v[200:203], v177 offset:36864
	ds_read_b128 v[204:207], v177 offset:37888
	ds_read_b128 v[208:211], v177 offset:38912
	ds_read_b128 v[212:215], v177 offset:39936
	global_load_lds_dwordx4 v[218:219], off
	v_lshl_add_u64 v[218:219], v[216:217], 0, s[16:17]
	s_mov_b32 m0, s72
	s_nop 0
	global_load_lds_dwordx4 v[218:219], off
	s_waitcnt vmcnt(8)
	s_waitcnt lgkmcnt(0)
	s_barrier
	s_setprio 1
	v_mfma_f32_16x16x32_bf16 v[126:129], v[130:133], v[184:187], v[126:129]
	v_mfma_f32_16x16x32_bf16 v[126:129], v[134:137], v[188:191], v[126:129]
	v_mfma_f32_16x16x32_bf16 v[110:113], v[134:137], v[196:199], v[110:113]
	v_mfma_f32_16x16x32_bf16 v[110:113], v[130:133], v[192:195], v[110:113]
	v_mfma_f32_16x16x32_bf16 v[94:97], v[130:133], v[200:203], v[94:97]
	v_mfma_f32_16x16x32_bf16 v[94:97], v[134:137], v[204:207], v[94:97]
	v_mfma_f32_16x16x32_bf16 v[78:81], v[134:137], v[212:215], v[78:81]
	v_mfma_f32_16x16x32_bf16 v[78:81], v[130:133], v[208:211], v[78:81]
	v_mfma_f32_16x16x32_bf16 v[74:77], v[138:141], v[208:211], v[74:77]
	v_mfma_f32_16x16x32_bf16 v[74:77], v[142:145], v[212:215], v[74:77]
	v_mfma_f32_16x16x32_bf16 v[90:93], v[142:145], v[204:207], v[90:93]
	v_mfma_f32_16x16x32_bf16 v[90:93], v[138:141], v[200:203], v[90:93]
	v_mfma_f32_16x16x32_bf16 v[106:109], v[138:141], v[192:195], v[106:109]
	v_mfma_f32_16x16x32_bf16 v[106:109], v[142:145], v[196:199], v[106:109]
	v_mfma_f32_16x16x32_bf16 v[122:125], v[142:145], v[188:191], v[122:125]
	v_mfma_f32_16x16x32_bf16 v[122:125], v[138:141], v[184:187], v[122:125]
	v_mfma_f32_16x16x32_bf16 v[118:121], v[146:149], v[184:187], v[118:121]
	v_mfma_f32_16x16x32_bf16 v[118:121], v[150:153], v[188:191], v[118:121]
	v_mfma_f32_16x16x32_bf16 v[102:105], v[150:153], v[196:199], v[102:105]
	v_mfma_f32_16x16x32_bf16 v[102:105], v[146:149], v[192:195], v[102:105]
	v_mfma_f32_16x16x32_bf16 v[86:89], v[146:149], v[200:203], v[86:89]
	v_mfma_f32_16x16x32_bf16 v[86:89], v[150:153], v[204:207], v[86:89]
	v_mfma_f32_16x16x32_bf16 v[70:73], v[150:153], v[212:215], v[70:73]
	v_mfma_f32_16x16x32_bf16 v[70:73], v[146:149], v[208:211], v[70:73]
	v_mfma_f32_16x16x32_bf16 v[66:69], v[154:157], v[208:211], v[66:69]
	v_mfma_f32_16x16x32_bf16 v[66:69], v[158:161], v[212:215], v[66:69]
	v_mfma_f32_16x16x32_bf16 v[82:85], v[158:161], v[204:207], v[82:85]
	v_mfma_f32_16x16x32_bf16 v[82:85], v[154:157], v[200:203], v[82:85]
	s_barrier
; #define PG8_LDA(dst, b, h) do { _Pragma("unroll") for (int m = 0; m < 4; ++m) _Pragma("unroll") for (int k = 0; k < 2; ++k) dst[m][k] = *(const PG8_LAS bf16x8*)(lds + PG8_SA(b, h) + aoff + m * 2048 + k * 1024); } while (0)
; #define PG8_WAIT_V(n) asm volatile("s_waitcnt vmcnt(" #n ")" ::: "memory")
; template <class Epi, class Sched, bool ALIGN_EPI = false, bool SP2 = false, bool ABLK = false>
; __device__ __forceinline__ void gemm_phase(PG8_LAS unsigned char* lds, const Gemm g, const Sched& S, const Epi& E) {
;     ...
;             PG8_WAIT_V(8); PG8_WAIT_L(0); PG8_BAR; PG8_MMA(0, 0, At, B0); PG8_MMA(0, 1, At, B1); PG8_BAR; PG8_SCHED;
;             PG8_LDA(At, 1, 1); PG8_STAGE(PG8_SB(1, 0), b3, voffB); PG8_STAGE(PG8_SB(1, 1), b3 + hstep, voffB); PG8_STAGE(PG8_SA(1, 0), a3, voffA);
;             PG8_WAIT_V(8); PG8_WAIT_L(0); PG8_BAR; PG8_MMA(1, 0, At, B0); PG8_MMA(1, 1, At, B1); PG8_BAR; PG8_SCHED;
;             } else {
;             PG8_LDB(B0, 0, 0); PG8_SCHED; PG8_LDA(At, 0, 0); PG8_STAGE(PG8_SA(1, 1), a1 + hstep, voffA);
;             PG8_WAIT_L(8); PG8_BAR; PG8_WAIT_L(0); PG8_MMA(0, 0, At, B0); PG8_BAR; PG8_SCHED;
;             PG8_LDB(B1, 0, 1); PG8_STAGE(PG8_SB(0, 0), b2, voffB);
;             PG8_BAR; PG8_WAIT_L(0); PG8_MMA(0, 1, At, B1); PG8_BAR;
;             PG8_LDA(At, 0, 1); PG8_STAGE(PG8_SA(0, 0), a2, voffA);
;             PG8_BAR; PG8_WAIT_L(0); PG8_MMA(1, 0, At, B0); PG8_BAR; PG8_SCHED;
;             PG8_STAGE(PG8_SB(0, 1), b2 + hstep, voffB);
;             PG8_WAIT_V(6); PG8_BAR; PG8_MMA(1, 1, At, B1); PG8_BAR;
;             PG8_LDB(B0, 1, 0); PG8_SCHED; PG8_LDA(At, 1, 0); PG8_STAGE(PG8_SA(0, 1), a2 + hstep, voffA);
;             PG8_WAIT_L(8); PG8_BAR; PG8_WAIT_L(0); PG8_MMA(0, 0, At, B0); PG8_BAR; PG8_SCHED;
;             PG8_LDB(B1, 1, 1); PG8_STAGE(PG8_SB(1, 0), b3, voffB);
;             PG8_BAR; PG8_WAIT_L(0); PG8_MMA(0, 1, At, B1); PG8_BAR;
;             PG8_LDA(At, 1, 1); PG8_STAGE(PG8_SA(1, 0), a3, voffA);
;             PG8_BAR; PG8_WAIT_L(0); PG8_MMA(1, 0, At, B0); PG8_BAR; PG8_SCHED;
;             PG8_STAGE(PG8_SB(1, 1), b3 + hstep, voffB);
;             PG8_WAIT_V(6); PG8_BAR; PG8_MMA(1, 1, At, B1); PG8_BAR;
;             }
;         }
;         if constexpr (ALIGN_EPI) { if (wr == 0) PG8_BAR; }
;         if constexpr (!Epi::AFTER_DRAIN) { E(acc, cur, wr, wc, fr, fq); S.done(cur); }
;         if (!has_next) break;
	s_setprio 2
	v_mfma_f32_16x16x32_bf16 v[98:101], v[154:157], v[192:195], v[98:101]
	v_mfma_f32_16x16x32_bf16 v[98:101], v[158:161], v[196:199], v[98:101]
	v_mfma_f32_16x16x32_bf16 v[114:117], v[158:161], v[188:191], v[114:117]
	v_mfma_f32_16x16x32_bf16 v[114:117], v[154:157], v[184:187], v[114:117]
	s_setprio 0
	s_add_i32 s53, s53, s69
	v_lshl_add_u64 v[218:219], v[170:171], 0, s[24:25]
	s_mov_b32 m0, s53
	ds_read_b128 v[184:187], v177 offset:49152
	ds_read_b128 v[188:191], v177 offset:50176
	ds_read_b128 v[192:195], v177 offset:51200
	ds_read_b128 v[196:199], v177 offset:52224
	ds_read_b128 v[200:203], v177 offset:53248
	ds_read_b128 v[204:207], v177 offset:54272
	ds_read_b128 v[208:211], v177 offset:55296
	ds_read_b128 v[212:215], v177 offset:56320
	global_load_lds_dwordx4 v[218:219], off
	v_lshl_add_u64 v[218:219], v[170:171], 0, s[26:27]
	s_add_i32 m0, s53, 0x2000
	s_add_i32 s53, s64, s69
	global_load_lds_dwordx4 v[218:219], off
	v_lshl_add_u64 v[218:219], v[170:171], 0, s[28:29]
	s_mov_b32 m0, s53
	v_lshl_add_u64 v[170:171], v[170:171], 0, s[30:31]
	global_load_lds_dwordx4 v[218:219], off
	s_add_i32 m0, s53, 0x2000
	s_nop 0
	global_load_lds_dwordx4 v[170:171], off
	v_lshl_add_u64 v[170:171], v[216:217], 0, s[24:25]
	s_mov_b32 m0, s75
	s_nop 0
	global_load_lds_dwordx4 v[170:171], off
	v_lshl_add_u64 v[170:171], v[216:217], 0, s[26:27]
	s_mov_b32 m0, s76
	s_nop 0
	global_load_lds_dwordx4 v[170:171], off
	s_waitcnt vmcnt(8)
	s_waitcnt lgkmcnt(0)
	s_barrier
	s_setprio 1
	v_mfma_f32_16x16x32_bf16 v[62:65], v[130:133], v[184:187], v[62:65]
	v_mfma_f32_16x16x32_bf16 v[62:65], v[134:137], v[188:191], v[62:65]
	v_mfma_f32_16x16x32_bf16 v[46:49], v[134:137], v[196:199], v[46:49]
	v_mfma_f32_16x16x32_bf16 v[46:49], v[130:133], v[192:195], v[46:49]
	v_mfma_f32_16x16x32_bf16 v[30:33], v[130:133], v[200:203], v[30:33]
	v_mfma_f32_16x16x32_bf16 v[30:33], v[134:137], v[204:207], v[30:33]
	v_mfma_f32_16x16x32_bf16 v[14:17], v[134:137], v[212:215], v[14:17]
	v_mfma_f32_16x16x32_bf16 v[14:17], v[130:133], v[208:211], v[14:17]
	v_mfma_f32_16x16x32_bf16 v[10:13], v[138:141], v[208:211], v[10:13]
	v_mfma_f32_16x16x32_bf16 v[10:13], v[142:145], v[212:215], v[10:13]
	v_mfma_f32_16x16x32_bf16 v[26:29], v[142:145], v[204:207], v[26:29]
	v_mfma_f32_16x16x32_bf16 v[26:29], v[138:141], v[200:203], v[26:29]
	v_mfma_f32_16x16x32_bf16 v[42:45], v[138:141], v[192:195], v[42:45]
	v_mfma_f32_16x16x32_bf16 v[42:45], v[142:145], v[196:199], v[42:45]
	v_mfma_f32_16x16x32_bf16 v[58:61], v[142:145], v[188:191], v[58:61]
	v_mfma_f32_16x16x32_bf16 v[58:61], v[138:141], v[184:187], v[58:61]
	v_mfma_f32_16x16x32_bf16 v[54:57], v[146:149], v[184:187], v[54:57]
	v_mfma_f32_16x16x32_bf16 v[54:57], v[150:153], v[188:191], v[54:57]
	v_mfma_f32_16x16x32_bf16 v[38:41], v[150:153], v[196:199], v[38:41]
	v_mfma_f32_16x16x32_bf16 v[38:41], v[146:149], v[192:195], v[38:41]
	v_mfma_f32_16x16x32_bf16 v[22:25], v[146:149], v[200:203], v[22:25]
	v_mfma_f32_16x16x32_bf16 v[22:25], v[150:153], v[204:207], v[22:25]
	v_mfma_f32_16x16x32_bf16 v[6:9], v[150:153], v[212:215], v[6:9]
	v_mfma_f32_16x16x32_bf16 v[6:9], v[146:149], v[208:211], v[6:9]
	v_mfma_f32_16x16x32_bf16 v[2:5], v[154:157], v[208:211], v[2:5]
	v_mfma_f32_16x16x32_bf16 v[2:5], v[158:161], v[212:215], v[2:5]
	v_mfma_f32_16x16x32_bf16 v[18:21], v[158:161], v[204:207], v[18:21]
	v_mfma_f32_16x16x32_bf16 v[18:21], v[154:157], v[200:203], v[18:21]
	s_barrier
	s_setprio 2
	v_mfma_f32_16x16x32_bf16 v[34:37], v[154:157], v[192:195], v[34:37]
	v_mfma_f32_16x16x32_bf16 v[34:37], v[158:161], v[196:199], v[34:37]
	v_mfma_f32_16x16x32_bf16 v[50:53], v[158:161], v[188:191], v[50:53]
	v_mfma_f32_16x16x32_bf16 v[50:53], v[154:157], v[184:187], v[50:53]
	s_setprio 0
	s_add_u32 s62, s62, 0x1000
	s_addc_u32 s63, s63, 0
	s_add_u32 s11, s11, 0x1000
	s_addc_u32 s49, s49, 0
	s_cmp_ge_i32 s55, s89
	s_mov_b32 s53, s55
	s_cbranch_scc0 .LBB0_2399
	s_and_b64 vcc, exec, s[34:35]
	s_cbranch_vccnz .LBB0_2404
	s_lshl_b32 s11, s2, 8
	s_cmp_gt_i32 s2, 63
	s_mov_b64 s[62:63], -1
	s_cbranch_scc1 .LBB0_2405
